# prep_rows 4 loads in flight; rowscale: both row groups loaded before first wait (5 GEMM instances); INB q-norm gain loads hoisted out of row blocks
# speedup vs baseline: 1.0497x; 1.0071x over previous
.LBB0_282:
	s_add_i32 s22, s4, 2
	s_add_u32 s10, s0, 0x80
	s_addc_u32 s5, s1, 0
	s_add_i32 s23, 0, 0x10000
	v_add_u32_e32 v154, s23, v165
	ds_read_b128 v[142:145], v154
	ds_read_b128 v[146:149], v154 offset:1024
	ds_read_b128 v[150:153], v154 offset:2048
	ds_read_b128 v[154:157], v154 offset:3072
	s_cmp_eq_u32 s44, s4
	s_cselect_b32 s4, s16, s10
	s_cselect_b32 s5, s17, s5
	s_cselect_b32 s11, s13, s21
	s_cselect_b32 s10, s12, s20
	v_lshl_add_u64 v[162:163], s[0:1], 0, v[138:139]
	s_add_i32 m0, s29, 0xc000
	ds_read_b128 v[158:161], v166
	ds_read_b128 v[168:171], v166 offset:1024
	ds_read_b128 v[172:175], v166 offset:2048
	ds_read_b128 v[176:179], v166 offset:3072
	ds_read_b128 v[180:183], v166 offset:4096
	ds_read_b128 v[204:207], v166 offset:5120
	ds_read_b128 v[208:211], v166 offset:6144
	ds_read_b128 v[212:215], v166 offset:7168
	global_load_lds_dwordx4 v[162:163], off
	v_lshl_add_u64 v[162:163], s[0:1], 0, v[140:141]
	s_add_i32 m0, s29, 0xe000
	s_nop 0
	global_load_lds_dwordx4 v[162:163], off
	s_waitcnt lgkmcnt(8)
	s_barrier
	s_waitcnt lgkmcnt(0)
	s_setprio 1
	s_waitcnt lgkmcnt(0)
	v_mfma_f32_16x16x32_bf16 v[126:129], v[142:145], v[158:161], v[126:129]
	v_mfma_f32_16x16x32_bf16 v[122:125], v[150:153], v[158:161], v[122:125]
	v_mfma_f32_16x16x32_bf16 v[110:113], v[142:145], v[172:175], v[110:113]
	v_mfma_f32_16x16x32_bf16 v[106:109], v[150:153], v[172:175], v[106:109]
	v_mfma_f32_16x16x32_bf16 v[94:97], v[142:145], v[180:183], v[94:97]
	v_mfma_f32_16x16x32_bf16 v[90:93], v[150:153], v[180:183], v[90:93]
	v_mfma_f32_16x16x32_bf16 v[78:81], v[142:145], v[208:211], v[78:81]
	v_mfma_f32_16x16x32_bf16 v[74:77], v[150:153], v[208:211], v[74:77]
	v_mfma_f32_16x16x32_bf16 v[126:129], v[146:149], v[168:171], v[126:129]
	v_mfma_f32_16x16x32_bf16 v[122:125], v[154:157], v[168:171], v[122:125]
	v_mfma_f32_16x16x32_bf16 v[110:113], v[146:149], v[176:179], v[110:113]
	v_mfma_f32_16x16x32_bf16 v[106:109], v[154:157], v[176:179], v[106:109]
	v_mfma_f32_16x16x32_bf16 v[94:97], v[146:149], v[204:207], v[94:97]
	v_mfma_f32_16x16x32_bf16 v[90:93], v[154:157], v[204:207], v[90:93]
	v_mfma_f32_16x16x32_bf16 v[78:81], v[146:149], v[212:215], v[78:81]
	v_mfma_f32_16x16x32_bf16 v[74:77], v[154:157], v[212:215], v[74:77]
	s_setprio 0
	s_barrier
	s_add_i32 s24, 0, 0x14000
	v_add_u32_e32 v162, s24, v165
	s_add_i32 s23, s23, s28
	ds_read_b128 v[216:219], v162
	ds_read_b128 v[220:223], v162 offset:1024
	ds_read_b128 v[224:227], v162 offset:2048
	ds_read_b128 v[228:231], v162 offset:3072
	v_lshl_add_u64 v[162:163], s[10:11], 0, v[132:133]
	s_mov_b32 m0, s23
	v_lshl_add_u64 v[184:185], s[10:11], 0, v[136:137]
	global_load_lds_dwordx4 v[162:163], off
	s_add_i32 m0, s23, 0x2000
	s_nop 0
	global_load_lds_dwordx4 v[184:185], off
	s_barrier
	s_waitcnt lgkmcnt(0)
	s_setprio 1
	s_waitcnt lgkmcnt(0)
	v_mfma_f32_16x16x32_bf16 v[118:121], v[216:219], v[158:161], v[118:121]
	v_mfma_f32_16x16x32_bf16 v[114:117], v[224:227], v[158:161], v[114:117]
	v_mfma_f32_16x16x32_bf16 v[102:105], v[216:219], v[172:175], v[102:105]
	v_mfma_f32_16x16x32_bf16 v[98:101], v[224:227], v[172:175], v[98:101]
	v_mfma_f32_16x16x32_bf16 v[86:89], v[216:219], v[180:183], v[86:89]
	v_mfma_f32_16x16x32_bf16 v[82:85], v[224:227], v[180:183], v[82:85]
	v_mfma_f32_16x16x32_bf16 v[70:73], v[216:219], v[208:211], v[70:73]
	v_mfma_f32_16x16x32_bf16 v[66:69], v[224:227], v[208:211], v[66:69]
	v_mfma_f32_16x16x32_bf16 v[118:121], v[220:223], v[168:171], v[118:121]
	v_mfma_f32_16x16x32_bf16 v[114:117], v[228:231], v[168:171], v[114:117]
	v_mfma_f32_16x16x32_bf16 v[102:105], v[220:223], v[176:179], v[102:105]
	v_mfma_f32_16x16x32_bf16 v[98:101], v[228:231], v[176:179], v[98:101]
	v_mfma_f32_16x16x32_bf16 v[86:89], v[220:223], v[204:207], v[86:89]
	v_mfma_f32_16x16x32_bf16 v[82:85], v[228:231], v[204:207], v[82:85]
	v_mfma_f32_16x16x32_bf16 v[70:73], v[220:223], v[212:215], v[70:73]
	v_mfma_f32_16x16x32_bf16 v[66:69], v[228:231], v[212:215], v[66:69]
	s_setprio 0
	s_mov_b32 m0, s29
	v_lshl_add_u64 v[232:233], s[4:5], 0, v[130:131]
	s_barrier
	ds_read_b128 v[158:161], v166 offset:16384
	ds_read_b128 v[168:171], v166 offset:17408
	ds_read_b128 v[172:175], v166 offset:18432
	ds_read_b128 v[176:179], v166 offset:19456
	ds_read_b128 v[180:183], v166 offset:20480
	ds_read_b128 v[204:207], v166 offset:21504
	ds_read_b128 v[208:211], v166 offset:22528
	ds_read_b128 v[212:215], v166 offset:23552
	global_load_lds_dwordx4 v[232:233], off
	v_lshl_add_u64 v[234:235], s[4:5], 0, v[134:135]
	s_mov_b32 m0, s30
	s_nop 0
	global_load_lds_dwordx4 v[234:235], off
	s_barrier
	s_waitcnt lgkmcnt(0)
	s_setprio 1
	s_waitcnt lgkmcnt(0)
	v_mfma_f32_16x16x32_bf16 v[62:65], v[142:145], v[158:161], v[62:65]
	v_mfma_f32_16x16x32_bf16 v[58:61], v[150:153], v[158:161], v[58:61]
	v_mfma_f32_16x16x32_bf16 v[46:49], v[142:145], v[172:175], v[46:49]
	v_mfma_f32_16x16x32_bf16 v[42:45], v[150:153], v[172:175], v[42:45]
	v_mfma_f32_16x16x32_bf16 v[30:33], v[142:145], v[180:183], v[30:33]
	v_mfma_f32_16x16x32_bf16 v[26:29], v[150:153], v[180:183], v[26:29]
	v_mfma_f32_16x16x32_bf16 v[14:17], v[142:145], v[208:211], v[14:17]
	v_mfma_f32_16x16x32_bf16 v[10:13], v[150:153], v[208:211], v[10:13]
	v_mfma_f32_16x16x32_bf16 v[62:65], v[146:149], v[168:171], v[62:65]
	v_mfma_f32_16x16x32_bf16 v[58:61], v[154:157], v[168:171], v[58:61]
	v_mfma_f32_16x16x32_bf16 v[46:49], v[146:149], v[176:179], v[46:49]
	v_mfma_f32_16x16x32_bf16 v[42:45], v[154:157], v[176:179], v[42:45]
	v_mfma_f32_16x16x32_bf16 v[30:33], v[146:149], v[204:207], v[30:33]
	v_mfma_f32_16x16x32_bf16 v[26:29], v[154:157], v[204:207], v[26:29]
	v_mfma_f32_16x16x32_bf16 v[14:17], v[146:149], v[212:215], v[14:17]
	v_mfma_f32_16x16x32_bf16 v[10:13], v[154:157], v[212:215], v[10:13]
	s_setprio 0
	s_barrier
	s_add_u32 s10, s10, s92
	s_addc_u32 s11, s11, 0
	s_add_i32 s23, s24, s28
	v_lshl_add_u64 v[236:237], s[10:11], 0, v[132:133]
	s_mov_b32 m0, s23
	v_lshl_add_u64 v[238:239], s[10:11], 0, v[136:137]
	global_load_lds_dwordx4 v[236:237], off
	s_add_i32 m0, s23, 0x2000
	s_nop 0
	global_load_lds_dwordx4 v[238:239], off
	s_waitcnt vmcnt(6)
	s_barrier
	s_setprio 1
	v_mfma_f32_16x16x32_bf16 v[54:57], v[216:219], v[158:161], v[54:57]
	v_mfma_f32_16x16x32_bf16 v[50:53], v[224:227], v[158:161], v[50:53]
	v_mfma_f32_16x16x32_bf16 v[38:41], v[216:219], v[172:175], v[38:41]
	v_mfma_f32_16x16x32_bf16 v[34:37], v[224:227], v[172:175], v[34:37]
	v_mfma_f32_16x16x32_bf16 v[22:25], v[216:219], v[180:183], v[22:25]
	v_mfma_f32_16x16x32_bf16 v[18:21], v[224:227], v[180:183], v[18:21]
	v_mfma_f32_16x16x32_bf16 v[6:9], v[216:219], v[208:211], v[6:9]
	v_mfma_f32_16x16x32_bf16 v[2:5], v[224:227], v[208:211], v[2:5]
	v_mfma_f32_16x16x32_bf16 v[54:57], v[220:223], v[168:171], v[54:57]
	v_mfma_f32_16x16x32_bf16 v[50:53], v[228:231], v[168:171], v[50:53]
	v_mfma_f32_16x16x32_bf16 v[38:41], v[220:223], v[176:179], v[38:41]
	v_mfma_f32_16x16x32_bf16 v[34:37], v[228:231], v[176:179], v[34:37]
	v_mfma_f32_16x16x32_bf16 v[22:25], v[220:223], v[204:207], v[22:25]
	v_mfma_f32_16x16x32_bf16 v[18:21], v[228:231], v[204:207], v[18:21]
	v_mfma_f32_16x16x32_bf16 v[6:9], v[220:223], v[212:215], v[6:9]
	v_mfma_f32_16x16x32_bf16 v[2:5], v[228:231], v[212:215], v[2:5]
	s_setprio 0
	s_add_i32 s10, 0, 0x18000
	v_add_u32_e32 v154, s10, v165
	s_barrier
	ds_read_b128 v[142:145], v154
	ds_read_b128 v[146:149], v154 offset:1024
	ds_read_b128 v[150:153], v154 offset:2048
	ds_read_b128 v[154:157], v154 offset:3072
	s_add_u32 s4, s4, s92
	s_addc_u32 s5, s5, 0
	s_mov_b32 m0, s31
	v_lshl_add_u64 v[216:217], s[4:5], 0, v[130:131]
	ds_read_b128 v[158:161], v166 offset:32768
	ds_read_b128 v[168:171], v166 offset:33792
	ds_read_b128 v[172:175], v166 offset:34816
	ds_read_b128 v[176:179], v166 offset:35840
	ds_read_b128 v[180:183], v166 offset:36864
	ds_read_b128 v[204:207], v166 offset:37888
	ds_read_b128 v[208:211], v166 offset:38912
	ds_read_b128 v[212:215], v166 offset:39936
	global_load_lds_dwordx4 v[216:217], off
	v_lshl_add_u64 v[216:217], s[4:5], 0, v[134:135]
	s_mov_b32 m0, s34
	s_nop 0
	global_load_lds_dwordx4 v[216:217], off
	s_waitcnt lgkmcnt(8)
	s_barrier
	s_waitcnt lgkmcnt(0)
	s_setprio 1
	s_waitcnt lgkmcnt(0)
	v_mfma_f32_16x16x32_bf16 v[126:129], v[142:145], v[158:161], v[126:129]
	v_mfma_f32_16x16x32_bf16 v[122:125], v[150:153], v[158:161], v[122:125]
	v_mfma_f32_16x16x32_bf16 v[110:113], v[142:145], v[172:175], v[110:113]
	v_mfma_f32_16x16x32_bf16 v[106:109], v[150:153], v[172:175], v[106:109]
	v_mfma_f32_16x16x32_bf16 v[94:97], v[142:145], v[180:183], v[94:97]
	v_mfma_f32_16x16x32_bf16 v[90:93], v[150:153], v[180:183], v[90:93]
	v_mfma_f32_16x16x32_bf16 v[78:81], v[142:145], v[208:211], v[78:81]
	v_mfma_f32_16x16x32_bf16 v[74:77], v[150:153], v[208:211], v[74:77]
	v_mfma_f32_16x16x32_bf16 v[126:129], v[146:149], v[168:171], v[126:129]
	v_mfma_f32_16x16x32_bf16 v[122:125], v[154:157], v[168:171], v[122:125]
	v_mfma_f32_16x16x32_bf16 v[110:113], v[146:149], v[176:179], v[110:113]
	v_mfma_f32_16x16x32_bf16 v[106:109], v[154:157], v[176:179], v[106:109]
	v_mfma_f32_16x16x32_bf16 v[94:97], v[146:149], v[204:207], v[94:97]
	v_mfma_f32_16x16x32_bf16 v[90:93], v[154:157], v[204:207], v[90:93]
	v_mfma_f32_16x16x32_bf16 v[78:81], v[146:149], v[212:215], v[78:81]
	v_mfma_f32_16x16x32_bf16 v[74:77], v[154:157], v[212:215], v[74:77]
	s_setprio 0
	s_barrier
	s_add_i32 s4, 0, 0x1c000
	s_add_i32 s5, s10, s28
	v_add_u32_e32 v167, s4, v165
	v_lshl_add_u64 v[162:163], v[162:163], 0, s[6:7]
	s_mov_b32 m0, s5
	ds_read_b128 v[216:219], v167
	ds_read_b128 v[220:223], v167 offset:1024
	ds_read_b128 v[224:227], v167 offset:2048
	ds_read_b128 v[228:231], v167 offset:3072
	global_load_lds_dwordx4 v[162:163], off
	v_lshl_add_u64 v[162:163], v[184:185], 0, s[6:7]
	s_add_i32 m0, s5, 0x2000
	s_nop 0
	global_load_lds_dwordx4 v[162:163], off
	s_barrier
	s_waitcnt lgkmcnt(0)
	s_setprio 1
	s_waitcnt lgkmcnt(0)
	v_mfma_f32_16x16x32_bf16 v[118:121], v[216:219], v[158:161], v[118:121]
	v_mfma_f32_16x16x32_bf16 v[114:117], v[224:227], v[158:161], v[114:117]
	v_mfma_f32_16x16x32_bf16 v[102:105], v[216:219], v[172:175], v[102:105]
	v_mfma_f32_16x16x32_bf16 v[98:101], v[224:227], v[172:175], v[98:101]
	v_mfma_f32_16x16x32_bf16 v[86:89], v[216:219], v[180:183], v[86:89]
	v_mfma_f32_16x16x32_bf16 v[82:85], v[224:227], v[180:183], v[82:85]
	v_mfma_f32_16x16x32_bf16 v[70:73], v[216:219], v[208:211], v[70:73]
	v_mfma_f32_16x16x32_bf16 v[66:69], v[224:227], v[208:211], v[66:69]
	v_mfma_f32_16x16x32_bf16 v[118:121], v[220:223], v[168:171], v[118:121]
	v_mfma_f32_16x16x32_bf16 v[114:117], v[228:231], v[168:171], v[114:117]
	v_mfma_f32_16x16x32_bf16 v[102:105], v[220:223], v[176:179], v[102:105]
	v_mfma_f32_16x16x32_bf16 v[98:101], v[228:231], v[176:179], v[98:101]
	v_mfma_f32_16x16x32_bf16 v[86:89], v[220:223], v[204:207], v[86:89]
	v_mfma_f32_16x16x32_bf16 v[82:85], v[228:231], v[204:207], v[82:85]
	v_mfma_f32_16x16x32_bf16 v[70:73], v[220:223], v[212:215], v[70:73]
	v_mfma_f32_16x16x32_bf16 v[66:69], v[228:231], v[212:215], v[66:69]
	s_setprio 0
	s_mov_b32 m0, s42
	v_lshl_add_u64 v[162:163], v[232:233], 0, s[6:7]
	s_barrier
	ds_read_b128 v[158:161], v166 offset:49152
	ds_read_b128 v[168:171], v166 offset:50176
	ds_read_b128 v[172:175], v166 offset:51200
	ds_read_b128 v[176:179], v166 offset:52224
	ds_read_b128 v[180:183], v166 offset:53248
	ds_read_b128 v[204:207], v166 offset:54272
	ds_read_b128 v[208:211], v166 offset:55296
	ds_read_b128 v[212:215], v166 offset:56320
	global_load_lds_dwordx4 v[162:163], off
	v_lshl_add_u64 v[162:163], v[234:235], 0, s[6:7]
	s_mov_b32 m0, s43
	s_nop 0
	global_load_lds_dwordx4 v[162:163], off
	s_barrier
	s_waitcnt lgkmcnt(0)
	s_setprio 1
	s_waitcnt lgkmcnt(0)
	v_mfma_f32_16x16x32_bf16 v[62:65], v[142:145], v[158:161], v[62:65]
	v_mfma_f32_16x16x32_bf16 v[58:61], v[150:153], v[158:161], v[58:61]
	v_mfma_f32_16x16x32_bf16 v[46:49], v[142:145], v[172:175], v[46:49]
	v_mfma_f32_16x16x32_bf16 v[42:45], v[150:153], v[172:175], v[42:45]
	v_mfma_f32_16x16x32_bf16 v[30:33], v[142:145], v[180:183], v[30:33]
	v_mfma_f32_16x16x32_bf16 v[26:29], v[150:153], v[180:183], v[26:29]
	v_mfma_f32_16x16x32_bf16 v[14:17], v[142:145], v[208:211], v[14:17]
	v_mfma_f32_16x16x32_bf16 v[10:13], v[150:153], v[208:211], v[10:13]
	v_mfma_f32_16x16x32_bf16 v[62:65], v[146:149], v[168:171], v[62:65]
	v_mfma_f32_16x16x32_bf16 v[58:61], v[154:157], v[168:171], v[58:61]
	v_mfma_f32_16x16x32_bf16 v[46:49], v[146:149], v[176:179], v[46:49]
	v_mfma_f32_16x16x32_bf16 v[42:45], v[154:157], v[176:179], v[42:45]
	v_mfma_f32_16x16x32_bf16 v[30:33], v[146:149], v[204:207], v[30:33]
	v_mfma_f32_16x16x32_bf16 v[26:29], v[154:157], v[204:207], v[26:29]
	v_mfma_f32_16x16x32_bf16 v[14:17], v[146:149], v[212:215], v[14:17]
	v_mfma_f32_16x16x32_bf16 v[10:13], v[154:157], v[212:215], v[10:13]
	s_setprio 0
	s_barrier
	s_add_i32 s4, s4, s28
	v_lshl_add_u64 v[142:143], v[236:237], 0, s[6:7]
	s_mov_b32 m0, s4
	s_nop 0
	global_load_lds_dwordx4 v[142:143], off
	v_lshl_add_u64 v[142:143], v[238:239], 0, s[6:7]
	s_add_i32 m0, s4, 0x2000
	s_nop 0
	global_load_lds_dwordx4 v[142:143], off
	s_waitcnt vmcnt(6)
	s_barrier
	s_setprio 1
	v_mfma_f32_16x16x32_bf16 v[54:57], v[216:219], v[158:161], v[54:57]
	v_mfma_f32_16x16x32_bf16 v[50:53], v[224:227], v[158:161], v[50:53]
	v_mfma_f32_16x16x32_bf16 v[38:41], v[216:219], v[172:175], v[38:41]
	v_mfma_f32_16x16x32_bf16 v[34:37], v[224:227], v[172:175], v[34:37]
	v_mfma_f32_16x16x32_bf16 v[22:25], v[216:219], v[180:183], v[22:25]
	v_mfma_f32_16x16x32_bf16 v[18:21], v[224:227], v[180:183], v[18:21]
	v_mfma_f32_16x16x32_bf16 v[6:9], v[216:219], v[208:211], v[6:9]
	v_mfma_f32_16x16x32_bf16 v[2:5], v[224:227], v[208:211], v[2:5]
	v_mfma_f32_16x16x32_bf16 v[54:57], v[220:223], v[168:171], v[54:57]
	v_mfma_f32_16x16x32_bf16 v[50:53], v[228:231], v[168:171], v[50:53]
	v_mfma_f32_16x16x32_bf16 v[38:41], v[220:223], v[176:179], v[38:41]
	v_mfma_f32_16x16x32_bf16 v[34:37], v[228:231], v[176:179], v[34:37]
	v_mfma_f32_16x16x32_bf16 v[22:25], v[220:223], v[204:207], v[22:25]
	v_mfma_f32_16x16x32_bf16 v[18:21], v[228:231], v[204:207], v[18:21]
	v_mfma_f32_16x16x32_bf16 v[6:9], v[220:223], v[212:215], v[6:9]
	v_mfma_f32_16x16x32_bf16 v[2:5], v[228:231], v[212:215], v[2:5]
	s_setprio 0
	s_add_u32 s0, s0, 0x100
	s_addc_u32 s1, s1, 0
	s_add_u32 s20, s20, 0x100
	s_addc_u32 s21, s21, 0
	s_cmp_ge_u32 s22, s35
	s_mov_b32 s4, s22
	s_barrier
	s_cbranch_scc0 .LBB0_282
	v_mov_b32_e32 v143, v1
	v_mov_b32_e32 v144, v164
	s_lshl_b32 s5, s68, 8
	s_cmp_lg_u32 s68, s19
	v_lshl_add_u32 v142, v143, 4, v144
	s_mov_b64 s[0:1], -1
	s_cbranch_scc0 .LBB0_285
	s_add_i32 s4, s5, s40
	v_and_or_b32 v145, v142, 63, s4
	v_lshlrev_b32_e32 v162, 1, v142
	v_add_u32_e32 v145, s50, v145
	v_and_b32_e32 v146, 0xffffff80, v162
	v_add_u32_e32 v146, v145, v146
	v_ashrrev_i32_e32 v147, 31, v146
	v_readlane_b32 s0, v243, 61
	v_lshlrev_b64 v[146:147], 6, v[146:147]
	v_readlane_b32 s1, v243, 62
	v_lshl_add_u32 v167, v142, 2, s49
	s_nop 0
	v_lshl_add_u64 v[158:159], s[0:1], 0, v[146:147]
	global_load_dwordx4 v[146:149], v[158:159], off offset:48
	global_load_dwordx4 v[150:153], v[158:159], off offset:32
	global_load_dwordx4 v[154:157], v[158:159], off offset:16
	s_nop 0
	global_load_dwordx4 v[158:161], v[158:159], off
	v_add_u32_e32 v222, 0x80, v162
	v_and_b32_e32 v222, 0xffffff80, v222
	v_add_u32_e32 v222, v145, v222
	v_ashrrev_i32_e32 v223, 31, v222
	v_lshlrev_b64 v[222:223], 6, v[222:223]
	v_lshl_add_u64 v[220:221], s[0:1], 0, v[222:223]
	global_load_dwordx4 v[204:207], v[220:221], off offset:48
	global_load_dwordx4 v[208:211], v[220:221], off offset:32
	global_load_dwordx4 v[212:215], v[220:221], off offset:16
	global_load_dwordx4 v[216:219], v[220:221], off
	s_waitcnt vmcnt(4)
	v_add_f32_e32 v146, v146, v147
	v_add_f32_e32 v150, v150, v151
	v_add_f32_e32 v154, v154, v155
	v_add_f32_e32 v158, v158, v159
	v_add_f32_e32 v158, v160, v158
	v_add_f32_e32 v154, v156, v154
	v_add_f32_e32 v158, v161, v158
	v_add_f32_e32 v154, v157, v154
	v_add_f32_e32 v150, v152, v150
	v_add_f32_e32 v154, v158, v154
	v_add_f32_e32 v150, v153, v150
	v_add_f32_e32 v146, v148, v146
	v_add_f32_e32 v150, v154, v150
	v_add_f32_e32 v146, v149, v146
	v_add_f32_e32 v146, v150, v146
	v_fmamk_f32 v146, v146, 0x3a800000, v188
	v_rsq_f32_e32 v163, v146
	s_mov_b64 s[0:1], 0
	s_waitcnt vmcnt(0)
	v_add_f32_e32 v146, v204, v205
	v_add_f32_e32 v150, v208, v209
	v_add_f32_e32 v154, v212, v213
	v_add_f32_e32 v145, v216, v217
	v_add_f32_e32 v145, v218, v145
	v_add_f32_e32 v154, v214, v154
	v_add_f32_e32 v145, v219, v145
	v_add_f32_e32 v154, v215, v154
	v_add_f32_e32 v150, v210, v150
	v_add_f32_e32 v145, v145, v154
	v_add_f32_e32 v150, v211, v150
	v_add_f32_e32 v146, v206, v146
	v_add_f32_e32 v145, v145, v150
	v_add_f32_e32 v146, v207, v146
	v_add_f32_e32 v145, v145, v146
	v_fmamk_f32 v145, v145, 0x3a800000, v188
	v_rsq_f32_e32 v145, v145
	ds_write2st64_b32 v167, v163, v145 offset1:1
	s_waitcnt lgkmcnt(0)

.LBB0_347:
	s_add_i32 s15, s4, 2
	s_add_u32 s10, s0, 0x80
	s_addc_u32 s5, s1, 0
	s_add_i32 s16, 0, 0x10000
	v_add_u32_e32 v142, s16, v205
	ds_read_b128 v[130:133], v142
	ds_read_b128 v[134:137], v142 offset:1024
	ds_read_b128 v[138:141], v142 offset:2048
	ds_read_b128 v[142:145], v142 offset:3072
	s_cmp_eq_u32 s79, s4
	s_cselect_b32 s4, s44, s10
	s_cselect_b32 s5, s45, s5
	s_cselect_b32 s11, s47, s13
	s_cselect_b32 s10, s46, s12
	v_lshl_add_u64 v[212:213], s[0:1], 0, v[154:155]
	s_add_i32 m0, s71, 0xc000
	ds_read_b128 v[158:161], v206
	ds_read_b128 v[162:165], v206 offset:1024
	ds_read_b128 v[166:169], v206 offset:2048
	ds_read_b128 v[170:173], v206 offset:3072
	ds_read_b128 v[174:177], v206 offset:4096
	ds_read_b128 v[178:181], v206 offset:5120
	ds_read_b128 v[182:185], v206 offset:6144
	ds_read_b128 v[208:211], v206 offset:7168
	global_load_lds_dwordx4 v[212:213], off
	v_lshl_add_u64 v[212:213], s[0:1], 0, v[156:157]
	s_add_i32 m0, s71, 0xe000
	s_nop 0
	global_load_lds_dwordx4 v[212:213], off
	s_waitcnt lgkmcnt(8)
	s_barrier
	s_waitcnt lgkmcnt(0)
	s_setprio 1
	s_waitcnt lgkmcnt(0)
	v_mfma_f32_16x16x32_bf16 v[126:129], v[130:133], v[158:161], v[126:129]
	v_mfma_f32_16x16x32_bf16 v[122:125], v[138:141], v[158:161], v[122:125]
	v_mfma_f32_16x16x32_bf16 v[110:113], v[130:133], v[166:169], v[110:113]
	v_mfma_f32_16x16x32_bf16 v[106:109], v[138:141], v[166:169], v[106:109]
	v_mfma_f32_16x16x32_bf16 v[94:97], v[130:133], v[174:177], v[94:97]
	v_mfma_f32_16x16x32_bf16 v[90:93], v[138:141], v[174:177], v[90:93]
	v_mfma_f32_16x16x32_bf16 v[78:81], v[130:133], v[182:185], v[78:81]
	v_mfma_f32_16x16x32_bf16 v[74:77], v[138:141], v[182:185], v[74:77]
	v_mfma_f32_16x16x32_bf16 v[126:129], v[134:137], v[162:165], v[126:129]
	v_mfma_f32_16x16x32_bf16 v[122:125], v[142:145], v[162:165], v[122:125]
	v_mfma_f32_16x16x32_bf16 v[110:113], v[134:137], v[170:173], v[110:113]
	v_mfma_f32_16x16x32_bf16 v[106:109], v[142:145], v[170:173], v[106:109]
	v_mfma_f32_16x16x32_bf16 v[94:97], v[134:137], v[178:181], v[94:97]
	v_mfma_f32_16x16x32_bf16 v[90:93], v[142:145], v[178:181], v[90:93]
	v_mfma_f32_16x16x32_bf16 v[78:81], v[134:137], v[208:211], v[78:81]
	v_mfma_f32_16x16x32_bf16 v[74:77], v[142:145], v[208:211], v[74:77]
	s_setprio 0
	s_barrier
	s_add_i32 s17, 0, 0x14000
	s_add_i32 s16, s16, s70
	v_add_u32_e32 v207, s17, v205
	v_lshl_add_u64 v[228:229], s[10:11], 0, v[148:149]
	s_mov_b32 m0, s16
	ds_read_b128 v[212:215], v207
	ds_read_b128 v[216:219], v207 offset:1024
	ds_read_b128 v[220:223], v207 offset:2048
	ds_read_b128 v[224:227], v207 offset:3072
	global_load_lds_dwordx4 v[228:229], off
	v_lshl_add_u64 v[230:231], s[10:11], 0, v[152:153]
	s_add_i32 m0, s16, 0x2000
	s_nop 0
	global_load_lds_dwordx4 v[230:231], off
	s_barrier
	s_waitcnt lgkmcnt(0)
	s_setprio 1
	s_waitcnt lgkmcnt(0)
	v_mfma_f32_16x16x32_bf16 v[118:121], v[212:215], v[158:161], v[118:121]
	v_mfma_f32_16x16x32_bf16 v[114:117], v[220:223], v[158:161], v[114:117]
	v_mfma_f32_16x16x32_bf16 v[102:105], v[212:215], v[166:169], v[102:105]
	v_mfma_f32_16x16x32_bf16 v[98:101], v[220:223], v[166:169], v[98:101]
	v_mfma_f32_16x16x32_bf16 v[86:89], v[212:215], v[174:177], v[86:89]
	v_mfma_f32_16x16x32_bf16 v[82:85], v[220:223], v[174:177], v[82:85]
	v_mfma_f32_16x16x32_bf16 v[70:73], v[212:215], v[182:185], v[70:73]
	v_mfma_f32_16x16x32_bf16 v[66:69], v[220:223], v[182:185], v[66:69]
	v_mfma_f32_16x16x32_bf16 v[118:121], v[216:219], v[162:165], v[118:121]
	v_mfma_f32_16x16x32_bf16 v[114:117], v[224:227], v[162:165], v[114:117]
	v_mfma_f32_16x16x32_bf16 v[102:105], v[216:219], v[170:173], v[102:105]
	v_mfma_f32_16x16x32_bf16 v[98:101], v[224:227], v[170:173], v[98:101]
	v_mfma_f32_16x16x32_bf16 v[86:89], v[216:219], v[178:181], v[86:89]
	v_mfma_f32_16x16x32_bf16 v[82:85], v[224:227], v[178:181], v[82:85]
	v_mfma_f32_16x16x32_bf16 v[70:73], v[216:219], v[208:211], v[70:73]
	v_mfma_f32_16x16x32_bf16 v[66:69], v[224:227], v[208:211], v[66:69]
	s_setprio 0
	s_mov_b32 m0, s71
	v_lshl_add_u64 v[232:233], s[4:5], 0, v[146:147]
	s_barrier
	ds_read_b128 v[158:161], v206 offset:16384
	ds_read_b128 v[162:165], v206 offset:17408
	ds_read_b128 v[166:169], v206 offset:18432
	ds_read_b128 v[170:173], v206 offset:19456
	ds_read_b128 v[174:177], v206 offset:20480
	ds_read_b128 v[178:181], v206 offset:21504
	ds_read_b128 v[182:185], v206 offset:22528
	ds_read_b128 v[208:211], v206 offset:23552
	global_load_lds_dwordx4 v[232:233], off
	v_lshl_add_u64 v[234:235], s[4:5], 0, v[150:151]
	s_mov_b32 m0, s72
	s_nop 0
	global_load_lds_dwordx4 v[234:235], off
	s_barrier
	s_waitcnt lgkmcnt(0)
	s_setprio 1
	s_waitcnt lgkmcnt(0)
	v_mfma_f32_16x16x32_bf16 v[62:65], v[130:133], v[158:161], v[62:65]
	v_mfma_f32_16x16x32_bf16 v[58:61], v[138:141], v[158:161], v[58:61]
	v_mfma_f32_16x16x32_bf16 v[46:49], v[130:133], v[166:169], v[46:49]
	v_mfma_f32_16x16x32_bf16 v[42:45], v[138:141], v[166:169], v[42:45]
	v_mfma_f32_16x16x32_bf16 v[30:33], v[130:133], v[174:177], v[30:33]
	v_mfma_f32_16x16x32_bf16 v[26:29], v[138:141], v[174:177], v[26:29]
	v_mfma_f32_16x16x32_bf16 v[14:17], v[130:133], v[182:185], v[14:17]
	v_mfma_f32_16x16x32_bf16 v[10:13], v[138:141], v[182:185], v[10:13]
	v_mfma_f32_16x16x32_bf16 v[62:65], v[134:137], v[162:165], v[62:65]
	v_mfma_f32_16x16x32_bf16 v[58:61], v[142:145], v[162:165], v[58:61]
	v_mfma_f32_16x16x32_bf16 v[46:49], v[134:137], v[170:173], v[46:49]
	v_mfma_f32_16x16x32_bf16 v[42:45], v[142:145], v[170:173], v[42:45]
	v_mfma_f32_16x16x32_bf16 v[30:33], v[134:137], v[178:181], v[30:33]
	v_mfma_f32_16x16x32_bf16 v[26:29], v[142:145], v[178:181], v[26:29]
	v_mfma_f32_16x16x32_bf16 v[14:17], v[134:137], v[208:211], v[14:17]
	v_mfma_f32_16x16x32_bf16 v[10:13], v[142:145], v[208:211], v[10:13]
	s_setprio 0
	s_barrier
	s_add_u32 s10, s10, s92
	s_addc_u32 s11, s11, 0
	s_add_i32 s16, s17, s70
	v_lshl_add_u64 v[236:237], s[10:11], 0, v[148:149]
	s_mov_b32 m0, s16
	v_lshl_add_u64 v[238:239], s[10:11], 0, v[152:153]
	global_load_lds_dwordx4 v[236:237], off
	s_add_i32 m0, s16, 0x2000
	s_nop 0
	global_load_lds_dwordx4 v[238:239], off
	s_waitcnt vmcnt(6)
	s_barrier
	s_setprio 1
	v_mfma_f32_16x16x32_bf16 v[54:57], v[212:215], v[158:161], v[54:57]
	v_mfma_f32_16x16x32_bf16 v[50:53], v[220:223], v[158:161], v[50:53]
	v_mfma_f32_16x16x32_bf16 v[38:41], v[212:215], v[166:169], v[38:41]
	v_mfma_f32_16x16x32_bf16 v[34:37], v[220:223], v[166:169], v[34:37]
	v_mfma_f32_16x16x32_bf16 v[22:25], v[212:215], v[174:177], v[22:25]
	v_mfma_f32_16x16x32_bf16 v[18:21], v[220:223], v[174:177], v[18:21]
	v_mfma_f32_16x16x32_bf16 v[6:9], v[212:215], v[182:185], v[6:9]
	v_mfma_f32_16x16x32_bf16 v[2:5], v[220:223], v[182:185], v[2:5]
	v_mfma_f32_16x16x32_bf16 v[54:57], v[216:219], v[162:165], v[54:57]
	v_mfma_f32_16x16x32_bf16 v[50:53], v[224:227], v[162:165], v[50:53]
	v_mfma_f32_16x16x32_bf16 v[38:41], v[216:219], v[170:173], v[38:41]
	v_mfma_f32_16x16x32_bf16 v[34:37], v[224:227], v[170:173], v[34:37]
	v_mfma_f32_16x16x32_bf16 v[22:25], v[216:219], v[178:181], v[22:25]
	v_mfma_f32_16x16x32_bf16 v[18:21], v[224:227], v[178:181], v[18:21]
	v_mfma_f32_16x16x32_bf16 v[6:9], v[216:219], v[208:211], v[6:9]
	v_mfma_f32_16x16x32_bf16 v[2:5], v[224:227], v[208:211], v[2:5]
	s_setprio 0
	s_add_i32 s10, 0, 0x18000
	v_add_u32_e32 v142, s10, v205
	s_barrier
	ds_read_b128 v[130:133], v142
	ds_read_b128 v[134:137], v142 offset:1024
	ds_read_b128 v[138:141], v142 offset:2048
	ds_read_b128 v[142:145], v142 offset:3072
	s_add_u32 s4, s4, s92
	s_addc_u32 s5, s5, 0
	s_mov_b32 m0, s73
	v_lshl_add_u64 v[212:213], s[4:5], 0, v[146:147]
	ds_read_b128 v[158:161], v206 offset:32768
	ds_read_b128 v[162:165], v206 offset:33792
	ds_read_b128 v[166:169], v206 offset:34816
	ds_read_b128 v[170:173], v206 offset:35840
	ds_read_b128 v[174:177], v206 offset:36864
	ds_read_b128 v[178:181], v206 offset:37888
	ds_read_b128 v[182:185], v206 offset:38912
	ds_read_b128 v[208:211], v206 offset:39936
	global_load_lds_dwordx4 v[212:213], off
	v_lshl_add_u64 v[212:213], s[4:5], 0, v[150:151]
	s_mov_b32 m0, s74
	s_nop 0
	global_load_lds_dwordx4 v[212:213], off
	s_waitcnt lgkmcnt(8)
	s_barrier
	s_waitcnt lgkmcnt(0)
	s_setprio 1
	s_waitcnt lgkmcnt(0)
	v_mfma_f32_16x16x32_bf16 v[126:129], v[130:133], v[158:161], v[126:129]
	v_mfma_f32_16x16x32_bf16 v[122:125], v[138:141], v[158:161], v[122:125]
	v_mfma_f32_16x16x32_bf16 v[110:113], v[130:133], v[166:169], v[110:113]
	v_mfma_f32_16x16x32_bf16 v[106:109], v[138:141], v[166:169], v[106:109]
	v_mfma_f32_16x16x32_bf16 v[94:97], v[130:133], v[174:177], v[94:97]
	v_mfma_f32_16x16x32_bf16 v[90:93], v[138:141], v[174:177], v[90:93]
	v_mfma_f32_16x16x32_bf16 v[78:81], v[130:133], v[182:185], v[78:81]
	v_mfma_f32_16x16x32_bf16 v[74:77], v[138:141], v[182:185], v[74:77]
	v_mfma_f32_16x16x32_bf16 v[126:129], v[134:137], v[162:165], v[126:129]
	v_mfma_f32_16x16x32_bf16 v[122:125], v[142:145], v[162:165], v[122:125]
	v_mfma_f32_16x16x32_bf16 v[110:113], v[134:137], v[170:173], v[110:113]
	v_mfma_f32_16x16x32_bf16 v[106:109], v[142:145], v[170:173], v[106:109]
	v_mfma_f32_16x16x32_bf16 v[94:97], v[134:137], v[178:181], v[94:97]
	v_mfma_f32_16x16x32_bf16 v[90:93], v[142:145], v[178:181], v[90:93]
	v_mfma_f32_16x16x32_bf16 v[78:81], v[134:137], v[208:211], v[78:81]
	v_mfma_f32_16x16x32_bf16 v[74:77], v[142:145], v[208:211], v[74:77]
	s_setprio 0
	s_barrier
	s_add_i32 s4, 0, 0x1c000
	s_add_i32 s5, s10, s70
	v_add_u32_e32 v207, s4, v205
	v_lshl_add_u64 v[228:229], v[228:229], 0, s[6:7]
	s_mov_b32 m0, s5
	ds_read_b128 v[212:215], v207
	ds_read_b128 v[216:219], v207 offset:1024
	ds_read_b128 v[220:223], v207 offset:2048
	ds_read_b128 v[224:227], v207 offset:3072
	global_load_lds_dwordx4 v[228:229], off
	v_lshl_add_u64 v[228:229], v[230:231], 0, s[6:7]
	s_add_i32 m0, s5, 0x2000
	s_nop 0
	global_load_lds_dwordx4 v[228:229], off
	s_barrier
	s_waitcnt lgkmcnt(0)
	s_setprio 1
	s_waitcnt lgkmcnt(0)
	v_mfma_f32_16x16x32_bf16 v[118:121], v[212:215], v[158:161], v[118:121]
	v_mfma_f32_16x16x32_bf16 v[114:117], v[220:223], v[158:161], v[114:117]
	v_mfma_f32_16x16x32_bf16 v[102:105], v[212:215], v[166:169], v[102:105]
	v_mfma_f32_16x16x32_bf16 v[98:101], v[220:223], v[166:169], v[98:101]
	v_mfma_f32_16x16x32_bf16 v[86:89], v[212:215], v[174:177], v[86:89]
	v_mfma_f32_16x16x32_bf16 v[82:85], v[220:223], v[174:177], v[82:85]
	v_mfma_f32_16x16x32_bf16 v[70:73], v[212:215], v[182:185], v[70:73]
	v_mfma_f32_16x16x32_bf16 v[66:69], v[220:223], v[182:185], v[66:69]
	v_mfma_f32_16x16x32_bf16 v[118:121], v[216:219], v[162:165], v[118:121]
	v_mfma_f32_16x16x32_bf16 v[114:117], v[224:227], v[162:165], v[114:117]
	v_mfma_f32_16x16x32_bf16 v[102:105], v[216:219], v[170:173], v[102:105]
	v_mfma_f32_16x16x32_bf16 v[98:101], v[224:227], v[170:173], v[98:101]
	v_mfma_f32_16x16x32_bf16 v[86:89], v[216:219], v[178:181], v[86:89]
	v_mfma_f32_16x16x32_bf16 v[82:85], v[224:227], v[178:181], v[82:85]
	v_mfma_f32_16x16x32_bf16 v[70:73], v[216:219], v[208:211], v[70:73]
	v_mfma_f32_16x16x32_bf16 v[66:69], v[224:227], v[208:211], v[66:69]
	s_setprio 0
	s_mov_b32 m0, s77
	v_lshl_add_u64 v[228:229], v[232:233], 0, s[6:7]
	s_barrier
	ds_read_b128 v[158:161], v206 offset:49152
	ds_read_b128 v[162:165], v206 offset:50176
	ds_read_b128 v[166:169], v206 offset:51200
	ds_read_b128 v[170:173], v206 offset:52224
	ds_read_b128 v[174:177], v206 offset:53248
	ds_read_b128 v[178:181], v206 offset:54272
	ds_read_b128 v[182:185], v206 offset:55296
	ds_read_b128 v[208:211], v206 offset:56320
	global_load_lds_dwordx4 v[228:229], off
	v_lshl_add_u64 v[228:229], v[234:235], 0, s[6:7]
	s_mov_b32 m0, s78
	s_nop 0
	global_load_lds_dwordx4 v[228:229], off
	s_barrier
	s_waitcnt lgkmcnt(0)
	s_setprio 1
	s_waitcnt lgkmcnt(0)
	v_mfma_f32_16x16x32_bf16 v[62:65], v[130:133], v[158:161], v[62:65]
	v_mfma_f32_16x16x32_bf16 v[58:61], v[138:141], v[158:161], v[58:61]
	v_mfma_f32_16x16x32_bf16 v[46:49], v[130:133], v[166:169], v[46:49]
	v_mfma_f32_16x16x32_bf16 v[42:45], v[138:141], v[166:169], v[42:45]
	v_mfma_f32_16x16x32_bf16 v[30:33], v[130:133], v[174:177], v[30:33]
	v_mfma_f32_16x16x32_bf16 v[26:29], v[138:141], v[174:177], v[26:29]
	v_mfma_f32_16x16x32_bf16 v[14:17], v[130:133], v[182:185], v[14:17]
	v_mfma_f32_16x16x32_bf16 v[10:13], v[138:141], v[182:185], v[10:13]
	v_mfma_f32_16x16x32_bf16 v[62:65], v[134:137], v[162:165], v[62:65]
	v_mfma_f32_16x16x32_bf16 v[58:61], v[142:145], v[162:165], v[58:61]
	v_mfma_f32_16x16x32_bf16 v[46:49], v[134:137], v[170:173], v[46:49]
	v_mfma_f32_16x16x32_bf16 v[42:45], v[142:145], v[170:173], v[42:45]
	v_mfma_f32_16x16x32_bf16 v[30:33], v[134:137], v[178:181], v[30:33]
	v_mfma_f32_16x16x32_bf16 v[26:29], v[142:145], v[178:181], v[26:29]
	v_mfma_f32_16x16x32_bf16 v[14:17], v[134:137], v[208:211], v[14:17]
	v_mfma_f32_16x16x32_bf16 v[10:13], v[142:145], v[208:211], v[10:13]
	s_setprio 0
	s_barrier
	s_add_i32 s4, s4, s70
	v_lshl_add_u64 v[130:131], v[236:237], 0, s[6:7]
	s_mov_b32 m0, s4
	s_nop 0
	global_load_lds_dwordx4 v[130:131], off
	v_lshl_add_u64 v[130:131], v[238:239], 0, s[6:7]
	s_add_i32 m0, s4, 0x2000
	s_nop 0
	global_load_lds_dwordx4 v[130:131], off
	s_waitcnt vmcnt(6)
	s_barrier
	s_setprio 1
	v_mfma_f32_16x16x32_bf16 v[54:57], v[212:215], v[158:161], v[54:57]
	v_mfma_f32_16x16x32_bf16 v[50:53], v[220:223], v[158:161], v[50:53]
	v_mfma_f32_16x16x32_bf16 v[38:41], v[212:215], v[166:169], v[38:41]
	v_mfma_f32_16x16x32_bf16 v[34:37], v[220:223], v[166:169], v[34:37]
	v_mfma_f32_16x16x32_bf16 v[22:25], v[212:215], v[174:177], v[22:25]
	v_mfma_f32_16x16x32_bf16 v[18:21], v[220:223], v[174:177], v[18:21]
	v_mfma_f32_16x16x32_bf16 v[6:9], v[212:215], v[182:185], v[6:9]
	v_mfma_f32_16x16x32_bf16 v[2:5], v[220:223], v[182:185], v[2:5]
	v_mfma_f32_16x16x32_bf16 v[54:57], v[216:219], v[162:165], v[54:57]
	v_mfma_f32_16x16x32_bf16 v[50:53], v[224:227], v[162:165], v[50:53]
	v_mfma_f32_16x16x32_bf16 v[38:41], v[216:219], v[170:173], v[38:41]
	v_mfma_f32_16x16x32_bf16 v[34:37], v[224:227], v[170:173], v[34:37]
	v_mfma_f32_16x16x32_bf16 v[22:25], v[216:219], v[178:181], v[22:25]
	v_mfma_f32_16x16x32_bf16 v[18:21], v[224:227], v[178:181], v[18:21]
	v_mfma_f32_16x16x32_bf16 v[6:9], v[216:219], v[208:211], v[6:9]
	v_mfma_f32_16x16x32_bf16 v[2:5], v[224:227], v[208:211], v[2:5]
	s_setprio 0
	s_add_u32 s0, s0, 0x100
	s_addc_u32 s1, s1, 0
	s_add_u32 s12, s12, 0x100
	s_addc_u32 s13, s13, 0
	s_cmp_ge_u32 s15, s75
	s_mov_b32 s4, s15
	s_barrier
	s_cbranch_scc0 .LBB0_347
	v_mov_b32_e32 v130, v1
	v_mov_b32_e32 v131, v204
	s_lshl_b32 s5, s69, 8
	s_cmp_lg_u32 s69, s14
	v_lshl_add_u32 v140, v130, 4, v131
	s_mov_b64 s[0:1], -1
	s_cbranch_scc0 .LBB0_350
	s_add_i32 s4, s5, s76
	v_and_or_b32 v132, v140, 63, s4
	v_lshlrev_b32_e32 v162, 1, v140
	v_add_u32_e32 v141, s50, v132
	v_and_b32_e32 v132, 0xffffff80, v162
	v_add_u32_e32 v132, v141, v132
	v_ashrrev_i32_e32 v133, 31, v132
	v_readlane_b32 s0, v242, 3
	v_lshlrev_b64 v[132:133], 6, v[132:133]
	v_readlane_b32 s1, v242, 4
	v_lshl_add_u32 v164, v140, 2, s97
	s_nop 0
	v_lshl_add_u64 v[158:159], s[0:1], 0, v[132:133]
	global_load_dwordx4 v[132:135], v[158:159], off offset:48
	global_load_dwordx4 v[136:139], v[158:159], off offset:32
	global_load_dwordx4 v[142:145], v[158:159], off offset:16
	s_nop 0
	global_load_dwordx4 v[158:161], v[158:159], off
	v_add_u32_e32 v234, 0x80, v162
	v_and_b32_e32 v234, 0xffffff80, v234
	v_add_u32_e32 v234, v141, v234
	v_ashrrev_i32_e32 v235, 31, v234
	v_lshlrev_b64 v[234:235], 6, v[234:235]
	v_lshl_add_u64 v[232:233], s[0:1], 0, v[234:235]
	global_load_dwordx4 v[216:219], v[232:233], off offset:48
	global_load_dwordx4 v[220:223], v[232:233], off offset:32
	global_load_dwordx4 v[224:227], v[232:233], off offset:16
	global_load_dwordx4 v[228:231], v[232:233], off
	s_waitcnt vmcnt(4)
	v_add_f32_e32 v132, v132, v133
	v_add_f32_e32 v136, v136, v137
	v_add_f32_e32 v142, v142, v143
	v_add_f32_e32 v158, v158, v159
	v_add_f32_e32 v158, v160, v158
	v_add_f32_e32 v142, v144, v142
	v_add_f32_e32 v158, v161, v158
	v_add_f32_e32 v142, v145, v142
	v_add_f32_e32 v136, v138, v136
	v_add_f32_e32 v142, v158, v142
	v_add_f32_e32 v136, v139, v136
	v_add_f32_e32 v132, v134, v132
	v_add_f32_e32 v136, v142, v136
	v_add_f32_e32 v132, v135, v132
	v_add_f32_e32 v132, v136, v132
	v_fmamk_f32 v132, v132, 0x3a800000, v188
	v_rsq_f32_e32 v163, v132
	s_mov_b64 s[0:1], 0
	s_waitcnt vmcnt(0)
	v_add_f32_e32 v132, v216, v217
	v_add_f32_e32 v136, v220, v221
	v_add_f32_e32 v142, v224, v225
	v_add_f32_e32 v141, v228, v229
	v_add_f32_e32 v141, v230, v141
	v_add_f32_e32 v142, v226, v142
	v_add_f32_e32 v141, v231, v141
	v_add_f32_e32 v142, v227, v142
	v_add_f32_e32 v136, v222, v136
	v_add_f32_e32 v141, v141, v142
	v_add_f32_e32 v136, v223, v136
	v_add_f32_e32 v132, v218, v132
	v_add_f32_e32 v136, v141, v136
	v_add_f32_e32 v132, v219, v132
	v_add_f32_e32 v132, v136, v132
	v_fmamk_f32 v132, v132, 0x3a800000, v188
	v_rsq_f32_e32 v132, v132
	ds_write2st64_b32 v164, v163, v132 offset1:1
	s_waitcnt lgkmcnt(0)

.LBB0_664:
	s_add_i32 s66, s4, 2
	s_add_u32 s18, s0, 0x80
	s_addc_u32 s5, s1, 0
	s_add_i32 s68, 0, 0x10000
	v_add_u32_e32 v150, s68, v153
	ds_read_b128 v[142:145], v150
	ds_read_b128 v[146:149], v150 offset:1024
	ds_read_b128 v[156:159], v150 offset:2048
	ds_read_b128 v[160:163], v150 offset:3072
	s_cmp_eq_u32 s43, s4
	s_cselect_b32 s4, s10, s18
	s_cselect_b32 s5, s11, s5
	s_cselect_b32 s19, s13, s65
	s_cselect_b32 s18, s12, s49
	v_lshl_add_u64 v[150:151], s[0:1], 0, v[138:139]
	s_add_i32 m0, s28, 0xc000
	ds_read_b128 v[164:167], v154
	ds_read_b128 v[168:171], v154 offset:1024
	ds_read_b128 v[172:175], v154 offset:2048
	ds_read_b128 v[176:179], v154 offset:3072
	ds_read_b128 v[180:183], v154 offset:4096
	ds_read_b128 v[204:207], v154 offset:5120
	ds_read_b128 v[208:211], v154 offset:6144
	ds_read_b128 v[212:215], v154 offset:7168
	global_load_lds_dwordx4 v[150:151], off
	v_lshl_add_u64 v[150:151], s[0:1], 0, v[140:141]
	s_add_i32 m0, s28, 0xe000
	s_nop 0
	global_load_lds_dwordx4 v[150:151], off
	s_waitcnt lgkmcnt(8)
	s_barrier
	s_waitcnt lgkmcnt(0)
	s_setprio 1
	s_waitcnt lgkmcnt(0)
	v_mfma_f32_16x16x32_bf16 v[126:129], v[142:145], v[164:167], v[126:129]
	v_mfma_f32_16x16x32_bf16 v[122:125], v[156:159], v[164:167], v[122:125]
	v_mfma_f32_16x16x32_bf16 v[110:113], v[142:145], v[172:175], v[110:113]
	v_mfma_f32_16x16x32_bf16 v[106:109], v[156:159], v[172:175], v[106:109]
	v_mfma_f32_16x16x32_bf16 v[94:97], v[142:145], v[180:183], v[94:97]
	v_mfma_f32_16x16x32_bf16 v[90:93], v[156:159], v[180:183], v[90:93]
	v_mfma_f32_16x16x32_bf16 v[78:81], v[142:145], v[208:211], v[78:81]
	v_mfma_f32_16x16x32_bf16 v[74:77], v[156:159], v[208:211], v[74:77]
	v_mfma_f32_16x16x32_bf16 v[126:129], v[146:149], v[168:171], v[126:129]
	v_mfma_f32_16x16x32_bf16 v[122:125], v[160:163], v[168:171], v[122:125]
	v_mfma_f32_16x16x32_bf16 v[110:113], v[146:149], v[176:179], v[110:113]
	v_mfma_f32_16x16x32_bf16 v[106:109], v[160:163], v[176:179], v[106:109]
	v_mfma_f32_16x16x32_bf16 v[94:97], v[146:149], v[204:207], v[94:97]
	v_mfma_f32_16x16x32_bf16 v[90:93], v[160:163], v[204:207], v[90:93]
	v_mfma_f32_16x16x32_bf16 v[78:81], v[146:149], v[212:215], v[78:81]
	v_mfma_f32_16x16x32_bf16 v[74:77], v[160:163], v[212:215], v[74:77]
	s_setprio 0
	s_barrier
	s_add_i32 s69, 0, 0x14000
	v_add_u32_e32 v150, s69, v153
	s_add_i32 s68, s68, s25
	ds_read_b128 v[216:219], v150
	ds_read_b128 v[220:223], v150 offset:1024
	ds_read_b128 v[224:227], v150 offset:2048
	ds_read_b128 v[228:231], v150 offset:3072
	v_lshl_add_u64 v[150:151], s[18:19], 0, v[132:133]
	s_mov_b32 m0, s68
	v_lshl_add_u64 v[184:185], s[18:19], 0, v[136:137]
	global_load_lds_dwordx4 v[150:151], off
	s_add_i32 m0, s68, 0x2000
	s_nop 0
	global_load_lds_dwordx4 v[184:185], off
	s_barrier
	s_waitcnt lgkmcnt(0)
	s_setprio 1
	s_waitcnt lgkmcnt(0)
	v_mfma_f32_16x16x32_bf16 v[118:121], v[216:219], v[164:167], v[118:121]
	v_mfma_f32_16x16x32_bf16 v[114:117], v[224:227], v[164:167], v[114:117]
	v_mfma_f32_16x16x32_bf16 v[102:105], v[216:219], v[172:175], v[102:105]
	v_mfma_f32_16x16x32_bf16 v[98:101], v[224:227], v[172:175], v[98:101]
	v_mfma_f32_16x16x32_bf16 v[86:89], v[216:219], v[180:183], v[86:89]
	v_mfma_f32_16x16x32_bf16 v[82:85], v[224:227], v[180:183], v[82:85]
	v_mfma_f32_16x16x32_bf16 v[70:73], v[216:219], v[208:211], v[70:73]
	v_mfma_f32_16x16x32_bf16 v[66:69], v[224:227], v[208:211], v[66:69]
	v_mfma_f32_16x16x32_bf16 v[118:121], v[220:223], v[168:171], v[118:121]
	v_mfma_f32_16x16x32_bf16 v[114:117], v[228:231], v[168:171], v[114:117]
	v_mfma_f32_16x16x32_bf16 v[102:105], v[220:223], v[176:179], v[102:105]
	v_mfma_f32_16x16x32_bf16 v[98:101], v[228:231], v[176:179], v[98:101]
	v_mfma_f32_16x16x32_bf16 v[86:89], v[220:223], v[204:207], v[86:89]
	v_mfma_f32_16x16x32_bf16 v[82:85], v[228:231], v[204:207], v[82:85]
	v_mfma_f32_16x16x32_bf16 v[70:73], v[220:223], v[212:215], v[70:73]
	v_mfma_f32_16x16x32_bf16 v[66:69], v[228:231], v[212:215], v[66:69]
	s_setprio 0
	s_mov_b32 m0, s28
	v_lshl_add_u64 v[232:233], s[4:5], 0, v[130:131]
	s_barrier
	ds_read_b128 v[164:167], v154 offset:16384
	ds_read_b128 v[168:171], v154 offset:17408
	ds_read_b128 v[172:175], v154 offset:18432
	ds_read_b128 v[176:179], v154 offset:19456
	ds_read_b128 v[180:183], v154 offset:20480
	ds_read_b128 v[204:207], v154 offset:21504
	ds_read_b128 v[208:211], v154 offset:22528
	ds_read_b128 v[212:215], v154 offset:23552
	global_load_lds_dwordx4 v[232:233], off
	v_lshl_add_u64 v[234:235], s[4:5], 0, v[134:135]
	s_mov_b32 m0, s29
	s_nop 0
	global_load_lds_dwordx4 v[234:235], off
	s_barrier
	s_waitcnt lgkmcnt(0)
	s_setprio 1
	s_waitcnt lgkmcnt(0)
	v_mfma_f32_16x16x32_bf16 v[62:65], v[142:145], v[164:167], v[62:65]
	v_mfma_f32_16x16x32_bf16 v[58:61], v[156:159], v[164:167], v[58:61]
	v_mfma_f32_16x16x32_bf16 v[46:49], v[142:145], v[172:175], v[46:49]
	v_mfma_f32_16x16x32_bf16 v[42:45], v[156:159], v[172:175], v[42:45]
	v_mfma_f32_16x16x32_bf16 v[30:33], v[142:145], v[180:183], v[30:33]
	v_mfma_f32_16x16x32_bf16 v[26:29], v[156:159], v[180:183], v[26:29]
	v_mfma_f32_16x16x32_bf16 v[14:17], v[142:145], v[208:211], v[14:17]
	v_mfma_f32_16x16x32_bf16 v[10:13], v[156:159], v[208:211], v[10:13]
	v_mfma_f32_16x16x32_bf16 v[62:65], v[146:149], v[168:171], v[62:65]
	v_mfma_f32_16x16x32_bf16 v[58:61], v[160:163], v[168:171], v[58:61]
	v_mfma_f32_16x16x32_bf16 v[46:49], v[146:149], v[176:179], v[46:49]
	v_mfma_f32_16x16x32_bf16 v[42:45], v[160:163], v[176:179], v[42:45]
	v_mfma_f32_16x16x32_bf16 v[30:33], v[146:149], v[204:207], v[30:33]
	v_mfma_f32_16x16x32_bf16 v[26:29], v[160:163], v[204:207], v[26:29]
	v_mfma_f32_16x16x32_bf16 v[14:17], v[146:149], v[212:215], v[14:17]
	v_mfma_f32_16x16x32_bf16 v[10:13], v[160:163], v[212:215], v[10:13]
	s_setprio 0
	s_barrier
	s_add_u32 s18, s18, s14
	s_addc_u32 s19, s19, 0
	s_add_i32 s68, s69, s25
	v_lshl_add_u64 v[236:237], s[18:19], 0, v[132:133]
	s_mov_b32 m0, s68
	v_lshl_add_u64 v[238:239], s[18:19], 0, v[136:137]
	global_load_lds_dwordx4 v[236:237], off
	s_add_i32 m0, s68, 0x2000
	s_nop 0
	global_load_lds_dwordx4 v[238:239], off
	s_waitcnt vmcnt(6)
	s_barrier
	s_setprio 1
	v_mfma_f32_16x16x32_bf16 v[54:57], v[216:219], v[164:167], v[54:57]
	v_mfma_f32_16x16x32_bf16 v[50:53], v[224:227], v[164:167], v[50:53]
	v_mfma_f32_16x16x32_bf16 v[38:41], v[216:219], v[172:175], v[38:41]
	v_mfma_f32_16x16x32_bf16 v[34:37], v[224:227], v[172:175], v[34:37]
	v_mfma_f32_16x16x32_bf16 v[22:25], v[216:219], v[180:183], v[22:25]
	v_mfma_f32_16x16x32_bf16 v[18:21], v[224:227], v[180:183], v[18:21]
	v_mfma_f32_16x16x32_bf16 v[6:9], v[216:219], v[208:211], v[6:9]
	v_mfma_f32_16x16x32_bf16 v[2:5], v[224:227], v[208:211], v[2:5]
	v_mfma_f32_16x16x32_bf16 v[54:57], v[220:223], v[168:171], v[54:57]
	v_mfma_f32_16x16x32_bf16 v[50:53], v[228:231], v[168:171], v[50:53]
	v_mfma_f32_16x16x32_bf16 v[38:41], v[220:223], v[176:179], v[38:41]
	v_mfma_f32_16x16x32_bf16 v[34:37], v[228:231], v[176:179], v[34:37]
	v_mfma_f32_16x16x32_bf16 v[22:25], v[220:223], v[204:207], v[22:25]
	v_mfma_f32_16x16x32_bf16 v[18:21], v[228:231], v[204:207], v[18:21]
	v_mfma_f32_16x16x32_bf16 v[6:9], v[220:223], v[212:215], v[6:9]
	v_mfma_f32_16x16x32_bf16 v[2:5], v[228:231], v[212:215], v[2:5]
	s_setprio 0
	s_add_i32 s18, 0, 0x18000
	v_add_u32_e32 v155, s18, v153
	s_barrier
	ds_read_b128 v[142:145], v155
	ds_read_b128 v[146:149], v155 offset:1024
	ds_read_b128 v[156:159], v155 offset:2048
	ds_read_b128 v[160:163], v155 offset:3072
	s_add_u32 s4, s4, s14
	s_addc_u32 s5, s5, 0
	s_mov_b32 m0, s31
	v_lshl_add_u64 v[216:217], s[4:5], 0, v[130:131]
	ds_read_b128 v[164:167], v154 offset:32768
	ds_read_b128 v[168:171], v154 offset:33792
	ds_read_b128 v[172:175], v154 offset:34816
	ds_read_b128 v[176:179], v154 offset:35840
	ds_read_b128 v[180:183], v154 offset:36864
	ds_read_b128 v[204:207], v154 offset:37888
	ds_read_b128 v[208:211], v154 offset:38912
	ds_read_b128 v[212:215], v154 offset:39936
	global_load_lds_dwordx4 v[216:217], off
	v_lshl_add_u64 v[216:217], s[4:5], 0, v[134:135]
	s_mov_b32 m0, s34
	s_nop 0
	global_load_lds_dwordx4 v[216:217], off
	s_waitcnt lgkmcnt(8)
	s_barrier
	s_waitcnt lgkmcnt(0)
	s_setprio 1
	s_waitcnt lgkmcnt(0)
	v_mfma_f32_16x16x32_bf16 v[126:129], v[142:145], v[164:167], v[126:129]
	v_mfma_f32_16x16x32_bf16 v[122:125], v[156:159], v[164:167], v[122:125]
	v_mfma_f32_16x16x32_bf16 v[110:113], v[142:145], v[172:175], v[110:113]
	v_mfma_f32_16x16x32_bf16 v[106:109], v[156:159], v[172:175], v[106:109]
	v_mfma_f32_16x16x32_bf16 v[94:97], v[142:145], v[180:183], v[94:97]
	v_mfma_f32_16x16x32_bf16 v[90:93], v[156:159], v[180:183], v[90:93]
	v_mfma_f32_16x16x32_bf16 v[78:81], v[142:145], v[208:211], v[78:81]
	v_mfma_f32_16x16x32_bf16 v[74:77], v[156:159], v[208:211], v[74:77]
	v_mfma_f32_16x16x32_bf16 v[126:129], v[146:149], v[168:171], v[126:129]
	v_mfma_f32_16x16x32_bf16 v[122:125], v[160:163], v[168:171], v[122:125]
	v_mfma_f32_16x16x32_bf16 v[110:113], v[146:149], v[176:179], v[110:113]
	v_mfma_f32_16x16x32_bf16 v[106:109], v[160:163], v[176:179], v[106:109]
	v_mfma_f32_16x16x32_bf16 v[94:97], v[146:149], v[204:207], v[94:97]
	v_mfma_f32_16x16x32_bf16 v[90:93], v[160:163], v[204:207], v[90:93]
	v_mfma_f32_16x16x32_bf16 v[78:81], v[146:149], v[212:215], v[78:81]
	v_mfma_f32_16x16x32_bf16 v[74:77], v[160:163], v[212:215], v[74:77]
	s_setprio 0
	s_barrier
	s_add_i32 s4, 0, 0x1c000
	s_add_i32 s5, s18, s25
	v_add_u32_e32 v155, s4, v153
	v_lshl_add_u64 v[150:151], v[150:151], 0, s[6:7]
	s_mov_b32 m0, s5
	ds_read_b128 v[216:219], v155
	ds_read_b128 v[220:223], v155 offset:1024
	ds_read_b128 v[224:227], v155 offset:2048
	ds_read_b128 v[228:231], v155 offset:3072
	global_load_lds_dwordx4 v[150:151], off
	v_lshl_add_u64 v[150:151], v[184:185], 0, s[6:7]
	s_add_i32 m0, s5, 0x2000
	s_nop 0
	global_load_lds_dwordx4 v[150:151], off
	s_barrier
	s_waitcnt lgkmcnt(0)
	s_setprio 1
	s_waitcnt lgkmcnt(0)
	v_mfma_f32_16x16x32_bf16 v[118:121], v[216:219], v[164:167], v[118:121]
	v_mfma_f32_16x16x32_bf16 v[114:117], v[224:227], v[164:167], v[114:117]
	v_mfma_f32_16x16x32_bf16 v[102:105], v[216:219], v[172:175], v[102:105]
	v_mfma_f32_16x16x32_bf16 v[98:101], v[224:227], v[172:175], v[98:101]
	v_mfma_f32_16x16x32_bf16 v[86:89], v[216:219], v[180:183], v[86:89]
	v_mfma_f32_16x16x32_bf16 v[82:85], v[224:227], v[180:183], v[82:85]
	v_mfma_f32_16x16x32_bf16 v[70:73], v[216:219], v[208:211], v[70:73]
	v_mfma_f32_16x16x32_bf16 v[66:69], v[224:227], v[208:211], v[66:69]
	v_mfma_f32_16x16x32_bf16 v[118:121], v[220:223], v[168:171], v[118:121]
	v_mfma_f32_16x16x32_bf16 v[114:117], v[228:231], v[168:171], v[114:117]
	v_mfma_f32_16x16x32_bf16 v[102:105], v[220:223], v[176:179], v[102:105]
	v_mfma_f32_16x16x32_bf16 v[98:101], v[228:231], v[176:179], v[98:101]
	v_mfma_f32_16x16x32_bf16 v[86:89], v[220:223], v[204:207], v[86:89]
	v_mfma_f32_16x16x32_bf16 v[82:85], v[228:231], v[204:207], v[82:85]
	v_mfma_f32_16x16x32_bf16 v[70:73], v[220:223], v[212:215], v[70:73]
	v_mfma_f32_16x16x32_bf16 v[66:69], v[228:231], v[212:215], v[66:69]
	s_setprio 0
	s_mov_b32 m0, s41
	v_lshl_add_u64 v[150:151], v[232:233], 0, s[6:7]
	s_barrier
	ds_read_b128 v[164:167], v154 offset:49152
	ds_read_b128 v[168:171], v154 offset:50176
	ds_read_b128 v[172:175], v154 offset:51200
	ds_read_b128 v[176:179], v154 offset:52224
	ds_read_b128 v[180:183], v154 offset:53248
	ds_read_b128 v[204:207], v154 offset:54272
	ds_read_b128 v[208:211], v154 offset:55296
	ds_read_b128 v[212:215], v154 offset:56320
	global_load_lds_dwordx4 v[150:151], off
	v_lshl_add_u64 v[150:151], v[234:235], 0, s[6:7]
	s_mov_b32 m0, s42
	s_nop 0
	global_load_lds_dwordx4 v[150:151], off
	s_barrier
	s_waitcnt lgkmcnt(0)
	s_setprio 1
	s_waitcnt lgkmcnt(0)
	v_mfma_f32_16x16x32_bf16 v[62:65], v[142:145], v[164:167], v[62:65]
	v_mfma_f32_16x16x32_bf16 v[58:61], v[156:159], v[164:167], v[58:61]
	v_mfma_f32_16x16x32_bf16 v[46:49], v[142:145], v[172:175], v[46:49]
	v_mfma_f32_16x16x32_bf16 v[42:45], v[156:159], v[172:175], v[42:45]
	v_mfma_f32_16x16x32_bf16 v[30:33], v[142:145], v[180:183], v[30:33]
	v_mfma_f32_16x16x32_bf16 v[26:29], v[156:159], v[180:183], v[26:29]
	v_mfma_f32_16x16x32_bf16 v[14:17], v[142:145], v[208:211], v[14:17]
	v_mfma_f32_16x16x32_bf16 v[10:13], v[156:159], v[208:211], v[10:13]
	v_mfma_f32_16x16x32_bf16 v[62:65], v[146:149], v[168:171], v[62:65]
	v_mfma_f32_16x16x32_bf16 v[58:61], v[160:163], v[168:171], v[58:61]
	v_mfma_f32_16x16x32_bf16 v[46:49], v[146:149], v[176:179], v[46:49]
	v_mfma_f32_16x16x32_bf16 v[42:45], v[160:163], v[176:179], v[42:45]
	v_mfma_f32_16x16x32_bf16 v[30:33], v[146:149], v[204:207], v[30:33]
	v_mfma_f32_16x16x32_bf16 v[26:29], v[160:163], v[204:207], v[26:29]
	v_mfma_f32_16x16x32_bf16 v[14:17], v[146:149], v[212:215], v[14:17]
	v_mfma_f32_16x16x32_bf16 v[10:13], v[160:163], v[212:215], v[10:13]
	s_setprio 0
	s_barrier
	s_add_i32 s4, s4, s25
	v_lshl_add_u64 v[142:143], v[236:237], 0, s[6:7]
	s_mov_b32 m0, s4
	s_nop 0
	global_load_lds_dwordx4 v[142:143], off
	v_lshl_add_u64 v[142:143], v[238:239], 0, s[6:7]
	s_add_i32 m0, s4, 0x2000
	s_nop 0
	global_load_lds_dwordx4 v[142:143], off
	s_waitcnt vmcnt(6)
	s_barrier
	s_setprio 1
	v_mfma_f32_16x16x32_bf16 v[54:57], v[216:219], v[164:167], v[54:57]
	v_mfma_f32_16x16x32_bf16 v[50:53], v[224:227], v[164:167], v[50:53]
	v_mfma_f32_16x16x32_bf16 v[38:41], v[216:219], v[172:175], v[38:41]
	v_mfma_f32_16x16x32_bf16 v[34:37], v[224:227], v[172:175], v[34:37]
	v_mfma_f32_16x16x32_bf16 v[22:25], v[216:219], v[180:183], v[22:25]
	v_mfma_f32_16x16x32_bf16 v[18:21], v[224:227], v[180:183], v[18:21]
	v_mfma_f32_16x16x32_bf16 v[6:9], v[216:219], v[208:211], v[6:9]
	v_mfma_f32_16x16x32_bf16 v[2:5], v[224:227], v[208:211], v[2:5]
	v_mfma_f32_16x16x32_bf16 v[54:57], v[220:223], v[168:171], v[54:57]
	v_mfma_f32_16x16x32_bf16 v[50:53], v[228:231], v[168:171], v[50:53]
	v_mfma_f32_16x16x32_bf16 v[38:41], v[220:223], v[176:179], v[38:41]
	v_mfma_f32_16x16x32_bf16 v[34:37], v[228:231], v[176:179], v[34:37]
	v_mfma_f32_16x16x32_bf16 v[22:25], v[220:223], v[204:207], v[22:25]
	v_mfma_f32_16x16x32_bf16 v[18:21], v[228:231], v[204:207], v[18:21]
	v_mfma_f32_16x16x32_bf16 v[6:9], v[220:223], v[212:215], v[6:9]
	v_mfma_f32_16x16x32_bf16 v[2:5], v[228:231], v[212:215], v[2:5]
	s_setprio 0
	s_add_u32 s0, s0, 0x100
	s_addc_u32 s1, s1, 0
	s_add_u32 s49, s49, 0x100
	s_addc_u32 s65, s65, 0
	s_cmp_ge_u32 s66, s35
	s_mov_b32 s4, s66
	s_barrier
	s_cbranch_scc0 .LBB0_664
	v_mov_b32_e32 v150, v1
	v_mov_b32_e32 v151, v152
	s_cmp_lg_u32 s45, s48
	s_mov_b64 s[0:1], -1
	s_cbranch_scc0 .LBB0_667
	s_lshl_b32 s0, s45, 8
	v_lshl_add_u32 v155, v150, 4, v151
	s_add_i32 s4, s0, s40
	v_and_or_b32 v142, v155, 63, s4
	v_lshlrev_b32_e32 v165, 1, v155
	v_add_u32_e32 v164, s50, v142
	v_and_b32_e32 v142, 0xffffff80, v165
	v_add_u32_e32 v142, v164, v142
	v_ashrrev_i32_e32 v143, 31, v142
	v_readlane_b32 s0, v242, 3
	v_lshlrev_b64 v[142:143], 6, v[142:143]
	v_readlane_b32 s1, v242, 4
	v_lshl_add_u32 v155, v155, 2, s44
	s_nop 0
	v_lshl_add_u64 v[160:161], s[0:1], 0, v[142:143]
	global_load_dwordx4 v[142:145], v[160:161], off offset:48
	global_load_dwordx4 v[146:149], v[160:161], off offset:32
	global_load_dwordx4 v[156:159], v[160:161], off offset:16
	s_nop 0
	global_load_dwordx4 v[160:163], v[160:161], off
	v_add_u32_e32 v222, 0x80, v165
	v_and_b32_e32 v222, 0xffffff80, v222
	v_add_u32_e32 v222, v164, v222
	v_ashrrev_i32_e32 v223, 31, v222
	v_lshlrev_b64 v[222:223], 6, v[222:223]
	v_lshl_add_u64 v[220:221], s[0:1], 0, v[222:223]
	global_load_dwordx4 v[204:207], v[220:221], off offset:48
	global_load_dwordx4 v[208:211], v[220:221], off offset:32
	global_load_dwordx4 v[212:215], v[220:221], off offset:16
	global_load_dwordx4 v[216:219], v[220:221], off
	s_waitcnt vmcnt(4)
	v_add_f32_e32 v142, v142, v143
	v_add_f32_e32 v146, v146, v147
	v_add_f32_e32 v156, v156, v157
	v_add_f32_e32 v160, v160, v161
	v_add_f32_e32 v160, v162, v160
	v_add_f32_e32 v156, v158, v156
	v_add_f32_e32 v160, v163, v160
	v_add_f32_e32 v156, v159, v156
	v_add_f32_e32 v146, v148, v146
	v_add_f32_e32 v156, v160, v156
	v_add_f32_e32 v146, v149, v146
	v_add_f32_e32 v142, v144, v142
	v_add_f32_e32 v146, v156, v146
	v_add_f32_e32 v142, v145, v142
	v_add_f32_e32 v142, v146, v142
	v_fmamk_f32 v142, v142, 0x3a800000, v188
	v_rsq_f32_e32 v166, v142
	s_mov_b64 s[0:1], 0
	s_waitcnt vmcnt(0)
	v_add_f32_e32 v142, v204, v205
	v_add_f32_e32 v146, v208, v209
	v_add_f32_e32 v156, v212, v213
	v_add_f32_e32 v160, v216, v217
	v_add_f32_e32 v160, v218, v160
	v_add_f32_e32 v156, v214, v156
	v_add_f32_e32 v160, v219, v160
	v_add_f32_e32 v156, v215, v156
	v_add_f32_e32 v146, v210, v146
	v_add_f32_e32 v156, v160, v156
	v_add_f32_e32 v146, v211, v146
	v_add_f32_e32 v142, v206, v142
	v_add_f32_e32 v146, v156, v146
	v_add_f32_e32 v142, v207, v142
	v_add_f32_e32 v142, v146, v142
	v_fmamk_f32 v142, v142, 0x3a800000, v188
	v_rsq_f32_e32 v142, v142
	ds_write2st64_b32 v155, v166, v142 offset1:1
	s_waitcnt lgkmcnt(0)

.LBB0_742:
	s_add_i32 s70, s4, 2
	s_add_u32 s10, s0, 0x80
	s_addc_u32 s5, s1, 0
	s_add_i32 s71, 0, 0x10000
	v_add_u32_e32 v154, s71, v165
	ds_read_b128 v[142:145], v154
	ds_read_b128 v[146:149], v154 offset:1024
	ds_read_b128 v[150:153], v154 offset:2048
	ds_read_b128 v[154:157], v154 offset:3072
	s_cmp_eq_u32 s43, s4
	s_cselect_b32 s4, s22, s10
	s_cselect_b32 s5, s23, s5
	s_cselect_b32 s11, s13, s66
	s_cselect_b32 s10, s12, s65
	v_lshl_add_u64 v[162:163], s[0:1], 0, v[138:139]
	s_add_i32 m0, s29, 0xc000
	ds_read_b128 v[158:161], v166
	ds_read_b128 v[168:171], v166 offset:1024
	ds_read_b128 v[172:175], v166 offset:2048
	ds_read_b128 v[176:179], v166 offset:3072
	ds_read_b128 v[180:183], v166 offset:4096
	ds_read_b128 v[204:207], v166 offset:5120
	ds_read_b128 v[208:211], v166 offset:6144
	ds_read_b128 v[212:215], v166 offset:7168
	global_load_lds_dwordx4 v[162:163], off
	v_lshl_add_u64 v[162:163], s[0:1], 0, v[140:141]
	s_add_i32 m0, s29, 0xe000
	s_nop 0
	global_load_lds_dwordx4 v[162:163], off
	s_waitcnt lgkmcnt(8)
	s_barrier
	s_waitcnt lgkmcnt(0)
	s_setprio 1
	s_waitcnt lgkmcnt(0)
	v_mfma_f32_16x16x32_bf16 v[126:129], v[142:145], v[158:161], v[126:129]
	v_mfma_f32_16x16x32_bf16 v[122:125], v[150:153], v[158:161], v[122:125]
	v_mfma_f32_16x16x32_bf16 v[110:113], v[142:145], v[172:175], v[110:113]
	v_mfma_f32_16x16x32_bf16 v[106:109], v[150:153], v[172:175], v[106:109]
	v_mfma_f32_16x16x32_bf16 v[94:97], v[142:145], v[180:183], v[94:97]
	v_mfma_f32_16x16x32_bf16 v[90:93], v[150:153], v[180:183], v[90:93]
	v_mfma_f32_16x16x32_bf16 v[78:81], v[142:145], v[208:211], v[78:81]
	v_mfma_f32_16x16x32_bf16 v[74:77], v[150:153], v[208:211], v[74:77]
	v_mfma_f32_16x16x32_bf16 v[126:129], v[146:149], v[168:171], v[126:129]
	v_mfma_f32_16x16x32_bf16 v[122:125], v[154:157], v[168:171], v[122:125]
	v_mfma_f32_16x16x32_bf16 v[110:113], v[146:149], v[176:179], v[110:113]
	v_mfma_f32_16x16x32_bf16 v[106:109], v[154:157], v[176:179], v[106:109]
	v_mfma_f32_16x16x32_bf16 v[94:97], v[146:149], v[204:207], v[94:97]
	v_mfma_f32_16x16x32_bf16 v[90:93], v[154:157], v[204:207], v[90:93]
	v_mfma_f32_16x16x32_bf16 v[78:81], v[146:149], v[212:215], v[78:81]
	v_mfma_f32_16x16x32_bf16 v[74:77], v[154:157], v[212:215], v[74:77]
	s_setprio 0
	s_barrier
	s_add_i32 s72, 0, 0x14000
	v_add_u32_e32 v162, s72, v165
	s_add_i32 s71, s71, s28
	ds_read_b128 v[216:219], v162
	ds_read_b128 v[220:223], v162 offset:1024
	ds_read_b128 v[224:227], v162 offset:2048
	ds_read_b128 v[228:231], v162 offset:3072
	v_lshl_add_u64 v[162:163], s[10:11], 0, v[132:133]
	s_mov_b32 m0, s71
	v_lshl_add_u64 v[184:185], s[10:11], 0, v[136:137]
	global_load_lds_dwordx4 v[162:163], off
	s_add_i32 m0, s71, 0x2000
	s_nop 0
	global_load_lds_dwordx4 v[184:185], off
	s_barrier
	s_waitcnt lgkmcnt(0)
	s_setprio 1
	s_waitcnt lgkmcnt(0)
	v_mfma_f32_16x16x32_bf16 v[118:121], v[216:219], v[158:161], v[118:121]
	v_mfma_f32_16x16x32_bf16 v[114:117], v[224:227], v[158:161], v[114:117]
	v_mfma_f32_16x16x32_bf16 v[102:105], v[216:219], v[172:175], v[102:105]
	v_mfma_f32_16x16x32_bf16 v[98:101], v[224:227], v[172:175], v[98:101]
	v_mfma_f32_16x16x32_bf16 v[86:89], v[216:219], v[180:183], v[86:89]
	v_mfma_f32_16x16x32_bf16 v[82:85], v[224:227], v[180:183], v[82:85]
	v_mfma_f32_16x16x32_bf16 v[70:73], v[216:219], v[208:211], v[70:73]
	v_mfma_f32_16x16x32_bf16 v[66:69], v[224:227], v[208:211], v[66:69]
	v_mfma_f32_16x16x32_bf16 v[118:121], v[220:223], v[168:171], v[118:121]
	v_mfma_f32_16x16x32_bf16 v[114:117], v[228:231], v[168:171], v[114:117]
	v_mfma_f32_16x16x32_bf16 v[102:105], v[220:223], v[176:179], v[102:105]
	v_mfma_f32_16x16x32_bf16 v[98:101], v[228:231], v[176:179], v[98:101]
	v_mfma_f32_16x16x32_bf16 v[86:89], v[220:223], v[204:207], v[86:89]
	v_mfma_f32_16x16x32_bf16 v[82:85], v[228:231], v[204:207], v[82:85]
	v_mfma_f32_16x16x32_bf16 v[70:73], v[220:223], v[212:215], v[70:73]
	v_mfma_f32_16x16x32_bf16 v[66:69], v[228:231], v[212:215], v[66:69]
	s_setprio 0
	s_mov_b32 m0, s29
	v_lshl_add_u64 v[232:233], s[4:5], 0, v[130:131]
	s_barrier
	ds_read_b128 v[158:161], v166 offset:16384
	ds_read_b128 v[168:171], v166 offset:17408
	ds_read_b128 v[172:175], v166 offset:18432
	ds_read_b128 v[176:179], v166 offset:19456
	ds_read_b128 v[180:183], v166 offset:20480
	ds_read_b128 v[204:207], v166 offset:21504
	ds_read_b128 v[208:211], v166 offset:22528
	ds_read_b128 v[212:215], v166 offset:23552
	global_load_lds_dwordx4 v[232:233], off
	v_lshl_add_u64 v[234:235], s[4:5], 0, v[134:135]
	s_mov_b32 m0, s30
	s_nop 0
	global_load_lds_dwordx4 v[234:235], off
	s_barrier
	s_waitcnt lgkmcnt(0)
	s_setprio 1
	s_waitcnt lgkmcnt(0)
	v_mfma_f32_16x16x32_bf16 v[62:65], v[142:145], v[158:161], v[62:65]
	v_mfma_f32_16x16x32_bf16 v[58:61], v[150:153], v[158:161], v[58:61]
	v_mfma_f32_16x16x32_bf16 v[46:49], v[142:145], v[172:175], v[46:49]
	v_mfma_f32_16x16x32_bf16 v[42:45], v[150:153], v[172:175], v[42:45]
	v_mfma_f32_16x16x32_bf16 v[30:33], v[142:145], v[180:183], v[30:33]
	v_mfma_f32_16x16x32_bf16 v[26:29], v[150:153], v[180:183], v[26:29]
	v_mfma_f32_16x16x32_bf16 v[14:17], v[142:145], v[208:211], v[14:17]
	v_mfma_f32_16x16x32_bf16 v[10:13], v[150:153], v[208:211], v[10:13]
	v_mfma_f32_16x16x32_bf16 v[62:65], v[146:149], v[168:171], v[62:65]
	v_mfma_f32_16x16x32_bf16 v[58:61], v[154:157], v[168:171], v[58:61]
	v_mfma_f32_16x16x32_bf16 v[46:49], v[146:149], v[176:179], v[46:49]
	v_mfma_f32_16x16x32_bf16 v[42:45], v[154:157], v[176:179], v[42:45]
	v_mfma_f32_16x16x32_bf16 v[30:33], v[146:149], v[204:207], v[30:33]
	v_mfma_f32_16x16x32_bf16 v[26:29], v[154:157], v[204:207], v[26:29]
	v_mfma_f32_16x16x32_bf16 v[14:17], v[146:149], v[212:215], v[14:17]
	v_mfma_f32_16x16x32_bf16 v[10:13], v[154:157], v[212:215], v[10:13]
	s_setprio 0
	s_barrier
	s_add_u32 s10, s10, s2
	s_addc_u32 s11, s11, 0
	s_add_i32 s71, s72, s28
	v_lshl_add_u64 v[236:237], s[10:11], 0, v[132:133]
	s_mov_b32 m0, s71
	v_lshl_add_u64 v[238:239], s[10:11], 0, v[136:137]
	global_load_lds_dwordx4 v[236:237], off
	s_add_i32 m0, s71, 0x2000
	s_nop 0
	global_load_lds_dwordx4 v[238:239], off
	s_waitcnt vmcnt(6)
	s_barrier
	s_setprio 1
	v_mfma_f32_16x16x32_bf16 v[54:57], v[216:219], v[158:161], v[54:57]
	v_mfma_f32_16x16x32_bf16 v[50:53], v[224:227], v[158:161], v[50:53]
	v_mfma_f32_16x16x32_bf16 v[38:41], v[216:219], v[172:175], v[38:41]
	v_mfma_f32_16x16x32_bf16 v[34:37], v[224:227], v[172:175], v[34:37]
	v_mfma_f32_16x16x32_bf16 v[22:25], v[216:219], v[180:183], v[22:25]
	v_mfma_f32_16x16x32_bf16 v[18:21], v[224:227], v[180:183], v[18:21]
	v_mfma_f32_16x16x32_bf16 v[6:9], v[216:219], v[208:211], v[6:9]
	v_mfma_f32_16x16x32_bf16 v[2:5], v[224:227], v[208:211], v[2:5]
	v_mfma_f32_16x16x32_bf16 v[54:57], v[220:223], v[168:171], v[54:57]
	v_mfma_f32_16x16x32_bf16 v[50:53], v[228:231], v[168:171], v[50:53]
	v_mfma_f32_16x16x32_bf16 v[38:41], v[220:223], v[176:179], v[38:41]
	v_mfma_f32_16x16x32_bf16 v[34:37], v[228:231], v[176:179], v[34:37]
	v_mfma_f32_16x16x32_bf16 v[22:25], v[220:223], v[204:207], v[22:25]
	v_mfma_f32_16x16x32_bf16 v[18:21], v[228:231], v[204:207], v[18:21]
	v_mfma_f32_16x16x32_bf16 v[6:9], v[220:223], v[212:215], v[6:9]
	v_mfma_f32_16x16x32_bf16 v[2:5], v[228:231], v[212:215], v[2:5]
	s_setprio 0
	s_add_i32 s10, 0, 0x18000
	v_add_u32_e32 v154, s10, v165
	s_barrier
	ds_read_b128 v[142:145], v154
	ds_read_b128 v[146:149], v154 offset:1024
	ds_read_b128 v[150:153], v154 offset:2048
	ds_read_b128 v[154:157], v154 offset:3072
	s_add_u32 s4, s4, s2
	s_addc_u32 s5, s5, 0
	s_mov_b32 m0, s31
	v_lshl_add_u64 v[216:217], s[4:5], 0, v[130:131]
	ds_read_b128 v[158:161], v166 offset:32768
	ds_read_b128 v[168:171], v166 offset:33792
	ds_read_b128 v[172:175], v166 offset:34816
	ds_read_b128 v[176:179], v166 offset:35840
	ds_read_b128 v[180:183], v166 offset:36864
	ds_read_b128 v[204:207], v166 offset:37888
	ds_read_b128 v[208:211], v166 offset:38912
	ds_read_b128 v[212:215], v166 offset:39936
	global_load_lds_dwordx4 v[216:217], off
	v_lshl_add_u64 v[216:217], s[4:5], 0, v[134:135]
	s_mov_b32 m0, s34
	s_nop 0
	global_load_lds_dwordx4 v[216:217], off
	s_waitcnt lgkmcnt(8)
	s_barrier
	s_waitcnt lgkmcnt(0)
	s_setprio 1
	s_waitcnt lgkmcnt(0)
	v_mfma_f32_16x16x32_bf16 v[126:129], v[142:145], v[158:161], v[126:129]
	v_mfma_f32_16x16x32_bf16 v[122:125], v[150:153], v[158:161], v[122:125]
	v_mfma_f32_16x16x32_bf16 v[110:113], v[142:145], v[172:175], v[110:113]
	v_mfma_f32_16x16x32_bf16 v[106:109], v[150:153], v[172:175], v[106:109]
	v_mfma_f32_16x16x32_bf16 v[94:97], v[142:145], v[180:183], v[94:97]
	v_mfma_f32_16x16x32_bf16 v[90:93], v[150:153], v[180:183], v[90:93]
	v_mfma_f32_16x16x32_bf16 v[78:81], v[142:145], v[208:211], v[78:81]
	v_mfma_f32_16x16x32_bf16 v[74:77], v[150:153], v[208:211], v[74:77]
	v_mfma_f32_16x16x32_bf16 v[126:129], v[146:149], v[168:171], v[126:129]
	v_mfma_f32_16x16x32_bf16 v[122:125], v[154:157], v[168:171], v[122:125]
	v_mfma_f32_16x16x32_bf16 v[110:113], v[146:149], v[176:179], v[110:113]
	v_mfma_f32_16x16x32_bf16 v[106:109], v[154:157], v[176:179], v[106:109]
	v_mfma_f32_16x16x32_bf16 v[94:97], v[146:149], v[204:207], v[94:97]
	v_mfma_f32_16x16x32_bf16 v[90:93], v[154:157], v[204:207], v[90:93]
	v_mfma_f32_16x16x32_bf16 v[78:81], v[146:149], v[212:215], v[78:81]
	v_mfma_f32_16x16x32_bf16 v[74:77], v[154:157], v[212:215], v[74:77]
	s_setprio 0
	s_barrier
	s_add_i32 s4, 0, 0x1c000
	s_add_i32 s5, s10, s28
	v_add_u32_e32 v167, s4, v165
	v_lshl_add_u64 v[162:163], v[162:163], 0, s[6:7]
	s_mov_b32 m0, s5
	ds_read_b128 v[216:219], v167
	ds_read_b128 v[220:223], v167 offset:1024
	ds_read_b128 v[224:227], v167 offset:2048
	ds_read_b128 v[228:231], v167 offset:3072
	global_load_lds_dwordx4 v[162:163], off
	v_lshl_add_u64 v[162:163], v[184:185], 0, s[6:7]
	s_add_i32 m0, s5, 0x2000
	s_nop 0
	global_load_lds_dwordx4 v[162:163], off
	s_barrier
	s_waitcnt lgkmcnt(0)
	s_setprio 1
	s_waitcnt lgkmcnt(0)
	v_mfma_f32_16x16x32_bf16 v[118:121], v[216:219], v[158:161], v[118:121]
	v_mfma_f32_16x16x32_bf16 v[114:117], v[224:227], v[158:161], v[114:117]
	v_mfma_f32_16x16x32_bf16 v[102:105], v[216:219], v[172:175], v[102:105]
	v_mfma_f32_16x16x32_bf16 v[98:101], v[224:227], v[172:175], v[98:101]
	v_mfma_f32_16x16x32_bf16 v[86:89], v[216:219], v[180:183], v[86:89]
	v_mfma_f32_16x16x32_bf16 v[82:85], v[224:227], v[180:183], v[82:85]
	v_mfma_f32_16x16x32_bf16 v[70:73], v[216:219], v[208:211], v[70:73]
	v_mfma_f32_16x16x32_bf16 v[66:69], v[224:227], v[208:211], v[66:69]
	v_mfma_f32_16x16x32_bf16 v[118:121], v[220:223], v[168:171], v[118:121]
	v_mfma_f32_16x16x32_bf16 v[114:117], v[228:231], v[168:171], v[114:117]
	v_mfma_f32_16x16x32_bf16 v[102:105], v[220:223], v[176:179], v[102:105]
	v_mfma_f32_16x16x32_bf16 v[98:101], v[228:231], v[176:179], v[98:101]
	v_mfma_f32_16x16x32_bf16 v[86:89], v[220:223], v[204:207], v[86:89]
	v_mfma_f32_16x16x32_bf16 v[82:85], v[228:231], v[204:207], v[82:85]
	v_mfma_f32_16x16x32_bf16 v[70:73], v[220:223], v[212:215], v[70:73]
	v_mfma_f32_16x16x32_bf16 v[66:69], v[228:231], v[212:215], v[66:69]
	s_setprio 0
	s_mov_b32 m0, s41
	v_lshl_add_u64 v[162:163], v[232:233], 0, s[6:7]
	s_barrier
	ds_read_b128 v[158:161], v166 offset:49152
	ds_read_b128 v[168:171], v166 offset:50176
	ds_read_b128 v[172:175], v166 offset:51200
	ds_read_b128 v[176:179], v166 offset:52224
	ds_read_b128 v[180:183], v166 offset:53248
	ds_read_b128 v[204:207], v166 offset:54272
	ds_read_b128 v[208:211], v166 offset:55296
	ds_read_b128 v[212:215], v166 offset:56320
	global_load_lds_dwordx4 v[162:163], off
	v_lshl_add_u64 v[162:163], v[234:235], 0, s[6:7]
	s_mov_b32 m0, s42
	s_nop 0
	global_load_lds_dwordx4 v[162:163], off
	s_barrier
	s_waitcnt lgkmcnt(0)
	s_setprio 1
	s_waitcnt lgkmcnt(0)
	v_mfma_f32_16x16x32_bf16 v[62:65], v[142:145], v[158:161], v[62:65]
	v_mfma_f32_16x16x32_bf16 v[58:61], v[150:153], v[158:161], v[58:61]
	v_mfma_f32_16x16x32_bf16 v[46:49], v[142:145], v[172:175], v[46:49]
	v_mfma_f32_16x16x32_bf16 v[42:45], v[150:153], v[172:175], v[42:45]
	v_mfma_f32_16x16x32_bf16 v[30:33], v[142:145], v[180:183], v[30:33]
	v_mfma_f32_16x16x32_bf16 v[26:29], v[150:153], v[180:183], v[26:29]
	v_mfma_f32_16x16x32_bf16 v[14:17], v[142:145], v[208:211], v[14:17]
	v_mfma_f32_16x16x32_bf16 v[10:13], v[150:153], v[208:211], v[10:13]
	v_mfma_f32_16x16x32_bf16 v[62:65], v[146:149], v[168:171], v[62:65]
	v_mfma_f32_16x16x32_bf16 v[58:61], v[154:157], v[168:171], v[58:61]
	v_mfma_f32_16x16x32_bf16 v[46:49], v[146:149], v[176:179], v[46:49]
	v_mfma_f32_16x16x32_bf16 v[42:45], v[154:157], v[176:179], v[42:45]
	v_mfma_f32_16x16x32_bf16 v[30:33], v[146:149], v[204:207], v[30:33]
	v_mfma_f32_16x16x32_bf16 v[26:29], v[154:157], v[204:207], v[26:29]
	v_mfma_f32_16x16x32_bf16 v[14:17], v[146:149], v[212:215], v[14:17]
	v_mfma_f32_16x16x32_bf16 v[10:13], v[154:157], v[212:215], v[10:13]
	s_setprio 0
	s_barrier
	s_add_i32 s4, s4, s28
	v_lshl_add_u64 v[142:143], v[236:237], 0, s[6:7]
	s_mov_b32 m0, s4
	s_nop 0
	global_load_lds_dwordx4 v[142:143], off
	v_lshl_add_u64 v[142:143], v[238:239], 0, s[6:7]
	s_add_i32 m0, s4, 0x2000
	s_nop 0
	global_load_lds_dwordx4 v[142:143], off
	s_waitcnt vmcnt(6)
	s_barrier
	s_setprio 1
	v_mfma_f32_16x16x32_bf16 v[54:57], v[216:219], v[158:161], v[54:57]
	v_mfma_f32_16x16x32_bf16 v[50:53], v[224:227], v[158:161], v[50:53]
	v_mfma_f32_16x16x32_bf16 v[38:41], v[216:219], v[172:175], v[38:41]
	v_mfma_f32_16x16x32_bf16 v[34:37], v[224:227], v[172:175], v[34:37]
	v_mfma_f32_16x16x32_bf16 v[22:25], v[216:219], v[180:183], v[22:25]
	v_mfma_f32_16x16x32_bf16 v[18:21], v[224:227], v[180:183], v[18:21]
	v_mfma_f32_16x16x32_bf16 v[6:9], v[216:219], v[208:211], v[6:9]
	v_mfma_f32_16x16x32_bf16 v[2:5], v[224:227], v[208:211], v[2:5]
	v_mfma_f32_16x16x32_bf16 v[54:57], v[220:223], v[168:171], v[54:57]
	v_mfma_f32_16x16x32_bf16 v[50:53], v[228:231], v[168:171], v[50:53]
	v_mfma_f32_16x16x32_bf16 v[38:41], v[220:223], v[176:179], v[38:41]
	v_mfma_f32_16x16x32_bf16 v[34:37], v[228:231], v[176:179], v[34:37]
	v_mfma_f32_16x16x32_bf16 v[22:25], v[220:223], v[204:207], v[22:25]
	v_mfma_f32_16x16x32_bf16 v[18:21], v[228:231], v[204:207], v[18:21]
	v_mfma_f32_16x16x32_bf16 v[6:9], v[220:223], v[212:215], v[6:9]
	v_mfma_f32_16x16x32_bf16 v[2:5], v[228:231], v[212:215], v[2:5]
	s_setprio 0
	s_add_u32 s0, s0, 0x100
	s_addc_u32 s1, s1, 0
	s_add_u32 s65, s65, 0x100
	s_addc_u32 s66, s66, 0
	s_cmp_ge_u32 s70, s35
	s_mov_b32 s4, s70
	s_barrier
	s_cbranch_scc0 .LBB0_742
	v_mov_b32_e32 v152, v164
	v_mov_b32_e32 v142, v1
	s_lshl_b32 s5, s3, 8
	s_cmp_lg_u32 s3, s25
	v_lshl_add_u32 v143, v142, 4, v152
	s_mov_b64 s[0:1], -1
	s_cbranch_scc0 .LBB0_745
	s_add_i32 s4, s5, s40
	v_and_or_b32 v144, v143, 63, s4
	v_lshlrev_b32_e32 v162, 1, v143
	v_add_u32_e32 v153, s50, v144
	v_and_b32_e32 v144, 0xffffff80, v162
	v_add_u32_e32 v144, v153, v144
	v_ashrrev_i32_e32 v145, 31, v144
	v_readlane_b32 s0, v242, 3
	v_lshlrev_b64 v[144:145], 6, v[144:145]
	v_readlane_b32 s1, v242, 4
	v_lshl_add_u32 v167, v143, 2, s49
	s_nop 0
	v_lshl_add_u64 v[158:159], s[0:1], 0, v[144:145]
	global_load_dwordx4 v[144:147], v[158:159], off offset:48
	global_load_dwordx4 v[148:151], v[158:159], off offset:32
	global_load_dwordx4 v[154:157], v[158:159], off offset:16
	s_nop 0
	global_load_dwordx4 v[158:161], v[158:159], off
	v_add_u32_e32 v222, 0x80, v162
	v_and_b32_e32 v222, 0xffffff80, v222
	v_add_u32_e32 v222, v153, v222
	v_ashrrev_i32_e32 v223, 31, v222
	v_lshlrev_b64 v[222:223], 6, v[222:223]
	v_lshl_add_u64 v[220:221], s[0:1], 0, v[222:223]
	global_load_dwordx4 v[204:207], v[220:221], off offset:48
	global_load_dwordx4 v[208:211], v[220:221], off offset:32
	global_load_dwordx4 v[212:215], v[220:221], off offset:16
	global_load_dwordx4 v[216:219], v[220:221], off
	s_waitcnt vmcnt(4)
	v_add_f32_e32 v144, v144, v145
	v_add_f32_e32 v148, v148, v149
	v_add_f32_e32 v154, v154, v155
	v_add_f32_e32 v158, v158, v159
	v_add_f32_e32 v158, v160, v158
	v_add_f32_e32 v154, v156, v154
	v_add_f32_e32 v158, v161, v158
	v_add_f32_e32 v154, v157, v154
	v_add_f32_e32 v148, v150, v148
	v_add_f32_e32 v154, v158, v154
	v_add_f32_e32 v148, v151, v148
	v_add_f32_e32 v144, v146, v144
	v_add_f32_e32 v148, v154, v148
	v_add_f32_e32 v144, v147, v144
	v_add_f32_e32 v144, v148, v144
	v_fmamk_f32 v144, v144, 0x3a800000, v188
	v_rsq_f32_e32 v163, v144
	s_mov_b64 s[0:1], 0
	s_waitcnt vmcnt(0)
	v_add_f32_e32 v144, v204, v205
	v_add_f32_e32 v148, v208, v209
	v_add_f32_e32 v154, v212, v213
	v_add_f32_e32 v153, v216, v217
	v_add_f32_e32 v153, v218, v153
	v_add_f32_e32 v154, v214, v154
	v_add_f32_e32 v153, v219, v153
	v_add_f32_e32 v154, v215, v154
	v_add_f32_e32 v148, v210, v148
	v_add_f32_e32 v153, v153, v154
	v_add_f32_e32 v148, v211, v148
	v_add_f32_e32 v144, v206, v144
	v_add_f32_e32 v148, v153, v148
	v_add_f32_e32 v144, v207, v144
	v_add_f32_e32 v144, v148, v144
	v_fmamk_f32 v144, v144, 0x3a800000, v188
	v_rsq_f32_e32 v144, v144
	ds_write2st64_b32 v167, v163, v144 offset1:1
	s_waitcnt lgkmcnt(0)

.LBB0_747:
	v_lshl_add_u32 v144, v152, 2, s49
	ds_read2_b32 v[150:151], v144 offset1:16
	ds_read2_b32 v[148:149], v144 offset0:32 offset1:48
	ds_read2_b32 v[146:147], v144 offset0:64 offset1:80
	ds_read2_b32 v[144:145], v144 offset0:96 offset1:112
	v_add_u32_e32 v169, s4, v152
	s_waitcnt lgkmcnt(0)
	v_pk_mul_f32 v[158:159], v[126:127], v[150:151] op_sel_hi:[1,0]
	v_pk_mul_f32 v[154:155], v[128:129], v[150:151] op_sel_hi:[1,0]
	v_pk_mul_f32 v[156:157], v[124:125], v[150:151] op_sel_hi:[1,0]
	v_pk_mul_f32 v[160:161], v[122:123], v[150:151] op_sel_hi:[1,0]
	v_pk_mul_f32 v[124:125], v[120:121], v[150:151] op_sel_hi:[1,0]
	v_pk_mul_f32 v[128:129], v[118:119], v[150:151] op_sel_hi:[1,0]
	v_pk_mul_f32 v[126:127], v[116:117], v[150:151] op_sel_hi:[1,0]
	v_pk_mul_f32 v[152:153], v[114:115], v[150:151] op_sel_hi:[1,0]
	v_mul_f32_e32 v150, v159, v159
	v_fmac_f32_e32 v150, v158, v158
	v_fmac_f32_e32 v150, v154, v154
	v_fmac_f32_e32 v150, v155, v155
	v_fmac_f32_e32 v150, v160, v160
	v_fmac_f32_e32 v150, v161, v161
	v_fmac_f32_e32 v150, v156, v156
	v_fmac_f32_e32 v150, v157, v157
	v_fmac_f32_e32 v150, v128, v128
	v_fmac_f32_e32 v150, v129, v129
	v_fmac_f32_e32 v150, v124, v124
	v_fmac_f32_e32 v150, v125, v125
	v_fmac_f32_e32 v150, v152, v152
	s_cmp_gt_i32 s24, 2
	v_lshlrev_b32_e32 v143, 2, v143
	v_lshlrev_b32_e32 v142, 3, v142
	v_fmac_f32_e32 v150, v153, v153
	s_cselect_b64 s[0:1], -1, 0
	v_xor_b32_e32 v168, 64, v143
	v_xor_b32_e32 v167, 0x80, v143
	v_ashrrev_i32_e32 v143, 31, v142
	v_fmac_f32_e32 v150, v126, v126
	v_add_u32_e32 v122, s50, v169
	v_fmac_f32_e32 v150, v127, v127
	s_mov_b64 s[4:5], -1
	s_and_b64 vcc, exec, s[0:1]
	v_lshl_add_u64 v[118:119], v[142:143], 2, s[14:15]
	global_load_dwordx4 v[204:207], v[118:119], off
	global_load_dwordx4 v[208:211], v[118:119], off offset:16
	global_load_dwordx4 v[212:215], v[118:119], off offset:128
	global_load_dwordx4 v[216:219], v[118:119], off offset:144
	v_lshl_add_u64 v[236:237], v[142:143], 2, s[18:19]
	global_load_dwordx4 v[220:223], v[236:237], off offset:-512
	global_load_dwordx4 v[224:227], v[236:237], off offset:-496
	global_load_dwordx4 v[228:231], v[236:237], off offset:-384
	global_load_dwordx4 v[232:235], v[236:237], off offset:-368
	s_cbranch_vccz .LBB0_749
	ds_bpermute_b32 v114, v168, v150
	v_ashrrev_i32_e32 v123, 31, v122
	v_readlane_b32 s4, v243, 4
	v_readlane_b32 s5, v243, 5
	s_waitcnt lgkmcnt(0)
	v_add_f32_e32 v114, v150, v114
	ds_bpermute_b32 v115, v167, v114
	s_waitcnt lgkmcnt(0)
	v_add_f32_e32 v114, v114, v115
	v_fmamk_f32 v114, v114, 0x3c800000, v188
	v_rsq_f32_e32 v114, v114
	s_nop 0
	v_mul_f32_e32 v120, 0x3e38aa3b, v114
	s_nop 0
	s_nop 0
	v_mul_f32_e32 v121, v158, v120
	s_waitcnt vmcnt(0)
	v_mul_f32_e32 v162, v204, v121
	v_mul_f32_e32 v121, v160, v120
	v_mul_f32_e32 v163, v208, v121
	v_mul_f32_e32 v114, v159, v120
	v_mul_f32_e32 v174, v205, v114
	v_mul_f32_e32 v114, v161, v120
	v_mul_f32_e32 v175, v209, v114
	v_mul_f32_e32 v114, v154, v120
	v_mul_f32_e32 v176, v206, v114
	v_mul_f32_e32 v114, v156, v120
	v_mul_f32_e32 v177, v210, v114
	v_mul_f32_e32 v114, v155, v120
	v_mul_f32_e32 v178, v207, v114
	v_mul_f32_e32 v114, v157, v120
	v_mul_f32_e32 v179, v211, v114
	s_nop 0
	s_nop 0
	v_mul_f32_e32 v121, v128, v120
	s_nop 0
	v_mul_f32_e32 v170, v212, v121
	v_mul_f32_e32 v121, v152, v120
	v_mul_f32_e32 v180, v216, v121
	v_mul_f32_e32 v114, v129, v120
	v_mul_f32_e32 v171, v213, v114
	v_mul_f32_e32 v114, v153, v120
	v_mul_f32_e32 v181, v217, v114
	v_mul_f32_e32 v114, v124, v120
	v_mul_f32_e32 v172, v214, v114
	v_mul_f32_e32 v114, v126, v120
	v_mul_f32_e32 v182, v218, v114
	v_mul_f32_e32 v114, v125, v120
	v_mul_f32_e32 v173, v215, v114
	v_mul_f32_e32 v114, v127, v120
	v_lshlrev_b64 v[120:121], 9, v[122:123]
	v_mul_f32_e32 v183, v219, v114
	v_cvt_pk_bf16_f32 v114, v162, v174
	v_cvt_pk_bf16_f32 v116, v163, v175
	v_lshl_add_u64 v[162:163], s[20:21], 0, v[120:121]
	v_cvt_pk_bf16_f32 v115, v176, v178
	v_cvt_pk_bf16_f32 v117, v177, v179
	v_lshl_add_u64 v[162:163], v[142:143], 1, v[162:163]
	global_store_dwordx4 v[162:163], v[114:117], off
	v_lshl_add_u64 v[162:163], s[4:5], 0, v[120:121]
	s_mov_b64 s[4:5], 0
	v_cvt_pk_bf16_f32 v114, v170, v171
	v_cvt_pk_bf16_f32 v115, v172, v173
	v_cvt_pk_bf16_f32 v116, v180, v181
	v_cvt_pk_bf16_f32 v117, v182, v183
.LBB0_749:
	s_lshl_b32 s24, s24, 8
	s_ashr_i32 s25, s24, 31
	s_mov_b64 s[10:11], 0x3b6e9140
	s_andn2_b64 vcc, exec, s[4:5]
	v_lshl_add_u64 v[120:121], v[142:143], 2, s[18:19]
	s_cbranch_vccnz .LBB0_751
	ds_bpermute_b32 v114, v168, v150
	s_movk_i32 s10, 0x600
	s_lshl_b32 s92, s44, 1
	s_movk_i32 s89, 0x600
	s_waitcnt lgkmcnt(0)
	v_add_f32_e32 v114, v150, v114
	ds_bpermute_b32 v115, v167, v114
	s_waitcnt lgkmcnt(0)
	v_add_f32_e32 v114, v114, v115
	v_fmamk_f32 v114, v114, 0x3c800000, v188
	v_rsq_f32_e32 v114, v114
	s_nop 0
	v_mul_f32_e32 v123, 0x3e38aa3b, v114
	s_nop 0
	s_nop 0
	v_mul_f32_e32 v150, v158, v123
	v_mul_f32_e32 v158, v160, v123
	v_mul_f32_e32 v152, v152, v123
	v_mul_f32_e32 v128, v128, v123
	s_waitcnt vmcnt(0)
	v_mul_f32_e32 v158, v224, v158
	v_mul_f32_e32 v114, v159, v123
	v_mul_f32_e32 v159, v221, v114
	v_mul_f32_e32 v114, v161, v123
	v_mul_f32_e32 v160, v225, v114
	v_mul_f32_e32 v114, v154, v123
	v_mul_f32_e32 v161, v222, v114
	v_mul_f32_e32 v114, v156, v123
	v_mul_f32_e32 v162, v226, v114
	v_mul_f32_e32 v114, v155, v123
	v_mul_f32_e32 v163, v223, v114
	v_mul_f32_e32 v114, v157, v123
	v_mul_f32_e32 v150, v220, v150
	v_mul_f32_e32 v170, v227, v114
	s_nop 0
	s_nop 0
	s_nop 0
	v_mul_f32_e32 v152, v232, v152
	v_mul_f32_e32 v114, v129, v123
	s_nop 0
	v_mul_f32_e32 v129, v229, v114
	v_mul_f32_e32 v114, v153, v123
	v_mul_f32_e32 v153, v233, v114
	v_mul_f32_e32 v114, v124, v123
	v_mul_f32_e32 v128, v228, v128
	v_mul_f32_e32 v154, v230, v114
	v_mul_f32_e32 v114, v126, v123
	v_mul_f32_e32 v126, v234, v114
	v_mul_f32_e32 v114, v125, v123
	v_mov_b64_e32 v[124:125], s[94:95]
	v_mad_i64_i32 v[124:125], s[4:5], v122, s10, v[124:125]
	s_lshl_b64 s[4:5], s[24:25], 1
	s_nop 0
	v_lshl_add_u64 v[124:125], v[124:125], 0, s[4:5]
	v_lshl_add_u64 v[124:125], v[124:125], 0, s[92:93]
	v_mul_f32_e32 v155, v231, v114
	v_mul_f32_e32 v114, v127, v123
	v_lshl_add_u64 v[124:125], v[142:143], 1, v[124:125]
	v_mul_f32_e32 v123, v235, v114
	v_cvt_pk_bf16_f32 v114, v150, v159
	v_cvt_pk_bf16_f32 v115, v161, v163
	v_cvt_pk_bf16_f32 v116, v158, v160
	v_cvt_pk_bf16_f32 v117, v162, v170
	global_store_dwordx4 v[124:125], v[114:117], off
	v_mov_b64_e32 v[124:125], s[74:75]
	s_nop 0
	v_cvt_pk_bf16_f32 v117, v126, v123
	v_mad_i64_i32 v[122:123], s[10:11], v122, s10, v[124:125]
	v_lshl_add_u64 v[162:163], v[122:123], 0, s[4:5]
	s_mov_b64 s[10:11], 0x80a0040
	v_cvt_pk_bf16_f32 v114, v128, v129
	v_cvt_pk_bf16_f32 v115, v154, v155
	v_cvt_pk_bf16_f32 v116, v152, v153
.LBB0_751:
	s_lshl_b32 s92, s44, 1
	v_lshl_add_u64 v[122:123], v[162:163], 0, s[92:93]
	v_lshl_add_u64 v[122:123], v[122:123], 0, s[10:11]
	v_lshl_add_u64 v[122:123], v[142:143], 1, v[122:123]
	v_mov_b32_e32 v124, v151
	global_store_dwordx4 v[122:123], v[114:117], off
	v_pk_mul_f32 v[112:113], v[112:113], v[124:125] op_sel_hi:[1,0]
	v_pk_mul_f32 v[122:123], v[106:107], v[124:125] op_sel_hi:[1,0]
	v_pk_mul_f32 v[116:117], v[110:111], v[124:125] op_sel_hi:[1,0]
	v_pk_mul_f32 v[114:115], v[108:109], v[124:125] op_sel_hi:[1,0]
	v_mul_f32_e32 v126, v117, v117
	v_fmac_f32_e32 v126, v116, v116
	v_fmac_f32_e32 v126, v112, v112
	v_fmac_f32_e32 v126, v113, v113
	v_fmac_f32_e32 v126, v122, v122
	v_fmac_f32_e32 v126, v123, v123
	v_fmac_f32_e32 v126, v114, v114
	v_pk_mul_f32 v[108:109], v[102:103], v[124:125] op_sel_hi:[1,0]
	v_fmac_f32_e32 v126, v115, v115
	v_fmac_f32_e32 v126, v108, v108
	v_pk_mul_f32 v[104:105], v[104:105], v[124:125] op_sel_hi:[1,0]
	v_fmac_f32_e32 v126, v109, v109
	v_fmac_f32_e32 v126, v104, v104
	v_pk_mul_f32 v[110:111], v[98:99], v[124:125] op_sel_hi:[1,0]
	v_fmac_f32_e32 v126, v105, v105
	v_fmac_f32_e32 v126, v110, v110
	v_pk_mul_f32 v[106:107], v[100:101], v[124:125] op_sel_hi:[1,0]
	v_fmac_f32_e32 v126, v111, v111
	v_fmac_f32_e32 v126, v106, v106
	v_cndmask_b32_e64 v98, 0, 1, s[0:1]
	v_add_u32_e32 v102, s83, v169
	v_fmac_f32_e32 v126, v107, v107
	v_cmp_ne_u32_e64 s[10:11], 1, v98
	s_andn2_b64 vcc, exec, s[0:1]
	s_mov_b64 s[0:1], -1
	s_cbranch_vccnz .LBB0_753
	ds_bpermute_b32 v98, v168, v126
	v_readlane_b32 s0, v243, 4
	v_readlane_b32 s1, v243, 5
	s_waitcnt lgkmcnt(0)
	v_add_f32_e32 v98, v126, v98
	ds_bpermute_b32 v99, v167, v98
	s_waitcnt lgkmcnt(0)
	v_add_f32_e32 v98, v98, v99
	v_fmamk_f32 v98, v98, 0x3c800000, v188
	v_rsq_f32_e32 v98, v98
	s_nop 0
	v_mul_f32_e32 v103, 0x3e38aa3b, v98
	s_nop 0
	s_nop 0
	v_mul_f32_e32 v124, v116, v103
	s_nop 0
	v_mul_f32_e32 v127, v204, v124
	v_mul_f32_e32 v124, v122, v103
	v_mul_f32_e32 v128, v208, v124
	v_mul_f32_e32 v98, v117, v103
	v_mul_f32_e32 v129, v205, v98
	v_mul_f32_e32 v98, v123, v103
	v_mul_f32_e32 v154, v209, v98
	v_mul_f32_e32 v98, v112, v103
	v_mul_f32_e32 v155, v206, v98
	v_mul_f32_e32 v98, v114, v103
	v_mul_f32_e32 v156, v210, v98
	v_mul_f32_e32 v98, v113, v103
	v_mul_f32_e32 v157, v207, v98
	v_mul_f32_e32 v98, v115, v103
	v_mul_f32_e32 v158, v211, v98
	s_nop 0
	s_nop 0
	v_mul_f32_e32 v124, v108, v103
	s_nop 0
	v_mul_f32_e32 v150, v212, v124
	v_mul_f32_e32 v124, v110, v103
	v_mul_f32_e32 v159, v216, v124
	v_mul_f32_e32 v98, v109, v103
	v_mul_f32_e32 v151, v213, v98
	v_mul_f32_e32 v98, v111, v103
	v_mul_f32_e32 v160, v217, v98
	v_mul_f32_e32 v98, v104, v103
	v_mul_f32_e32 v152, v214, v98
	v_mul_f32_e32 v98, v106, v103
	v_mul_f32_e32 v161, v218, v98
	v_mul_f32_e32 v98, v105, v103
	v_mul_f32_e32 v153, v215, v98
	v_mul_f32_e32 v98, v107, v103
	v_ashrrev_i32_e32 v103, 31, v102
	v_lshlrev_b64 v[124:125], 9, v[102:103]
	v_mul_f32_e32 v162, v219, v98
	v_cvt_pk_bf16_f32 v98, v127, v129
	v_cvt_pk_bf16_f32 v100, v128, v154
	v_lshl_add_u64 v[128:129], s[20:21], 0, v[124:125]
	v_cvt_pk_bf16_f32 v99, v155, v157
	v_cvt_pk_bf16_f32 v101, v156, v158
	v_lshl_add_u64 v[128:129], v[142:143], 1, v[128:129]
	v_lshl_add_u64 v[124:125], s[0:1], 0, v[124:125]
	s_mov_b64 s[0:1], 0
	global_store_dwordx4 v[128:129], v[98:101], off
	s_nop 1
	v_cvt_pk_bf16_f32 v98, v150, v151
	v_cvt_pk_bf16_f32 v99, v152, v153
	v_cvt_pk_bf16_f32 v100, v159, v160
	v_cvt_pk_bf16_f32 v101, v161, v162
.LBB0_753:
	s_andn2_b64 vcc, exec, s[0:1]
	s_mov_b64 s[0:1], 0x3b6e9140
	s_cbranch_vccnz .LBB0_755
	ds_bpermute_b32 v98, v168, v126
	s_movk_i32 s4, 0x600
	s_movk_i32 s89, 0x600
	s_waitcnt lgkmcnt(0)
	v_add_f32_e32 v98, v126, v98
	ds_bpermute_b32 v99, v167, v98
	s_waitcnt lgkmcnt(0)
	v_add_f32_e32 v98, v98, v99
	v_fmamk_f32 v98, v98, 0x3c800000, v188
	v_rsq_f32_e32 v98, v98
	s_nop 0
	v_mul_f32_e32 v103, 0x3e38aa3b, v98
	s_nop 0
	s_nop 0
	v_mul_f32_e32 v122, v122, v103
	v_mul_f32_e32 v116, v116, v103
	v_mul_f32_e32 v110, v110, v103
	v_mul_f32_e32 v108, v108, v103
	s_nop 0
	v_mul_f32_e32 v122, v224, v122
	v_mul_f32_e32 v98, v117, v103
	v_mul_f32_e32 v117, v221, v98
	v_mul_f32_e32 v98, v123, v103
	v_mul_f32_e32 v123, v225, v98
	v_mul_f32_e32 v98, v112, v103
	v_mul_f32_e32 v116, v220, v116
	v_mul_f32_e32 v124, v222, v98
	v_mul_f32_e32 v98, v114, v103
	v_mul_f32_e32 v125, v226, v98
	v_mul_f32_e32 v98, v113, v103
	v_mul_f32_e32 v126, v223, v98
	v_mul_f32_e32 v98, v115, v103
	v_mul_f32_e32 v127, v227, v98
	s_nop 0
	s_nop 0
	s_nop 0
	v_mul_f32_e32 v110, v232, v110
	v_mul_f32_e32 v98, v109, v103
	s_nop 0
	v_mul_f32_e32 v109, v229, v98
	v_mul_f32_e32 v98, v111, v103
	v_mul_f32_e32 v111, v233, v98
	v_mul_f32_e32 v98, v104, v103
	v_mul_f32_e32 v108, v228, v108
	v_mul_f32_e32 v112, v230, v98
	v_mul_f32_e32 v98, v106, v103
	v_mul_f32_e32 v106, v234, v98
	v_mul_f32_e32 v98, v105, v103
	v_mov_b64_e32 v[104:105], s[94:95]
	v_mad_i64_i32 v[104:105], s[0:1], v102, s4, v[104:105]
	s_lshl_b64 s[0:1], s[24:25], 1
	s_nop 0
	v_lshl_add_u64 v[104:105], v[104:105], 0, s[0:1]
	v_lshl_add_u64 v[104:105], v[104:105], 0, s[92:93]
	v_mul_f32_e32 v113, v231, v98
	v_mul_f32_e32 v98, v107, v103
	v_lshl_add_u64 v[104:105], v[142:143], 1, v[104:105]
	v_mul_f32_e32 v103, v235, v98
	v_cvt_pk_bf16_f32 v98, v116, v117
	v_cvt_pk_bf16_f32 v99, v124, v126
	v_cvt_pk_bf16_f32 v100, v122, v123
	v_cvt_pk_bf16_f32 v101, v125, v127
	global_store_dwordx4 v[104:105], v[98:101], off
	v_mov_b64_e32 v[104:105], s[74:75]
	s_nop 0
	v_cvt_pk_bf16_f32 v101, v106, v103
	v_mad_i64_i32 v[102:103], s[4:5], v102, s4, v[104:105]
	v_lshl_add_u64 v[124:125], v[102:103], 0, s[0:1]
	s_mov_b64 s[0:1], 0x80a0040
	v_cvt_pk_bf16_f32 v98, v108, v109
	v_cvt_pk_bf16_f32 v99, v112, v113
	v_cvt_pk_bf16_f32 v100, v110, v111
.LBB0_755:
	v_lshl_add_u64 v[102:103], v[124:125], 0, s[92:93]
	v_lshl_add_u64 v[102:103], v[102:103], 0, s[0:1]
	v_lshl_add_u64 v[102:103], v[142:143], 1, v[102:103]
	global_store_dwordx4 v[102:103], v[98:101], off
	v_pk_mul_f32 v[96:97], v[96:97], v[148:149] op_sel_hi:[1,0]
	v_pk_mul_f32 v[102:103], v[90:91], v[148:149] op_sel_hi:[1,0]
	v_pk_mul_f32 v[100:101], v[94:95], v[148:149] op_sel_hi:[1,0]
	v_pk_mul_f32 v[98:99], v[92:93], v[148:149] op_sel_hi:[1,0]
	v_mul_f32_e32 v106, v101, v101
	v_fmac_f32_e32 v106, v100, v100
	v_fmac_f32_e32 v106, v96, v96
	v_fmac_f32_e32 v106, v97, v97
	v_fmac_f32_e32 v106, v102, v102
	v_fmac_f32_e32 v106, v103, v103
	v_fmac_f32_e32 v106, v98, v98
	v_pk_mul_f32 v[92:93], v[86:87], v[148:149] op_sel_hi:[1,0]
	v_fmac_f32_e32 v106, v99, v99
	v_fmac_f32_e32 v106, v92, v92
	v_pk_mul_f32 v[88:89], v[88:89], v[148:149] op_sel_hi:[1,0]
	v_fmac_f32_e32 v106, v93, v93
	v_fmac_f32_e32 v106, v88, v88
	v_pk_mul_f32 v[94:95], v[82:83], v[148:149] op_sel_hi:[1,0]
	v_fmac_f32_e32 v106, v89, v89
	v_fmac_f32_e32 v106, v94, v94
	v_pk_mul_f32 v[90:91], v[84:85], v[148:149] op_sel_hi:[1,0]
	v_fmac_f32_e32 v106, v95, v95
	v_fmac_f32_e32 v106, v90, v90
	v_add_u32_e32 v86, s91, v169
	v_fmac_f32_e32 v106, v91, v91
	s_and_b64 vcc, exec, s[10:11]
	s_mov_b64 s[0:1], -1
	s_cbranch_vccnz .LBB0_757
	ds_bpermute_b32 v82, v168, v106
	v_readlane_b32 s0, v243, 4
	v_readlane_b32 s1, v243, 5
	s_waitcnt lgkmcnt(0)
	v_add_f32_e32 v82, v106, v82
	ds_bpermute_b32 v83, v167, v82
	s_waitcnt lgkmcnt(0)
	v_add_f32_e32 v82, v82, v83
	v_fmamk_f32 v82, v82, 0x3c800000, v188
	v_rsq_f32_e32 v82, v82
	s_nop 0
	v_mul_f32_e32 v87, 0x3e38aa3b, v82
	s_nop 0
	s_nop 0
	v_mul_f32_e32 v104, v100, v87
	s_nop 0
	v_mul_f32_e32 v107, v204, v104
	v_mul_f32_e32 v104, v102, v87
	v_mul_f32_e32 v112, v208, v104
	v_mul_f32_e32 v82, v101, v87
	v_mul_f32_e32 v113, v205, v82
	v_mul_f32_e32 v82, v103, v87
	v_mul_f32_e32 v114, v209, v82
	v_mul_f32_e32 v82, v96, v87
	v_mul_f32_e32 v115, v206, v82
	v_mul_f32_e32 v82, v98, v87
	v_mul_f32_e32 v116, v210, v82
	v_mul_f32_e32 v82, v97, v87
	v_mul_f32_e32 v117, v207, v82
	v_mul_f32_e32 v82, v99, v87
	v_mul_f32_e32 v122, v211, v82
	s_nop 0
	s_nop 0
	v_mul_f32_e32 v104, v92, v87
	s_nop 0
	v_mul_f32_e32 v123, v212, v104
	v_mul_f32_e32 v104, v94, v87
	v_mul_f32_e32 v124, v216, v104
	v_mul_f32_e32 v82, v93, v87
	v_mul_f32_e32 v125, v213, v82
	v_mul_f32_e32 v82, v95, v87
	v_mul_f32_e32 v126, v217, v82
	v_mul_f32_e32 v82, v88, v87
	v_mul_f32_e32 v110, v214, v82
	v_mul_f32_e32 v82, v90, v87
	v_mul_f32_e32 v127, v218, v82
	v_mul_f32_e32 v82, v89, v87
	v_mul_f32_e32 v111, v215, v82
	v_mul_f32_e32 v82, v91, v87
	v_ashrrev_i32_e32 v87, 31, v86
	v_lshlrev_b64 v[104:105], 9, v[86:87]
	v_lshl_add_u64 v[108:109], s[20:21], 0, v[104:105]
	v_mul_f32_e32 v128, v219, v82
	v_cvt_pk_bf16_f32 v82, v107, v113
	v_cvt_pk_bf16_f32 v83, v115, v117
	v_cvt_pk_bf16_f32 v84, v112, v114
	v_cvt_pk_bf16_f32 v85, v116, v122
	v_lshl_add_u64 v[108:109], v[142:143], 1, v[108:109]
	v_lshl_add_u64 v[104:105], s[0:1], 0, v[104:105]
	s_mov_b64 s[0:1], 0
	global_store_dwordx4 v[108:109], v[82:85], off
	s_nop 1
	v_cvt_pk_bf16_f32 v82, v123, v125
	v_cvt_pk_bf16_f32 v83, v110, v111
	v_cvt_pk_bf16_f32 v84, v124, v126
	v_cvt_pk_bf16_f32 v85, v127, v128
.LBB0_757:
	s_andn2_b64 vcc, exec, s[0:1]
	s_mov_b64 s[0:1], 0x3b6e9140
	s_cbranch_vccnz .LBB0_759
	ds_bpermute_b32 v82, v168, v106
	s_movk_i32 s4, 0x600
	s_movk_i32 s89, 0x600
	s_waitcnt lgkmcnt(0)
	v_add_f32_e32 v82, v106, v82
	ds_bpermute_b32 v83, v167, v82
	s_waitcnt lgkmcnt(0)
	v_add_f32_e32 v82, v82, v83
	v_fmamk_f32 v82, v82, 0x3c800000, v188
	v_rsq_f32_e32 v82, v82
	s_nop 0
	v_mul_f32_e32 v87, 0x3e38aa3b, v82
	s_nop 0
	s_nop 0
	v_mul_f32_e32 v102, v102, v87
	v_mul_f32_e32 v100, v100, v87
	v_mul_f32_e32 v94, v94, v87
	v_mul_f32_e32 v92, v92, v87
	s_nop 0
	v_mul_f32_e32 v102, v224, v102
	v_mul_f32_e32 v82, v101, v87
	v_mul_f32_e32 v101, v221, v82
	v_mul_f32_e32 v82, v103, v87
	v_mul_f32_e32 v103, v225, v82
	v_mul_f32_e32 v82, v96, v87
	v_mul_f32_e32 v100, v220, v100
	v_mul_f32_e32 v104, v222, v82
	v_mul_f32_e32 v82, v98, v87
	v_mul_f32_e32 v105, v226, v82
	v_mul_f32_e32 v82, v97, v87
	v_mul_f32_e32 v106, v223, v82
	v_mul_f32_e32 v82, v99, v87
	v_mul_f32_e32 v107, v227, v82
	s_nop 0
	s_nop 0
	s_nop 0
	v_mul_f32_e32 v94, v232, v94
	v_mul_f32_e32 v82, v93, v87
	s_nop 0
	v_mul_f32_e32 v93, v229, v82
	v_mul_f32_e32 v82, v95, v87
	v_mul_f32_e32 v95, v233, v82
	v_mul_f32_e32 v82, v88, v87
	v_mul_f32_e32 v92, v228, v92
	v_mul_f32_e32 v96, v230, v82
	v_mul_f32_e32 v82, v90, v87
	v_mul_f32_e32 v90, v234, v82
	v_mul_f32_e32 v82, v89, v87
	v_mov_b64_e32 v[88:89], s[94:95]
	v_mad_i64_i32 v[88:89], s[0:1], v86, s4, v[88:89]
	s_lshl_b64 s[0:1], s[24:25], 1
	s_nop 0
	v_lshl_add_u64 v[88:89], v[88:89], 0, s[0:1]
	v_lshl_add_u64 v[88:89], v[88:89], 0, s[92:93]
	v_mul_f32_e32 v97, v231, v82
	v_mul_f32_e32 v82, v91, v87
	v_lshl_add_u64 v[88:89], v[142:143], 1, v[88:89]
	v_mul_f32_e32 v87, v235, v82
	v_cvt_pk_bf16_f32 v82, v100, v101
	v_cvt_pk_bf16_f32 v83, v104, v106
	v_cvt_pk_bf16_f32 v84, v102, v103
	v_cvt_pk_bf16_f32 v85, v105, v107
	global_store_dwordx4 v[88:89], v[82:85], off
	v_mov_b64_e32 v[88:89], s[74:75]
	s_nop 0
	v_cvt_pk_bf16_f32 v85, v90, v87
	v_mad_i64_i32 v[86:87], s[4:5], v86, s4, v[88:89]
	v_lshl_add_u64 v[104:105], v[86:87], 0, s[0:1]
	s_mov_b64 s[0:1], 0x80a0040
	v_cvt_pk_bf16_f32 v82, v92, v93
	v_cvt_pk_bf16_f32 v83, v96, v97
	v_cvt_pk_bf16_f32 v84, v94, v95
.LBB0_759:
	v_lshl_add_u64 v[86:87], v[104:105], 0, s[92:93]
	v_lshl_add_u64 v[86:87], v[86:87], 0, s[0:1]
	v_lshl_add_u64 v[86:87], v[142:143], 1, v[86:87]
	v_mov_b32_e32 v88, v149
	global_store_dwordx4 v[86:87], v[82:85], off
	v_pk_mul_f32 v[80:81], v[80:81], v[88:89] op_sel_hi:[1,0]
	v_pk_mul_f32 v[86:87], v[74:75], v[88:89] op_sel_hi:[1,0]
	v_pk_mul_f32 v[84:85], v[78:79], v[88:89] op_sel_hi:[1,0]
	v_pk_mul_f32 v[82:83], v[76:77], v[88:89] op_sel_hi:[1,0]
	v_mul_f32_e32 v90, v85, v85
	v_fmac_f32_e32 v90, v84, v84
	v_fmac_f32_e32 v90, v80, v80
	v_fmac_f32_e32 v90, v81, v81
	v_fmac_f32_e32 v90, v86, v86
	v_fmac_f32_e32 v90, v87, v87
	v_fmac_f32_e32 v90, v82, v82
	v_pk_mul_f32 v[76:77], v[70:71], v[88:89] op_sel_hi:[1,0]
	v_fmac_f32_e32 v90, v83, v83
	v_fmac_f32_e32 v90, v76, v76
	v_pk_mul_f32 v[72:73], v[72:73], v[88:89] op_sel_hi:[1,0]
	v_fmac_f32_e32 v90, v77, v77
	v_fmac_f32_e32 v90, v72, v72
	v_pk_mul_f32 v[78:79], v[66:67], v[88:89] op_sel_hi:[1,0]
	v_fmac_f32_e32 v90, v73, v73
	v_fmac_f32_e32 v90, v78, v78
	v_pk_mul_f32 v[74:75], v[68:69], v[88:89] op_sel_hi:[1,0]
	v_fmac_f32_e32 v90, v79, v79
	v_fmac_f32_e32 v90, v74, v74
	v_add_u32_e32 v70, s51, v169
	v_fmac_f32_e32 v90, v75, v75
	s_and_b64 vcc, exec, s[10:11]
	s_mov_b64 s[0:1], -1
	s_cbranch_vccnz .LBB0_761
	ds_bpermute_b32 v66, v168, v90
	v_readlane_b32 s0, v243, 4
	v_readlane_b32 s1, v243, 5
	s_waitcnt lgkmcnt(0)
	v_add_f32_e32 v66, v90, v66
	ds_bpermute_b32 v67, v167, v66
	s_waitcnt lgkmcnt(0)
	v_add_f32_e32 v66, v66, v67
	v_fmamk_f32 v66, v66, 0x3c800000, v188
	v_rsq_f32_e32 v66, v66
	s_nop 0
	v_mul_f32_e32 v71, 0x3e38aa3b, v66
	s_nop 0
	s_nop 0
	v_mul_f32_e32 v88, v84, v71
	s_nop 0
	v_mul_f32_e32 v91, v204, v88
	v_mul_f32_e32 v88, v86, v71
	v_mul_f32_e32 v96, v208, v88
	v_mul_f32_e32 v66, v85, v71
	v_mul_f32_e32 v97, v205, v66
	v_mul_f32_e32 v66, v87, v71
	v_mul_f32_e32 v98, v209, v66
	v_mul_f32_e32 v66, v80, v71
	v_mul_f32_e32 v99, v206, v66
	v_mul_f32_e32 v66, v82, v71
	v_mul_f32_e32 v100, v210, v66
	v_mul_f32_e32 v66, v81, v71
	v_mul_f32_e32 v101, v207, v66
	v_mul_f32_e32 v66, v83, v71
	v_mul_f32_e32 v102, v211, v66
	s_nop 0
	s_nop 0
	v_mul_f32_e32 v88, v76, v71
	s_nop 0
	v_mul_f32_e32 v103, v212, v88
	v_mul_f32_e32 v88, v78, v71
	v_mul_f32_e32 v104, v216, v88
	v_mul_f32_e32 v66, v77, v71
	v_mul_f32_e32 v105, v213, v66
	v_mul_f32_e32 v66, v79, v71
	v_mul_f32_e32 v106, v217, v66
	v_mul_f32_e32 v66, v72, v71
	v_mul_f32_e32 v94, v214, v66
	v_mul_f32_e32 v66, v74, v71
	v_mul_f32_e32 v107, v218, v66
	v_mul_f32_e32 v66, v73, v71
	v_mul_f32_e32 v95, v215, v66
	v_mul_f32_e32 v66, v75, v71
	v_ashrrev_i32_e32 v71, 31, v70
	v_lshlrev_b64 v[88:89], 9, v[70:71]
	v_lshl_add_u64 v[92:93], s[20:21], 0, v[88:89]
	v_mul_f32_e32 v108, v219, v66
	v_cvt_pk_bf16_f32 v66, v91, v97
	v_cvt_pk_bf16_f32 v67, v99, v101
	v_cvt_pk_bf16_f32 v68, v96, v98
	v_cvt_pk_bf16_f32 v69, v100, v102
	v_lshl_add_u64 v[92:93], v[142:143], 1, v[92:93]
	v_lshl_add_u64 v[88:89], s[0:1], 0, v[88:89]
	s_mov_b64 s[0:1], 0
	global_store_dwordx4 v[92:93], v[66:69], off
	s_nop 1
	v_cvt_pk_bf16_f32 v66, v103, v105
	v_cvt_pk_bf16_f32 v67, v94, v95
	v_cvt_pk_bf16_f32 v68, v104, v106
	v_cvt_pk_bf16_f32 v69, v107, v108
.LBB0_761:
	s_andn2_b64 vcc, exec, s[0:1]
	s_mov_b64 s[0:1], 0x3b6e9140
	s_cbranch_vccnz .LBB0_763
	ds_bpermute_b32 v66, v168, v90
	s_movk_i32 s4, 0x600
	s_movk_i32 s89, 0x600
	s_waitcnt lgkmcnt(0)
	v_add_f32_e32 v66, v90, v66
	ds_bpermute_b32 v67, v167, v66
	s_waitcnt lgkmcnt(0)
	v_add_f32_e32 v66, v66, v67
	v_fmamk_f32 v66, v66, 0x3c800000, v188
	v_rsq_f32_e32 v66, v66
	s_nop 0
	v_mul_f32_e32 v71, 0x3e38aa3b, v66
	s_nop 0
	s_nop 0
	v_mul_f32_e32 v86, v86, v71
	v_mul_f32_e32 v84, v84, v71
	v_mul_f32_e32 v78, v78, v71
	v_mul_f32_e32 v76, v76, v71
	s_nop 0
	v_mul_f32_e32 v86, v224, v86
	v_mul_f32_e32 v66, v85, v71
	v_mul_f32_e32 v85, v221, v66
	v_mul_f32_e32 v66, v87, v71
	v_mul_f32_e32 v87, v225, v66
	v_mul_f32_e32 v66, v80, v71
	v_mul_f32_e32 v84, v220, v84
	v_mul_f32_e32 v88, v222, v66
	v_mul_f32_e32 v66, v82, v71
	v_mul_f32_e32 v89, v226, v66
	v_mul_f32_e32 v66, v81, v71
	v_mul_f32_e32 v90, v223, v66
	v_mul_f32_e32 v66, v83, v71
	v_mul_f32_e32 v91, v227, v66
	s_nop 0
	s_nop 0
	s_nop 0
	v_mul_f32_e32 v78, v232, v78
	v_mul_f32_e32 v66, v77, v71
	s_nop 0
	v_mul_f32_e32 v77, v229, v66
	v_mul_f32_e32 v66, v79, v71
	v_mul_f32_e32 v79, v233, v66
	v_mul_f32_e32 v66, v72, v71
	v_mul_f32_e32 v76, v228, v76
	v_mul_f32_e32 v80, v230, v66
	v_mul_f32_e32 v66, v74, v71
	v_mul_f32_e32 v74, v234, v66
	v_mul_f32_e32 v66, v73, v71
	v_mov_b64_e32 v[72:73], s[94:95]
	v_mad_i64_i32 v[72:73], s[0:1], v70, s4, v[72:73]
	s_lshl_b64 s[0:1], s[24:25], 1
	s_nop 0
	v_lshl_add_u64 v[72:73], v[72:73], 0, s[0:1]
	v_lshl_add_u64 v[72:73], v[72:73], 0, s[92:93]
	v_mul_f32_e32 v81, v231, v66
	v_mul_f32_e32 v66, v75, v71
	v_lshl_add_u64 v[72:73], v[142:143], 1, v[72:73]
	v_mul_f32_e32 v71, v235, v66
	v_cvt_pk_bf16_f32 v66, v84, v85
	v_cvt_pk_bf16_f32 v67, v88, v90
	v_cvt_pk_bf16_f32 v68, v86, v87
	v_cvt_pk_bf16_f32 v69, v89, v91
	global_store_dwordx4 v[72:73], v[66:69], off
	v_mov_b64_e32 v[72:73], s[74:75]
	s_nop 0
	v_cvt_pk_bf16_f32 v69, v74, v71
	v_mad_i64_i32 v[70:71], s[4:5], v70, s4, v[72:73]
	v_lshl_add_u64 v[88:89], v[70:71], 0, s[0:1]
	s_mov_b64 s[0:1], 0x80a0040
	v_cvt_pk_bf16_f32 v66, v76, v77
	v_cvt_pk_bf16_f32 v67, v80, v81
	v_cvt_pk_bf16_f32 v68, v78, v79
.LBB0_763:
	v_lshl_add_u64 v[70:71], v[88:89], 0, s[92:93]
	v_lshl_add_u64 v[70:71], v[70:71], 0, s[0:1]
	v_lshl_add_u64 v[70:71], v[142:143], 1, v[70:71]
	global_store_dwordx4 v[70:71], v[66:69], off
	v_pk_mul_f32 v[64:65], v[64:65], v[146:147] op_sel_hi:[1,0]
	v_pk_mul_f32 v[70:71], v[58:59], v[146:147] op_sel_hi:[1,0]
	v_pk_mul_f32 v[68:69], v[62:63], v[146:147] op_sel_hi:[1,0]
	v_pk_mul_f32 v[66:67], v[60:61], v[146:147] op_sel_hi:[1,0]
	v_mul_f32_e32 v74, v69, v69
	v_fmac_f32_e32 v74, v68, v68
	v_fmac_f32_e32 v74, v64, v64
	v_fmac_f32_e32 v74, v65, v65
	v_fmac_f32_e32 v74, v70, v70
	v_fmac_f32_e32 v74, v71, v71
	v_fmac_f32_e32 v74, v66, v66
	v_pk_mul_f32 v[60:61], v[54:55], v[146:147] op_sel_hi:[1,0]
	v_fmac_f32_e32 v74, v67, v67
	v_fmac_f32_e32 v74, v60, v60
	v_pk_mul_f32 v[56:57], v[56:57], v[146:147] op_sel_hi:[1,0]
	v_fmac_f32_e32 v74, v61, v61
	v_fmac_f32_e32 v74, v56, v56
	v_pk_mul_f32 v[62:63], v[50:51], v[146:147] op_sel_hi:[1,0]
	v_fmac_f32_e32 v74, v57, v57
	v_fmac_f32_e32 v74, v62, v62
	v_pk_mul_f32 v[58:59], v[52:53], v[146:147] op_sel_hi:[1,0]
	v_fmac_f32_e32 v74, v63, v63
	v_fmac_f32_e32 v74, v58, v58
	v_add_u32_e32 v54, s88, v169
	v_fmac_f32_e32 v74, v59, v59
	s_and_b64 vcc, exec, s[10:11]
	s_mov_b64 s[0:1], -1
	s_cbranch_vccnz .LBB0_765
	ds_bpermute_b32 v50, v168, v74
	v_readlane_b32 s0, v243, 4
	v_readlane_b32 s1, v243, 5
	s_waitcnt lgkmcnt(0)
	v_add_f32_e32 v50, v74, v50
	ds_bpermute_b32 v51, v167, v50
	s_waitcnt lgkmcnt(0)
	v_add_f32_e32 v50, v50, v51
	v_fmamk_f32 v50, v50, 0x3c800000, v188
	v_rsq_f32_e32 v50, v50
	s_nop 0
	v_mul_f32_e32 v55, 0x3e38aa3b, v50
	s_nop 0
	s_nop 0
	v_mul_f32_e32 v72, v68, v55
	s_nop 0
	v_mul_f32_e32 v75, v204, v72
	v_mul_f32_e32 v72, v70, v55
	v_mul_f32_e32 v80, v208, v72
	v_mul_f32_e32 v50, v69, v55
	v_mul_f32_e32 v81, v205, v50
	v_mul_f32_e32 v50, v71, v55
	v_mul_f32_e32 v82, v209, v50
	v_mul_f32_e32 v50, v64, v55
	v_mul_f32_e32 v83, v206, v50
	v_mul_f32_e32 v50, v66, v55
	v_mul_f32_e32 v84, v210, v50
	v_mul_f32_e32 v50, v65, v55
	v_mul_f32_e32 v85, v207, v50
	v_mul_f32_e32 v50, v67, v55
	v_mul_f32_e32 v86, v211, v50
	s_nop 0
	s_nop 0
	v_mul_f32_e32 v72, v60, v55
	s_nop 0
	v_mul_f32_e32 v87, v212, v72
	v_mul_f32_e32 v72, v62, v55
	v_mul_f32_e32 v88, v216, v72
	v_mul_f32_e32 v50, v61, v55
	v_mul_f32_e32 v89, v213, v50
	v_mul_f32_e32 v50, v63, v55
	v_mul_f32_e32 v90, v217, v50
	v_mul_f32_e32 v50, v56, v55
	v_mul_f32_e32 v78, v214, v50
	v_mul_f32_e32 v50, v58, v55
	v_mul_f32_e32 v91, v218, v50
	v_mul_f32_e32 v50, v57, v55
	v_mul_f32_e32 v79, v215, v50
	v_mul_f32_e32 v50, v59, v55
	v_ashrrev_i32_e32 v55, 31, v54
	v_lshlrev_b64 v[72:73], 9, v[54:55]
	v_lshl_add_u64 v[76:77], s[20:21], 0, v[72:73]
	v_mul_f32_e32 v92, v219, v50
	v_cvt_pk_bf16_f32 v50, v75, v81
	v_cvt_pk_bf16_f32 v51, v83, v85
	v_cvt_pk_bf16_f32 v52, v80, v82
	v_cvt_pk_bf16_f32 v53, v84, v86
	v_lshl_add_u64 v[76:77], v[142:143], 1, v[76:77]
	v_lshl_add_u64 v[72:73], s[0:1], 0, v[72:73]
	s_mov_b64 s[0:1], 0
	global_store_dwordx4 v[76:77], v[50:53], off
	s_nop 1
	v_cvt_pk_bf16_f32 v50, v87, v89
	v_cvt_pk_bf16_f32 v51, v78, v79
	v_cvt_pk_bf16_f32 v52, v88, v90
	v_cvt_pk_bf16_f32 v53, v91, v92
.LBB0_765:
	s_andn2_b64 vcc, exec, s[0:1]
	s_mov_b64 s[0:1], 0x3b6e9140
	s_cbranch_vccnz .LBB0_767
	ds_bpermute_b32 v50, v168, v74
	s_movk_i32 s4, 0x600
	s_movk_i32 s89, 0x600
	s_waitcnt lgkmcnt(0)
	v_add_f32_e32 v50, v74, v50
	ds_bpermute_b32 v51, v167, v50
	s_waitcnt lgkmcnt(0)
	v_add_f32_e32 v50, v50, v51
	v_fmamk_f32 v50, v50, 0x3c800000, v188
	v_rsq_f32_e32 v50, v50
	s_nop 0
	v_mul_f32_e32 v55, 0x3e38aa3b, v50
	s_nop 0
	s_nop 0
	v_mul_f32_e32 v70, v70, v55
	v_mul_f32_e32 v68, v68, v55
	v_mul_f32_e32 v62, v62, v55
	v_mul_f32_e32 v60, v60, v55
	s_nop 0
	v_mul_f32_e32 v70, v224, v70
	v_mul_f32_e32 v50, v69, v55
	v_mul_f32_e32 v69, v221, v50
	v_mul_f32_e32 v50, v71, v55
	v_mul_f32_e32 v71, v225, v50
	v_mul_f32_e32 v50, v64, v55
	v_mul_f32_e32 v68, v220, v68
	v_mul_f32_e32 v72, v222, v50
	v_mul_f32_e32 v50, v66, v55
	v_mul_f32_e32 v73, v226, v50
	v_mul_f32_e32 v50, v65, v55
	v_mul_f32_e32 v74, v223, v50
	v_mul_f32_e32 v50, v67, v55
	v_mul_f32_e32 v75, v227, v50
	s_nop 0
	s_nop 0
	s_nop 0
	v_mul_f32_e32 v62, v232, v62
	v_mul_f32_e32 v50, v61, v55
	s_nop 0
	v_mul_f32_e32 v61, v229, v50
	v_mul_f32_e32 v50, v63, v55
	v_mul_f32_e32 v63, v233, v50
	v_mul_f32_e32 v50, v56, v55
	v_mul_f32_e32 v60, v228, v60
	v_mul_f32_e32 v64, v230, v50
	v_mul_f32_e32 v50, v58, v55
	v_mul_f32_e32 v58, v234, v50
	v_mul_f32_e32 v50, v57, v55
	v_mov_b64_e32 v[56:57], s[94:95]
	v_mad_i64_i32 v[56:57], s[0:1], v54, s4, v[56:57]
	s_lshl_b64 s[0:1], s[24:25], 1
	s_nop 0
	v_lshl_add_u64 v[56:57], v[56:57], 0, s[0:1]
	v_lshl_add_u64 v[56:57], v[56:57], 0, s[92:93]
	v_mul_f32_e32 v65, v231, v50
	v_mul_f32_e32 v50, v59, v55
	v_lshl_add_u64 v[56:57], v[142:143], 1, v[56:57]
	v_mul_f32_e32 v55, v235, v50
	v_cvt_pk_bf16_f32 v50, v68, v69
	v_cvt_pk_bf16_f32 v51, v72, v74
	v_cvt_pk_bf16_f32 v52, v70, v71
	v_cvt_pk_bf16_f32 v53, v73, v75
	global_store_dwordx4 v[56:57], v[50:53], off
	v_mov_b64_e32 v[56:57], s[74:75]
	s_nop 0
	v_cvt_pk_bf16_f32 v53, v58, v55
	v_mad_i64_i32 v[54:55], s[4:5], v54, s4, v[56:57]
	v_lshl_add_u64 v[72:73], v[54:55], 0, s[0:1]
	s_mov_b64 s[0:1], 0x80a0040
	v_cvt_pk_bf16_f32 v50, v60, v61
	v_cvt_pk_bf16_f32 v51, v64, v65
	v_cvt_pk_bf16_f32 v52, v62, v63
.LBB0_767:
	v_lshl_add_u64 v[54:55], v[72:73], 0, s[92:93]
	v_lshl_add_u64 v[54:55], v[54:55], 0, s[0:1]
	v_lshl_add_u64 v[54:55], v[142:143], 1, v[54:55]
	v_mov_b32_e32 v56, v147
	global_store_dwordx4 v[54:55], v[50:53], off
	v_pk_mul_f32 v[48:49], v[48:49], v[56:57] op_sel_hi:[1,0]
	v_pk_mul_f32 v[54:55], v[42:43], v[56:57] op_sel_hi:[1,0]
	v_pk_mul_f32 v[52:53], v[46:47], v[56:57] op_sel_hi:[1,0]
	v_pk_mul_f32 v[50:51], v[44:45], v[56:57] op_sel_hi:[1,0]
	v_mul_f32_e32 v58, v53, v53
	v_fmac_f32_e32 v58, v52, v52
	v_fmac_f32_e32 v58, v48, v48
	v_fmac_f32_e32 v58, v49, v49
	v_fmac_f32_e32 v58, v54, v54
	v_fmac_f32_e32 v58, v55, v55
	v_fmac_f32_e32 v58, v50, v50
	v_pk_mul_f32 v[44:45], v[38:39], v[56:57] op_sel_hi:[1,0]
	v_fmac_f32_e32 v58, v51, v51
	v_fmac_f32_e32 v58, v44, v44
	v_pk_mul_f32 v[40:41], v[40:41], v[56:57] op_sel_hi:[1,0]
	v_fmac_f32_e32 v58, v45, v45
	v_fmac_f32_e32 v58, v40, v40
	v_pk_mul_f32 v[46:47], v[34:35], v[56:57] op_sel_hi:[1,0]
	v_fmac_f32_e32 v58, v41, v41
	v_fmac_f32_e32 v58, v46, v46
	v_pk_mul_f32 v[42:43], v[36:37], v[56:57] op_sel_hi:[1,0]
	v_fmac_f32_e32 v58, v47, v47
	v_fmac_f32_e32 v58, v42, v42
	v_add_u32_e32 v38, s60, v169
	v_fmac_f32_e32 v58, v43, v43
	s_and_b64 vcc, exec, s[10:11]
	s_mov_b64 s[0:1], -1
	s_cbranch_vccnz .LBB0_769
	ds_bpermute_b32 v34, v168, v58
	v_readlane_b32 s0, v243, 4
	v_readlane_b32 s1, v243, 5
	s_waitcnt lgkmcnt(0)
	v_add_f32_e32 v34, v58, v34
	ds_bpermute_b32 v35, v167, v34
	s_waitcnt lgkmcnt(0)
	v_add_f32_e32 v34, v34, v35
	v_fmamk_f32 v34, v34, 0x3c800000, v188
	v_rsq_f32_e32 v34, v34
	s_nop 0
	v_mul_f32_e32 v39, 0x3e38aa3b, v34
	s_nop 0
	s_nop 0
	v_mul_f32_e32 v56, v52, v39
	s_nop 0
	v_mul_f32_e32 v59, v204, v56
	v_mul_f32_e32 v56, v54, v39
	v_mul_f32_e32 v64, v208, v56
	v_mul_f32_e32 v34, v53, v39
	v_mul_f32_e32 v65, v205, v34
	v_mul_f32_e32 v34, v55, v39
	v_mul_f32_e32 v66, v209, v34
	v_mul_f32_e32 v34, v48, v39
	v_mul_f32_e32 v67, v206, v34
	v_mul_f32_e32 v34, v50, v39
	v_mul_f32_e32 v68, v210, v34
	v_mul_f32_e32 v34, v49, v39
	v_mul_f32_e32 v69, v207, v34
	v_mul_f32_e32 v34, v51, v39
	v_mul_f32_e32 v70, v211, v34
	s_nop 0
	s_nop 0
	v_mul_f32_e32 v56, v44, v39
	s_nop 0
	v_mul_f32_e32 v71, v212, v56
	v_mul_f32_e32 v56, v46, v39
	v_mul_f32_e32 v72, v216, v56
	v_mul_f32_e32 v34, v45, v39
	v_mul_f32_e32 v73, v213, v34
	v_mul_f32_e32 v34, v47, v39
	v_mul_f32_e32 v74, v217, v34
	v_mul_f32_e32 v34, v40, v39
	v_mul_f32_e32 v62, v214, v34
	v_mul_f32_e32 v34, v42, v39
	v_mul_f32_e32 v75, v218, v34
	v_mul_f32_e32 v34, v41, v39
	v_mul_f32_e32 v63, v215, v34
	v_mul_f32_e32 v34, v43, v39
	v_ashrrev_i32_e32 v39, 31, v38
	v_lshlrev_b64 v[56:57], 9, v[38:39]
	v_lshl_add_u64 v[60:61], s[20:21], 0, v[56:57]
	v_mul_f32_e32 v76, v219, v34
	v_cvt_pk_bf16_f32 v34, v59, v65
	v_cvt_pk_bf16_f32 v35, v67, v69
	v_cvt_pk_bf16_f32 v36, v64, v66
	v_cvt_pk_bf16_f32 v37, v68, v70
	v_lshl_add_u64 v[60:61], v[142:143], 1, v[60:61]
	v_lshl_add_u64 v[56:57], s[0:1], 0, v[56:57]
	s_mov_b64 s[0:1], 0
	global_store_dwordx4 v[60:61], v[34:37], off
	s_nop 1
	v_cvt_pk_bf16_f32 v34, v71, v73
	v_cvt_pk_bf16_f32 v35, v62, v63
	v_cvt_pk_bf16_f32 v36, v72, v74
	v_cvt_pk_bf16_f32 v37, v75, v76
.LBB0_769:
	s_andn2_b64 vcc, exec, s[0:1]
	s_mov_b64 s[0:1], 0x3b6e9140
	s_cbranch_vccnz .LBB0_771
	ds_bpermute_b32 v34, v168, v58
	s_movk_i32 s4, 0x600
	s_movk_i32 s89, 0x600
	s_waitcnt lgkmcnt(0)
	v_add_f32_e32 v34, v58, v34
	ds_bpermute_b32 v35, v167, v34
	s_waitcnt lgkmcnt(0)
	v_add_f32_e32 v34, v34, v35
	v_fmamk_f32 v34, v34, 0x3c800000, v188
	v_rsq_f32_e32 v34, v34
	s_nop 0
	v_mul_f32_e32 v39, 0x3e38aa3b, v34
	s_nop 0
	s_nop 0
	v_mul_f32_e32 v54, v54, v39
	v_mul_f32_e32 v52, v52, v39
	v_mul_f32_e32 v46, v46, v39
	v_mul_f32_e32 v44, v44, v39
	s_nop 0
	v_mul_f32_e32 v54, v224, v54
	v_mul_f32_e32 v34, v53, v39
	v_mul_f32_e32 v53, v221, v34
	v_mul_f32_e32 v34, v55, v39
	v_mul_f32_e32 v55, v225, v34
	v_mul_f32_e32 v34, v48, v39
	v_mul_f32_e32 v52, v220, v52
	v_mul_f32_e32 v56, v222, v34
	v_mul_f32_e32 v34, v50, v39
	v_mul_f32_e32 v57, v226, v34
	v_mul_f32_e32 v34, v49, v39
	v_mul_f32_e32 v58, v223, v34
	v_mul_f32_e32 v34, v51, v39
	v_mul_f32_e32 v59, v227, v34
	s_nop 0
	s_nop 0
	s_nop 0
	v_mul_f32_e32 v46, v232, v46
	v_mul_f32_e32 v34, v45, v39
	s_nop 0
	v_mul_f32_e32 v45, v229, v34
	v_mul_f32_e32 v34, v47, v39
	v_mul_f32_e32 v47, v233, v34
	v_mul_f32_e32 v34, v40, v39
	v_mul_f32_e32 v44, v228, v44
	v_mul_f32_e32 v48, v230, v34
	v_mul_f32_e32 v34, v42, v39
	v_mul_f32_e32 v42, v234, v34
	v_mul_f32_e32 v34, v41, v39
	v_mov_b64_e32 v[40:41], s[94:95]
	v_mad_i64_i32 v[40:41], s[0:1], v38, s4, v[40:41]
	s_lshl_b64 s[0:1], s[24:25], 1
	s_nop 0
	v_lshl_add_u64 v[40:41], v[40:41], 0, s[0:1]
	v_lshl_add_u64 v[40:41], v[40:41], 0, s[92:93]
	v_mul_f32_e32 v49, v231, v34
	v_mul_f32_e32 v34, v43, v39
	v_lshl_add_u64 v[40:41], v[142:143], 1, v[40:41]
	v_mul_f32_e32 v39, v235, v34
	v_cvt_pk_bf16_f32 v34, v52, v53
	v_cvt_pk_bf16_f32 v35, v56, v58
	v_cvt_pk_bf16_f32 v36, v54, v55
	v_cvt_pk_bf16_f32 v37, v57, v59
	global_store_dwordx4 v[40:41], v[34:37], off
	v_mov_b64_e32 v[40:41], s[74:75]
	s_nop 0
	v_cvt_pk_bf16_f32 v37, v42, v39
	v_mad_i64_i32 v[38:39], s[4:5], v38, s4, v[40:41]
	v_lshl_add_u64 v[56:57], v[38:39], 0, s[0:1]
	s_mov_b64 s[0:1], 0x80a0040
	v_cvt_pk_bf16_f32 v34, v44, v45
	v_cvt_pk_bf16_f32 v35, v48, v49
	v_cvt_pk_bf16_f32 v36, v46, v47
.LBB0_771:
	v_lshl_add_u64 v[38:39], v[56:57], 0, s[92:93]
	v_lshl_add_u64 v[38:39], v[38:39], 0, s[0:1]
	v_lshl_add_u64 v[38:39], v[142:143], 1, v[38:39]
	global_store_dwordx4 v[38:39], v[34:37], off
	v_pk_mul_f32 v[32:33], v[32:33], v[144:145] op_sel_hi:[1,0]
	v_pk_mul_f32 v[38:39], v[26:27], v[144:145] op_sel_hi:[1,0]
	v_pk_mul_f32 v[36:37], v[30:31], v[144:145] op_sel_hi:[1,0]
	v_pk_mul_f32 v[34:35], v[28:29], v[144:145] op_sel_hi:[1,0]
	v_mul_f32_e32 v42, v37, v37
	v_fmac_f32_e32 v42, v36, v36
	v_fmac_f32_e32 v42, v32, v32
	v_fmac_f32_e32 v42, v33, v33
	v_fmac_f32_e32 v42, v38, v38
	v_fmac_f32_e32 v42, v39, v39
	v_fmac_f32_e32 v42, v34, v34
	v_pk_mul_f32 v[28:29], v[22:23], v[144:145] op_sel_hi:[1,0]
	v_fmac_f32_e32 v42, v35, v35
	v_fmac_f32_e32 v42, v28, v28
	v_pk_mul_f32 v[24:25], v[24:25], v[144:145] op_sel_hi:[1,0]
	v_fmac_f32_e32 v42, v29, v29
	v_fmac_f32_e32 v42, v24, v24
	v_pk_mul_f32 v[30:31], v[18:19], v[144:145] op_sel_hi:[1,0]
	v_fmac_f32_e32 v42, v25, v25
	v_fmac_f32_e32 v42, v30, v30
	v_pk_mul_f32 v[26:27], v[20:21], v[144:145] op_sel_hi:[1,0]
	v_fmac_f32_e32 v42, v31, v31
	v_fmac_f32_e32 v42, v26, v26
	v_add_u32_e32 v22, s61, v169
	v_fmac_f32_e32 v42, v27, v27
	s_and_b64 vcc, exec, s[10:11]
	s_mov_b64 s[0:1], -1
	s_cbranch_vccnz .LBB0_773
	ds_bpermute_b32 v18, v168, v42
	v_readlane_b32 s0, v243, 4
	v_readlane_b32 s1, v243, 5
	s_waitcnt lgkmcnt(0)
	v_add_f32_e32 v18, v42, v18
	ds_bpermute_b32 v19, v167, v18
	s_waitcnt lgkmcnt(0)
	v_add_f32_e32 v18, v18, v19
	v_fmamk_f32 v18, v18, 0x3c800000, v188
	v_rsq_f32_e32 v18, v18
	s_nop 0
	v_mul_f32_e32 v23, 0x3e38aa3b, v18
	s_nop 0
	s_nop 0
	v_mul_f32_e32 v40, v36, v23
	s_nop 0
	v_mul_f32_e32 v43, v204, v40
	v_mul_f32_e32 v40, v38, v23
	v_mul_f32_e32 v48, v208, v40
	v_mul_f32_e32 v18, v37, v23
	v_mul_f32_e32 v49, v205, v18
	v_mul_f32_e32 v18, v39, v23
	v_mul_f32_e32 v50, v209, v18
	v_mul_f32_e32 v18, v32, v23
	v_mul_f32_e32 v51, v206, v18
	v_mul_f32_e32 v18, v34, v23
	v_mul_f32_e32 v52, v210, v18
	v_mul_f32_e32 v18, v33, v23
	v_mul_f32_e32 v53, v207, v18
	v_mul_f32_e32 v18, v35, v23
	v_mul_f32_e32 v54, v211, v18
	s_nop 0
	s_nop 0
	v_mul_f32_e32 v40, v28, v23
	s_nop 0
	v_mul_f32_e32 v55, v212, v40
	v_mul_f32_e32 v40, v30, v23
	v_mul_f32_e32 v56, v216, v40
	v_mul_f32_e32 v18, v29, v23
	v_mul_f32_e32 v57, v213, v18
	v_mul_f32_e32 v18, v31, v23
	v_mul_f32_e32 v58, v217, v18
	v_mul_f32_e32 v18, v24, v23
	v_mul_f32_e32 v46, v214, v18
	v_mul_f32_e32 v18, v26, v23
	v_mul_f32_e32 v59, v218, v18
	v_mul_f32_e32 v18, v25, v23
	v_mul_f32_e32 v47, v215, v18
	v_mul_f32_e32 v18, v27, v23
	v_ashrrev_i32_e32 v23, 31, v22
	v_lshlrev_b64 v[40:41], 9, v[22:23]
	v_lshl_add_u64 v[44:45], s[20:21], 0, v[40:41]
	v_mul_f32_e32 v60, v219, v18
	v_cvt_pk_bf16_f32 v18, v43, v49
	v_cvt_pk_bf16_f32 v19, v51, v53
	v_cvt_pk_bf16_f32 v20, v48, v50
	v_cvt_pk_bf16_f32 v21, v52, v54
	v_lshl_add_u64 v[44:45], v[142:143], 1, v[44:45]
	v_lshl_add_u64 v[40:41], s[0:1], 0, v[40:41]
	s_mov_b64 s[0:1], 0
	global_store_dwordx4 v[44:45], v[18:21], off
	s_nop 1
	v_cvt_pk_bf16_f32 v18, v55, v57
	v_cvt_pk_bf16_f32 v19, v46, v47
	v_cvt_pk_bf16_f32 v20, v56, v58
	v_cvt_pk_bf16_f32 v21, v59, v60
.LBB0_773:
	s_andn2_b64 vcc, exec, s[0:1]
	s_mov_b64 s[0:1], 0x3b6e9140
	s_cbranch_vccnz .LBB0_775
	ds_bpermute_b32 v18, v168, v42
	s_movk_i32 s4, 0x600
	s_movk_i32 s89, 0x600
	s_waitcnt lgkmcnt(0)
	v_add_f32_e32 v18, v42, v18
	ds_bpermute_b32 v19, v167, v18
	s_waitcnt lgkmcnt(0)
	v_add_f32_e32 v18, v18, v19
	v_fmamk_f32 v18, v18, 0x3c800000, v188
	v_rsq_f32_e32 v18, v18
	s_nop 0
	v_mul_f32_e32 v23, 0x3e38aa3b, v18
	s_nop 0
	s_nop 0
	v_mul_f32_e32 v38, v38, v23
	v_mul_f32_e32 v36, v36, v23
	v_mul_f32_e32 v30, v30, v23
	v_mul_f32_e32 v28, v28, v23
	s_nop 0
	v_mul_f32_e32 v38, v224, v38
	v_mul_f32_e32 v18, v37, v23
	v_mul_f32_e32 v37, v221, v18
	v_mul_f32_e32 v18, v39, v23
	v_mul_f32_e32 v39, v225, v18
	v_mul_f32_e32 v18, v32, v23
	v_mul_f32_e32 v36, v220, v36
	v_mul_f32_e32 v40, v222, v18
	v_mul_f32_e32 v18, v34, v23
	v_mul_f32_e32 v41, v226, v18
	v_mul_f32_e32 v18, v33, v23
	v_mul_f32_e32 v42, v223, v18
	v_mul_f32_e32 v18, v35, v23
	v_mul_f32_e32 v43, v227, v18
	s_nop 0
	s_nop 0
	s_nop 0
	v_mul_f32_e32 v30, v232, v30
	v_mul_f32_e32 v18, v29, v23
	s_nop 0
	v_mul_f32_e32 v29, v229, v18
	v_mul_f32_e32 v18, v31, v23
	v_mul_f32_e32 v31, v233, v18
	v_mul_f32_e32 v18, v24, v23
	v_mul_f32_e32 v28, v228, v28
	v_mul_f32_e32 v32, v230, v18
	v_mul_f32_e32 v18, v26, v23
	v_mul_f32_e32 v26, v234, v18
	v_mul_f32_e32 v18, v25, v23
	v_mov_b64_e32 v[24:25], s[94:95]
	v_mad_i64_i32 v[24:25], s[0:1], v22, s4, v[24:25]
	s_lshl_b64 s[0:1], s[24:25], 1
	s_nop 0
	v_lshl_add_u64 v[24:25], v[24:25], 0, s[0:1]
	v_lshl_add_u64 v[24:25], v[24:25], 0, s[92:93]
	v_mul_f32_e32 v33, v231, v18
	v_mul_f32_e32 v18, v27, v23
	v_lshl_add_u64 v[24:25], v[142:143], 1, v[24:25]
	v_mul_f32_e32 v23, v235, v18
	v_cvt_pk_bf16_f32 v18, v36, v37
	v_cvt_pk_bf16_f32 v19, v40, v42
	v_cvt_pk_bf16_f32 v20, v38, v39
	v_cvt_pk_bf16_f32 v21, v41, v43
	global_store_dwordx4 v[24:25], v[18:21], off
	v_mov_b64_e32 v[24:25], s[74:75]
	s_nop 0
	v_cvt_pk_bf16_f32 v21, v26, v23
	v_mad_i64_i32 v[22:23], s[4:5], v22, s4, v[24:25]
	v_lshl_add_u64 v[40:41], v[22:23], 0, s[0:1]
	s_mov_b64 s[0:1], 0x80a0040
	v_cvt_pk_bf16_f32 v18, v28, v29
	v_cvt_pk_bf16_f32 v19, v32, v33
	v_cvt_pk_bf16_f32 v20, v30, v31
.LBB0_775:
	v_lshl_add_u64 v[22:23], v[40:41], 0, s[92:93]
	v_lshl_add_u64 v[22:23], v[22:23], 0, s[0:1]
	v_lshl_add_u64 v[22:23], v[142:143], 1, v[22:23]
	v_mov_b32_e32 v24, v145
	global_store_dwordx4 v[22:23], v[18:21], off
	v_pk_mul_f32 v[16:17], v[16:17], v[24:25] op_sel_hi:[1,0]
	v_pk_mul_f32 v[22:23], v[10:11], v[24:25] op_sel_hi:[1,0]
	v_pk_mul_f32 v[20:21], v[14:15], v[24:25] op_sel_hi:[1,0]
	v_pk_mul_f32 v[18:19], v[12:13], v[24:25] op_sel_hi:[1,0]
	v_mul_f32_e32 v26, v21, v21
	v_fmac_f32_e32 v26, v20, v20
	v_fmac_f32_e32 v26, v16, v16
	v_fmac_f32_e32 v26, v17, v17
	v_fmac_f32_e32 v26, v22, v22
	v_fmac_f32_e32 v26, v23, v23
	v_fmac_f32_e32 v26, v18, v18
	v_pk_mul_f32 v[12:13], v[6:7], v[24:25] op_sel_hi:[1,0]
	v_fmac_f32_e32 v26, v19, v19
	v_fmac_f32_e32 v26, v12, v12
	v_pk_mul_f32 v[8:9], v[8:9], v[24:25] op_sel_hi:[1,0]
	v_fmac_f32_e32 v26, v13, v13
	v_fmac_f32_e32 v26, v8, v8
	v_pk_mul_f32 v[14:15], v[2:3], v[24:25] op_sel_hi:[1,0]
	v_fmac_f32_e32 v26, v9, v9
	v_fmac_f32_e32 v26, v14, v14
	v_pk_mul_f32 v[10:11], v[4:5], v[24:25] op_sel_hi:[1,0]
	v_fmac_f32_e32 v26, v15, v15
	v_fmac_f32_e32 v26, v10, v10
	v_add_u32_e32 v6, s62, v169
	v_fmac_f32_e32 v26, v11, v11
	s_and_b64 vcc, exec, s[10:11]
	s_mov_b64 s[0:1], -1
	s_cbranch_vccnz .LBB0_777
	ds_bpermute_b32 v2, v168, v26
	v_readlane_b32 s0, v243, 4
	v_readlane_b32 s1, v243, 5
	s_waitcnt lgkmcnt(0)
	v_add_f32_e32 v2, v26, v2
	ds_bpermute_b32 v3, v167, v2
	s_waitcnt lgkmcnt(0)
	v_add_f32_e32 v2, v2, v3
	v_fmamk_f32 v2, v2, 0x3c800000, v188
	v_rsq_f32_e32 v2, v2
	s_nop 0
	v_mul_f32_e32 v7, 0x3e38aa3b, v2
	s_nop 0
	s_nop 0
	v_mul_f32_e32 v24, v20, v7
	s_nop 0
	v_mul_f32_e32 v27, v204, v24
	v_mul_f32_e32 v24, v22, v7
	v_mul_f32_e32 v32, v208, v24
	v_mul_f32_e32 v2, v21, v7
	v_mul_f32_e32 v33, v205, v2
	v_mul_f32_e32 v2, v23, v7
	v_mul_f32_e32 v34, v209, v2
	v_mul_f32_e32 v2, v16, v7
	v_mul_f32_e32 v35, v206, v2
	v_mul_f32_e32 v2, v18, v7
	v_mul_f32_e32 v36, v210, v2
	v_mul_f32_e32 v2, v17, v7
	v_mul_f32_e32 v37, v207, v2
	v_mul_f32_e32 v2, v19, v7
	v_mul_f32_e32 v38, v211, v2
	s_nop 0
	s_nop 0
	v_mul_f32_e32 v24, v12, v7
	s_nop 0
	v_mul_f32_e32 v39, v212, v24
	v_mul_f32_e32 v24, v14, v7
	v_mul_f32_e32 v40, v216, v24
	v_mul_f32_e32 v2, v13, v7
	v_mul_f32_e32 v41, v213, v2
	v_mul_f32_e32 v2, v15, v7
	v_mul_f32_e32 v42, v217, v2
	v_mul_f32_e32 v2, v8, v7
	v_mul_f32_e32 v30, v214, v2
	v_mul_f32_e32 v2, v10, v7
	v_mul_f32_e32 v43, v218, v2
	v_mul_f32_e32 v2, v9, v7
	v_mul_f32_e32 v31, v215, v2
	v_mul_f32_e32 v2, v11, v7
	v_ashrrev_i32_e32 v7, 31, v6
	v_lshlrev_b64 v[24:25], 9, v[6:7]
	v_lshl_add_u64 v[28:29], s[20:21], 0, v[24:25]
	v_mul_f32_e32 v44, v219, v2
	v_cvt_pk_bf16_f32 v2, v27, v33
	v_cvt_pk_bf16_f32 v3, v35, v37
	v_cvt_pk_bf16_f32 v4, v32, v34
	v_cvt_pk_bf16_f32 v5, v36, v38
	v_lshl_add_u64 v[28:29], v[142:143], 1, v[28:29]
	v_lshl_add_u64 v[24:25], s[0:1], 0, v[24:25]
	s_mov_b64 s[0:1], 0
	global_store_dwordx4 v[28:29], v[2:5], off
	s_nop 1
	v_cvt_pk_bf16_f32 v2, v39, v41
	v_cvt_pk_bf16_f32 v3, v30, v31
	v_cvt_pk_bf16_f32 v4, v40, v42
	v_cvt_pk_bf16_f32 v5, v43, v44
.LBB0_777:
	s_andn2_b64 vcc, exec, s[0:1]
	s_mov_b64 s[0:1], 0x3b6e9140
	s_cbranch_vccnz .LBB0_730
	ds_bpermute_b32 v2, v168, v26
	s_movk_i32 s4, 0x600
	s_movk_i32 s89, 0x600
	s_waitcnt lgkmcnt(0)
	v_add_f32_e32 v2, v26, v2
	ds_bpermute_b32 v3, v167, v2
	s_waitcnt lgkmcnt(0)
	v_add_f32_e32 v2, v2, v3
	v_fmamk_f32 v2, v2, 0x3c800000, v188
	v_rsq_f32_e32 v2, v2
	s_nop 0
	v_mul_f32_e32 v7, 0x3e38aa3b, v2
	s_nop 0
	s_nop 0
	v_mul_f32_e32 v22, v22, v7
	v_mul_f32_e32 v20, v20, v7
	v_mul_f32_e32 v14, v14, v7
	v_mul_f32_e32 v12, v12, v7
	s_nop 0
	v_mul_f32_e32 v22, v224, v22
	v_mul_f32_e32 v2, v21, v7
	v_mul_f32_e32 v21, v221, v2
	v_mul_f32_e32 v2, v23, v7
	v_mul_f32_e32 v23, v225, v2
	v_mul_f32_e32 v2, v16, v7
	v_mul_f32_e32 v20, v220, v20
	v_mul_f32_e32 v24, v222, v2
	v_mul_f32_e32 v2, v18, v7
	v_mul_f32_e32 v25, v226, v2
	v_mul_f32_e32 v2, v17, v7
	v_mul_f32_e32 v26, v223, v2
	v_mul_f32_e32 v2, v19, v7
	v_mul_f32_e32 v27, v227, v2
	s_nop 0
	s_nop 0
	s_nop 0
	v_mul_f32_e32 v14, v232, v14
	v_mul_f32_e32 v2, v13, v7
	s_nop 0
	v_mul_f32_e32 v13, v229, v2
	v_mul_f32_e32 v2, v15, v7
	v_mul_f32_e32 v15, v233, v2
	v_mul_f32_e32 v2, v8, v7
	v_mul_f32_e32 v12, v228, v12
	v_mul_f32_e32 v16, v230, v2
	v_mul_f32_e32 v2, v10, v7
	v_mul_f32_e32 v10, v234, v2
	v_mul_f32_e32 v2, v9, v7
	v_mov_b64_e32 v[8:9], s[94:95]
	v_mad_i64_i32 v[8:9], s[0:1], v6, s4, v[8:9]
	s_lshl_b64 s[0:1], s[24:25], 1
	s_nop 0
	v_lshl_add_u64 v[8:9], v[8:9], 0, s[0:1]
	v_lshl_add_u64 v[8:9], v[8:9], 0, s[92:93]
	v_mul_f32_e32 v17, v231, v2
	v_mul_f32_e32 v2, v11, v7
	v_lshl_add_u64 v[8:9], v[142:143], 1, v[8:9]
	v_mul_f32_e32 v7, v235, v2
	v_cvt_pk_bf16_f32 v2, v20, v21
	v_cvt_pk_bf16_f32 v3, v24, v26
	v_cvt_pk_bf16_f32 v4, v22, v23
	v_cvt_pk_bf16_f32 v5, v25, v27
	global_store_dwordx4 v[8:9], v[2:5], off
	v_mov_b64_e32 v[8:9], s[74:75]
	s_nop 0
	v_cvt_pk_bf16_f32 v5, v10, v7
	v_mad_i64_i32 v[6:7], s[4:5], v6, s4, v[8:9]
	v_lshl_add_u64 v[24:25], v[6:7], 0, s[0:1]
	s_mov_b64 s[0:1], 0x80a0040
	v_cvt_pk_bf16_f32 v2, v12, v13
	v_cvt_pk_bf16_f32 v3, v16, v17
	v_cvt_pk_bf16_f32 v4, v14, v15
	s_branch .LBB0_730

.LBB0_806:
	s_add_i32 s27, s4, 2
	s_add_u32 s10, s0, 0x80
	s_addc_u32 s5, s1, 0
	s_add_i32 s28, 0, 0x10000
	v_add_u32_e32 v154, s28, v171
	ds_read_b128 v[142:145], v154
	ds_read_b128 v[146:149], v154 offset:1024
	ds_read_b128 v[150:153], v154 offset:2048
	ds_read_b128 v[154:157], v154 offset:3072
	s_cmp_eq_u32 s48, s4
	s_cselect_b32 s4, s22, s10
	s_cselect_b32 s5, s23, s5
	s_cselect_b32 s11, s25, s13
	s_cselect_b32 s10, s24, s12
	v_lshl_add_u64 v[212:213], s[0:1], 0, v[138:139]
	s_add_i32 m0, s35, 0xc000
	ds_read_b128 v[158:161], v172
	ds_read_b128 v[162:165], v172 offset:1024
	ds_read_b128 v[166:169], v172 offset:2048
	ds_read_b128 v[174:177], v172 offset:3072
	ds_read_b128 v[178:181], v172 offset:4096
	ds_read_b128 v[182:185], v172 offset:5120
	ds_read_b128 v[204:207], v172 offset:6144
	ds_read_b128 v[208:211], v172 offset:7168
	global_load_lds_dwordx4 v[212:213], off
	v_lshl_add_u64 v[212:213], s[0:1], 0, v[140:141]
	s_add_i32 m0, s35, 0xe000
	s_nop 0
	global_load_lds_dwordx4 v[212:213], off
	s_waitcnt lgkmcnt(8)
	s_barrier
	s_waitcnt lgkmcnt(0)
	s_setprio 1
	s_waitcnt lgkmcnt(0)
	v_mfma_f32_16x16x32_bf16 v[126:129], v[142:145], v[158:161], v[126:129]
	v_mfma_f32_16x16x32_bf16 v[122:125], v[150:153], v[158:161], v[122:125]
	v_mfma_f32_16x16x32_bf16 v[110:113], v[142:145], v[166:169], v[110:113]
	v_mfma_f32_16x16x32_bf16 v[106:109], v[150:153], v[166:169], v[106:109]
	v_mfma_f32_16x16x32_bf16 v[94:97], v[142:145], v[178:181], v[94:97]
	v_mfma_f32_16x16x32_bf16 v[90:93], v[150:153], v[178:181], v[90:93]
	v_mfma_f32_16x16x32_bf16 v[78:81], v[142:145], v[204:207], v[78:81]
	v_mfma_f32_16x16x32_bf16 v[74:77], v[150:153], v[204:207], v[74:77]
	v_mfma_f32_16x16x32_bf16 v[126:129], v[146:149], v[162:165], v[126:129]
	v_mfma_f32_16x16x32_bf16 v[122:125], v[154:157], v[162:165], v[122:125]
	v_mfma_f32_16x16x32_bf16 v[110:113], v[146:149], v[174:177], v[110:113]
	v_mfma_f32_16x16x32_bf16 v[106:109], v[154:157], v[174:177], v[106:109]
	v_mfma_f32_16x16x32_bf16 v[94:97], v[146:149], v[182:185], v[94:97]
	v_mfma_f32_16x16x32_bf16 v[90:93], v[154:157], v[182:185], v[90:93]
	v_mfma_f32_16x16x32_bf16 v[78:81], v[146:149], v[208:211], v[78:81]
	v_mfma_f32_16x16x32_bf16 v[74:77], v[154:157], v[208:211], v[74:77]
	s_setprio 0
	s_barrier
	s_add_i32 s29, 0, 0x14000
	s_add_i32 s28, s28, s34
	v_add_u32_e32 v173, s29, v171
	v_lshl_add_u64 v[228:229], s[10:11], 0, v[132:133]
	s_mov_b32 m0, s28
	ds_read_b128 v[212:215], v173
	ds_read_b128 v[216:219], v173 offset:1024
	ds_read_b128 v[220:223], v173 offset:2048
	ds_read_b128 v[224:227], v173 offset:3072
	global_load_lds_dwordx4 v[228:229], off
	v_lshl_add_u64 v[230:231], s[10:11], 0, v[136:137]
	s_add_i32 m0, s28, 0x2000
	s_nop 0
	global_load_lds_dwordx4 v[230:231], off
	s_barrier
	s_waitcnt lgkmcnt(0)
	s_setprio 1
	s_waitcnt lgkmcnt(0)
	v_mfma_f32_16x16x32_bf16 v[118:121], v[212:215], v[158:161], v[118:121]
	v_mfma_f32_16x16x32_bf16 v[114:117], v[220:223], v[158:161], v[114:117]
	v_mfma_f32_16x16x32_bf16 v[102:105], v[212:215], v[166:169], v[102:105]
	v_mfma_f32_16x16x32_bf16 v[98:101], v[220:223], v[166:169], v[98:101]
	v_mfma_f32_16x16x32_bf16 v[86:89], v[212:215], v[178:181], v[86:89]
	v_mfma_f32_16x16x32_bf16 v[82:85], v[220:223], v[178:181], v[82:85]
	v_mfma_f32_16x16x32_bf16 v[70:73], v[212:215], v[204:207], v[70:73]
	v_mfma_f32_16x16x32_bf16 v[66:69], v[220:223], v[204:207], v[66:69]
	v_mfma_f32_16x16x32_bf16 v[118:121], v[216:219], v[162:165], v[118:121]
	v_mfma_f32_16x16x32_bf16 v[114:117], v[224:227], v[162:165], v[114:117]
	v_mfma_f32_16x16x32_bf16 v[102:105], v[216:219], v[174:177], v[102:105]
	v_mfma_f32_16x16x32_bf16 v[98:101], v[224:227], v[174:177], v[98:101]
	v_mfma_f32_16x16x32_bf16 v[86:89], v[216:219], v[182:185], v[86:89]
	v_mfma_f32_16x16x32_bf16 v[82:85], v[224:227], v[182:185], v[82:85]
	v_mfma_f32_16x16x32_bf16 v[70:73], v[216:219], v[208:211], v[70:73]
	v_mfma_f32_16x16x32_bf16 v[66:69], v[224:227], v[208:211], v[66:69]
	s_setprio 0
	s_mov_b32 m0, s35
	v_lshl_add_u64 v[232:233], s[4:5], 0, v[130:131]
	s_barrier
	ds_read_b128 v[158:161], v172 offset:16384
	ds_read_b128 v[162:165], v172 offset:17408
	ds_read_b128 v[166:169], v172 offset:18432
	ds_read_b128 v[174:177], v172 offset:19456
	ds_read_b128 v[178:181], v172 offset:20480
	ds_read_b128 v[182:185], v172 offset:21504
	ds_read_b128 v[204:207], v172 offset:22528
	ds_read_b128 v[208:211], v172 offset:23552
	global_load_lds_dwordx4 v[232:233], off
	v_lshl_add_u64 v[234:235], s[4:5], 0, v[134:135]
	s_mov_b32 m0, s40
	s_nop 0
	global_load_lds_dwordx4 v[234:235], off
	s_barrier
	s_waitcnt lgkmcnt(0)
	s_setprio 1
	s_waitcnt lgkmcnt(0)
	v_mfma_f32_16x16x32_bf16 v[62:65], v[142:145], v[158:161], v[62:65]
	v_mfma_f32_16x16x32_bf16 v[58:61], v[150:153], v[158:161], v[58:61]
	v_mfma_f32_16x16x32_bf16 v[46:49], v[142:145], v[166:169], v[46:49]
	v_mfma_f32_16x16x32_bf16 v[42:45], v[150:153], v[166:169], v[42:45]
	v_mfma_f32_16x16x32_bf16 v[30:33], v[142:145], v[178:181], v[30:33]
	v_mfma_f32_16x16x32_bf16 v[26:29], v[150:153], v[178:181], v[26:29]
	v_mfma_f32_16x16x32_bf16 v[14:17], v[142:145], v[204:207], v[14:17]
	v_mfma_f32_16x16x32_bf16 v[10:13], v[150:153], v[204:207], v[10:13]
	v_mfma_f32_16x16x32_bf16 v[62:65], v[146:149], v[162:165], v[62:65]
	v_mfma_f32_16x16x32_bf16 v[58:61], v[154:157], v[162:165], v[58:61]
	v_mfma_f32_16x16x32_bf16 v[46:49], v[146:149], v[174:177], v[46:49]
	v_mfma_f32_16x16x32_bf16 v[42:45], v[154:157], v[174:177], v[42:45]
	v_mfma_f32_16x16x32_bf16 v[30:33], v[146:149], v[182:185], v[30:33]
	v_mfma_f32_16x16x32_bf16 v[26:29], v[154:157], v[182:185], v[26:29]
	v_mfma_f32_16x16x32_bf16 v[14:17], v[146:149], v[208:211], v[14:17]
	v_mfma_f32_16x16x32_bf16 v[10:13], v[154:157], v[208:211], v[10:13]
	s_setprio 0
	s_barrier
	s_add_u32 s10, s10, s92
	s_addc_u32 s11, s11, 0
	s_add_i32 s28, s29, s34
	v_lshl_add_u64 v[236:237], s[10:11], 0, v[132:133]
	s_mov_b32 m0, s28
	v_lshl_add_u64 v[238:239], s[10:11], 0, v[136:137]
	global_load_lds_dwordx4 v[236:237], off
	s_add_i32 m0, s28, 0x2000
	s_nop 0
	global_load_lds_dwordx4 v[238:239], off
	s_waitcnt vmcnt(6)
	s_barrier
	s_setprio 1
	v_mfma_f32_16x16x32_bf16 v[54:57], v[212:215], v[158:161], v[54:57]
	v_mfma_f32_16x16x32_bf16 v[50:53], v[220:223], v[158:161], v[50:53]
	v_mfma_f32_16x16x32_bf16 v[38:41], v[212:215], v[166:169], v[38:41]
	v_mfma_f32_16x16x32_bf16 v[34:37], v[220:223], v[166:169], v[34:37]
	v_mfma_f32_16x16x32_bf16 v[22:25], v[212:215], v[178:181], v[22:25]
	v_mfma_f32_16x16x32_bf16 v[18:21], v[220:223], v[178:181], v[18:21]
	v_mfma_f32_16x16x32_bf16 v[6:9], v[212:215], v[204:207], v[6:9]
	v_mfma_f32_16x16x32_bf16 v[2:5], v[220:223], v[204:207], v[2:5]
	v_mfma_f32_16x16x32_bf16 v[54:57], v[216:219], v[162:165], v[54:57]
	v_mfma_f32_16x16x32_bf16 v[50:53], v[224:227], v[162:165], v[50:53]
	v_mfma_f32_16x16x32_bf16 v[38:41], v[216:219], v[174:177], v[38:41]
	v_mfma_f32_16x16x32_bf16 v[34:37], v[224:227], v[174:177], v[34:37]
	v_mfma_f32_16x16x32_bf16 v[22:25], v[216:219], v[182:185], v[22:25]
	v_mfma_f32_16x16x32_bf16 v[18:21], v[224:227], v[182:185], v[18:21]
	v_mfma_f32_16x16x32_bf16 v[6:9], v[216:219], v[208:211], v[6:9]
	v_mfma_f32_16x16x32_bf16 v[2:5], v[224:227], v[208:211], v[2:5]
	s_setprio 0
	s_add_i32 s10, 0, 0x18000
	v_add_u32_e32 v154, s10, v171
	s_barrier
	ds_read_b128 v[142:145], v154
	ds_read_b128 v[146:149], v154 offset:1024
	ds_read_b128 v[150:153], v154 offset:2048
	ds_read_b128 v[154:157], v154 offset:3072
	s_add_u32 s4, s4, s92
	s_addc_u32 s5, s5, 0
	s_mov_b32 m0, s41
	v_lshl_add_u64 v[212:213], s[4:5], 0, v[130:131]
	ds_read_b128 v[158:161], v172 offset:32768
	ds_read_b128 v[162:165], v172 offset:33792
	ds_read_b128 v[166:169], v172 offset:34816
	ds_read_b128 v[174:177], v172 offset:35840
	ds_read_b128 v[178:181], v172 offset:36864
	ds_read_b128 v[182:185], v172 offset:37888
	ds_read_b128 v[204:207], v172 offset:38912
	ds_read_b128 v[208:211], v172 offset:39936
	global_load_lds_dwordx4 v[212:213], off
	v_lshl_add_u64 v[212:213], s[4:5], 0, v[134:135]
	s_mov_b32 m0, s42
	s_nop 0
	global_load_lds_dwordx4 v[212:213], off
	s_waitcnt lgkmcnt(8)
	s_barrier
	s_waitcnt lgkmcnt(0)
	s_setprio 1
	s_waitcnt lgkmcnt(0)
	v_mfma_f32_16x16x32_bf16 v[126:129], v[142:145], v[158:161], v[126:129]
	v_mfma_f32_16x16x32_bf16 v[122:125], v[150:153], v[158:161], v[122:125]
	v_mfma_f32_16x16x32_bf16 v[110:113], v[142:145], v[166:169], v[110:113]
	v_mfma_f32_16x16x32_bf16 v[106:109], v[150:153], v[166:169], v[106:109]
	v_mfma_f32_16x16x32_bf16 v[94:97], v[142:145], v[178:181], v[94:97]
	v_mfma_f32_16x16x32_bf16 v[90:93], v[150:153], v[178:181], v[90:93]
	v_mfma_f32_16x16x32_bf16 v[78:81], v[142:145], v[204:207], v[78:81]
	v_mfma_f32_16x16x32_bf16 v[74:77], v[150:153], v[204:207], v[74:77]
	v_mfma_f32_16x16x32_bf16 v[126:129], v[146:149], v[162:165], v[126:129]
	v_mfma_f32_16x16x32_bf16 v[122:125], v[154:157], v[162:165], v[122:125]
	v_mfma_f32_16x16x32_bf16 v[110:113], v[146:149], v[174:177], v[110:113]
	v_mfma_f32_16x16x32_bf16 v[106:109], v[154:157], v[174:177], v[106:109]
	v_mfma_f32_16x16x32_bf16 v[94:97], v[146:149], v[182:185], v[94:97]
	v_mfma_f32_16x16x32_bf16 v[90:93], v[154:157], v[182:185], v[90:93]
	v_mfma_f32_16x16x32_bf16 v[78:81], v[146:149], v[208:211], v[78:81]
	v_mfma_f32_16x16x32_bf16 v[74:77], v[154:157], v[208:211], v[74:77]
	s_setprio 0
	s_barrier
	s_add_i32 s4, 0, 0x1c000
	s_add_i32 s5, s10, s34
	v_add_u32_e32 v173, s4, v171
	v_lshl_add_u64 v[228:229], v[228:229], 0, s[6:7]
	s_mov_b32 m0, s5
	ds_read_b128 v[212:215], v173
	ds_read_b128 v[216:219], v173 offset:1024
	ds_read_b128 v[220:223], v173 offset:2048
	ds_read_b128 v[224:227], v173 offset:3072
	global_load_lds_dwordx4 v[228:229], off
	v_lshl_add_u64 v[228:229], v[230:231], 0, s[6:7]
	s_add_i32 m0, s5, 0x2000
	s_nop 0
	global_load_lds_dwordx4 v[228:229], off
	s_barrier
	s_waitcnt lgkmcnt(0)
	s_setprio 1
	s_waitcnt lgkmcnt(0)
	v_mfma_f32_16x16x32_bf16 v[118:121], v[212:215], v[158:161], v[118:121]
	v_mfma_f32_16x16x32_bf16 v[114:117], v[220:223], v[158:161], v[114:117]
	v_mfma_f32_16x16x32_bf16 v[102:105], v[212:215], v[166:169], v[102:105]
	v_mfma_f32_16x16x32_bf16 v[98:101], v[220:223], v[166:169], v[98:101]
	v_mfma_f32_16x16x32_bf16 v[86:89], v[212:215], v[178:181], v[86:89]
	v_mfma_f32_16x16x32_bf16 v[82:85], v[220:223], v[178:181], v[82:85]
	v_mfma_f32_16x16x32_bf16 v[70:73], v[212:215], v[204:207], v[70:73]
	v_mfma_f32_16x16x32_bf16 v[66:69], v[220:223], v[204:207], v[66:69]
	v_mfma_f32_16x16x32_bf16 v[118:121], v[216:219], v[162:165], v[118:121]
	v_mfma_f32_16x16x32_bf16 v[114:117], v[224:227], v[162:165], v[114:117]
	v_mfma_f32_16x16x32_bf16 v[102:105], v[216:219], v[174:177], v[102:105]
	v_mfma_f32_16x16x32_bf16 v[98:101], v[224:227], v[174:177], v[98:101]
	v_mfma_f32_16x16x32_bf16 v[86:89], v[216:219], v[182:185], v[86:89]
	v_mfma_f32_16x16x32_bf16 v[82:85], v[224:227], v[182:185], v[82:85]
	v_mfma_f32_16x16x32_bf16 v[70:73], v[216:219], v[208:211], v[70:73]
	v_mfma_f32_16x16x32_bf16 v[66:69], v[224:227], v[208:211], v[66:69]
	s_setprio 0
	s_mov_b32 m0, s46
	v_lshl_add_u64 v[228:229], v[232:233], 0, s[6:7]
	s_barrier
	ds_read_b128 v[158:161], v172 offset:49152
	ds_read_b128 v[162:165], v172 offset:50176
	ds_read_b128 v[166:169], v172 offset:51200
	ds_read_b128 v[174:177], v172 offset:52224
	ds_read_b128 v[178:181], v172 offset:53248
	ds_read_b128 v[182:185], v172 offset:54272
	ds_read_b128 v[204:207], v172 offset:55296
	ds_read_b128 v[208:211], v172 offset:56320
	global_load_lds_dwordx4 v[228:229], off
	v_lshl_add_u64 v[228:229], v[234:235], 0, s[6:7]
	s_mov_b32 m0, s47
	s_nop 0
	global_load_lds_dwordx4 v[228:229], off
	s_barrier
	s_waitcnt lgkmcnt(0)
	s_setprio 1
	s_waitcnt lgkmcnt(0)
	v_mfma_f32_16x16x32_bf16 v[62:65], v[142:145], v[158:161], v[62:65]
	v_mfma_f32_16x16x32_bf16 v[58:61], v[150:153], v[158:161], v[58:61]
	v_mfma_f32_16x16x32_bf16 v[46:49], v[142:145], v[166:169], v[46:49]
	v_mfma_f32_16x16x32_bf16 v[42:45], v[150:153], v[166:169], v[42:45]
	v_mfma_f32_16x16x32_bf16 v[30:33], v[142:145], v[178:181], v[30:33]
	v_mfma_f32_16x16x32_bf16 v[26:29], v[150:153], v[178:181], v[26:29]
	v_mfma_f32_16x16x32_bf16 v[14:17], v[142:145], v[204:207], v[14:17]
	v_mfma_f32_16x16x32_bf16 v[10:13], v[150:153], v[204:207], v[10:13]
	v_mfma_f32_16x16x32_bf16 v[62:65], v[146:149], v[162:165], v[62:65]
	v_mfma_f32_16x16x32_bf16 v[58:61], v[154:157], v[162:165], v[58:61]
	v_mfma_f32_16x16x32_bf16 v[46:49], v[146:149], v[174:177], v[46:49]
	v_mfma_f32_16x16x32_bf16 v[42:45], v[154:157], v[174:177], v[42:45]
	v_mfma_f32_16x16x32_bf16 v[30:33], v[146:149], v[182:185], v[30:33]
	v_mfma_f32_16x16x32_bf16 v[26:29], v[154:157], v[182:185], v[26:29]
	v_mfma_f32_16x16x32_bf16 v[14:17], v[146:149], v[208:211], v[14:17]
	v_mfma_f32_16x16x32_bf16 v[10:13], v[154:157], v[208:211], v[10:13]
	s_setprio 0
	s_barrier
	s_add_i32 s4, s4, s34
	v_lshl_add_u64 v[142:143], v[236:237], 0, s[6:7]
	s_mov_b32 m0, s4
	s_nop 0
	global_load_lds_dwordx4 v[142:143], off
	v_lshl_add_u64 v[142:143], v[238:239], 0, s[6:7]
	s_add_i32 m0, s4, 0x2000
	s_nop 0
	global_load_lds_dwordx4 v[142:143], off
	s_waitcnt vmcnt(6)
	s_barrier
	s_setprio 1
	v_mfma_f32_16x16x32_bf16 v[54:57], v[212:215], v[158:161], v[54:57]
	v_mfma_f32_16x16x32_bf16 v[50:53], v[220:223], v[158:161], v[50:53]
	v_mfma_f32_16x16x32_bf16 v[38:41], v[212:215], v[166:169], v[38:41]
	v_mfma_f32_16x16x32_bf16 v[34:37], v[220:223], v[166:169], v[34:37]
	v_mfma_f32_16x16x32_bf16 v[22:25], v[212:215], v[178:181], v[22:25]
	v_mfma_f32_16x16x32_bf16 v[18:21], v[220:223], v[178:181], v[18:21]
	v_mfma_f32_16x16x32_bf16 v[6:9], v[212:215], v[204:207], v[6:9]
	v_mfma_f32_16x16x32_bf16 v[2:5], v[220:223], v[204:207], v[2:5]
	v_mfma_f32_16x16x32_bf16 v[54:57], v[216:219], v[162:165], v[54:57]
	v_mfma_f32_16x16x32_bf16 v[50:53], v[224:227], v[162:165], v[50:53]
	v_mfma_f32_16x16x32_bf16 v[38:41], v[216:219], v[174:177], v[38:41]
	v_mfma_f32_16x16x32_bf16 v[34:37], v[224:227], v[174:177], v[34:37]
	v_mfma_f32_16x16x32_bf16 v[22:25], v[216:219], v[182:185], v[22:25]
	v_mfma_f32_16x16x32_bf16 v[18:21], v[224:227], v[182:185], v[18:21]
	v_mfma_f32_16x16x32_bf16 v[6:9], v[216:219], v[208:211], v[6:9]
	v_mfma_f32_16x16x32_bf16 v[2:5], v[224:227], v[208:211], v[2:5]
	s_setprio 0
	s_add_u32 s0, s0, 0x100
	s_addc_u32 s1, s1, 0
	s_add_u32 s12, s12, 0x100
	s_addc_u32 s13, s13, 0
	s_cmp_ge_u32 s27, s43
	s_mov_b32 s4, s27
	s_barrier
	s_cbranch_scc0 .LBB0_806
	v_mov_b32_e32 v152, v170
	v_mov_b32_e32 v150, v1
	s_lshl_b32 s5, s69, 8
	s_cmp_lg_u32 s69, s26
	v_lshl_add_u32 v151, v150, 4, v152
	s_mov_b64 s[0:1], -1
	s_cbranch_scc0 .LBB0_809
	s_add_i32 s4, s5, s44
	v_and_or_b32 v142, v151, 63, s4
	v_lshlrev_b32_e32 v162, 1, v151
	v_add_u32_e32 v153, s50, v142
	v_and_b32_e32 v142, 0xffffff80, v162
	v_add_u32_e32 v142, v153, v142
	v_ashrrev_i32_e32 v143, 31, v142
	v_readlane_b32 s0, v242, 3
	v_lshlrev_b64 v[142:143], 6, v[142:143]
	v_readlane_b32 s1, v242, 4
	v_lshl_add_u32 v164, v151, 2, s66
	s_nop 0
	v_lshl_add_u64 v[158:159], s[0:1], 0, v[142:143]
	global_load_dwordx4 v[142:145], v[158:159], off offset:48
	global_load_dwordx4 v[146:149], v[158:159], off offset:32
	global_load_dwordx4 v[154:157], v[158:159], off offset:16
	s_nop 0
	global_load_dwordx4 v[158:161], v[158:159], off
	v_add_u32_e32 v222, 0x80, v162
	v_and_b32_e32 v222, 0xffffff80, v222
	v_add_u32_e32 v222, v153, v222
	v_ashrrev_i32_e32 v223, 31, v222
	v_lshlrev_b64 v[222:223], 6, v[222:223]
	v_lshl_add_u64 v[220:221], s[0:1], 0, v[222:223]
	global_load_dwordx4 v[204:207], v[220:221], off offset:48
	global_load_dwordx4 v[208:211], v[220:221], off offset:32
	global_load_dwordx4 v[212:215], v[220:221], off offset:16
	global_load_dwordx4 v[216:219], v[220:221], off
	s_waitcnt vmcnt(4)
	v_add_f32_e32 v142, v142, v143
	v_add_f32_e32 v146, v146, v147
	v_add_f32_e32 v154, v154, v155
	v_add_f32_e32 v158, v158, v159
	v_add_f32_e32 v158, v160, v158
	v_add_f32_e32 v154, v156, v154
	v_add_f32_e32 v158, v161, v158
	v_add_f32_e32 v154, v157, v154
	v_add_f32_e32 v146, v148, v146
	v_add_f32_e32 v154, v158, v154
	v_add_f32_e32 v146, v149, v146
	v_add_f32_e32 v142, v144, v142
	v_add_f32_e32 v146, v154, v146
	v_add_f32_e32 v142, v145, v142
	v_add_f32_e32 v142, v146, v142
	v_fmamk_f32 v142, v142, 0x3a800000, v188
	v_rsq_f32_e32 v163, v142
	s_mov_b64 s[0:1], 0
	s_waitcnt vmcnt(0)
	v_add_f32_e32 v142, v204, v205
	v_add_f32_e32 v146, v208, v209
	v_add_f32_e32 v154, v212, v213
	v_add_f32_e32 v153, v216, v217
	v_add_f32_e32 v153, v218, v153
	v_add_f32_e32 v154, v214, v154
	v_add_f32_e32 v153, v219, v153
	v_add_f32_e32 v154, v215, v154
	v_add_f32_e32 v146, v210, v146
	v_add_f32_e32 v153, v153, v154
	v_add_f32_e32 v146, v211, v146
	v_add_f32_e32 v142, v206, v142
	v_add_f32_e32 v146, v153, v146
	v_add_f32_e32 v142, v207, v142
	v_add_f32_e32 v142, v146, v142
	v_fmamk_f32 v142, v142, 0x3a800000, v188
	v_rsq_f32_e32 v142, v142
	ds_write2st64_b32 v164, v163, v142 offset1:1
	s_waitcnt lgkmcnt(0)

.LBB0_1033:
	s_or_b64 exec, exec, s[4:5]
	v_lshlrev_b32_e32 v24, 2, v4
	v_mov_b32_e32 v25, v0
	v_lshl_add_u64 v[28:29], v[16:17], 0, v[24:25]
	v_lshlrev_b32_e32 v16, 1, v4
	v_mov_b32_e32 v17, v0
	global_load_dwordx4 v[24:27], v[28:29], off nt
	global_load_dwordx4 v[34:37], v[28:29], off offset:1024 nt
	global_load_dwordx4 v[38:41], v[28:29], off offset:2048 nt
	global_load_dwordx4 v[42:45], v[28:29], off offset:3072 nt
	v_lshl_add_u64 v[30:31], v[18:19], 0, v[16:17]
	s_waitcnt vmcnt(3)
	v_cvt_pk_bf16_f32 v24, v24, v25
	v_cvt_pk_bf16_f32 v25, v26, v27
	global_store_dwordx2 v[30:31], v[24:25], off
	s_nop 0
	s_waitcnt vmcnt(3)
	v_cvt_pk_bf16_f32 v26, v34, v35
	v_cvt_pk_bf16_f32 v27, v36, v37
	global_store_dwordx2 v[30:31], v[26:27], off offset:512
	v_lshlrev_b32_e32 v11, 16, v24
	v_and_b32_e32 v24, 0xffff0000, v24
	s_nop 0
	s_waitcnt vmcnt(3)
	v_cvt_pk_bf16_f32 v32, v38, v39
	v_cvt_pk_bf16_f32 v33, v40, v41
	global_store_dwordx2 v[30:31], v[32:33], off offset:1024
	v_mul_f32_e32 v24, v24, v24
	s_nop 0
	v_lshlrev_b32_e32 v28, 16, v25
	v_fmac_f32_e32 v24, v11, v11
	v_and_b32_e32 v25, 0xffff0000, v25
	v_fmac_f32_e32 v24, v28, v28
	v_fmac_f32_e32 v24, v25, v25
	v_and_b32_e32 v25, 0xffff0000, v26
	v_lshlrev_b32_e32 v11, 16, v26
	v_mul_f32_e32 v25, v25, v25
	v_lshlrev_b32_e32 v26, 16, v27
	v_fmac_f32_e32 v25, v11, v11
	v_and_b32_e32 v27, 0xffff0000, v27
	v_fmac_f32_e32 v25, v26, v26
	v_fmac_f32_e32 v25, v27, v27
	v_add_f32_e32 v11, v24, v25
	v_and_b32_e32 v25, 0xffff0000, v32
	v_lshlrev_b32_e32 v24, 16, v32
	v_mul_f32_e32 v25, v25, v25
	v_lshlrev_b32_e32 v26, 16, v33
	v_fmac_f32_e32 v25, v24, v24
	v_and_b32_e32 v27, 0xffff0000, v33
	v_fmac_f32_e32 v25, v26, v26
	s_waitcnt vmcnt(3)
	v_cvt_pk_bf16_f32 v24, v42, v43
	v_fmac_f32_e32 v25, v27, v27
	v_and_b32_e32 v17, 0xffff0000, v24
	v_lshlrev_b32_e32 v16, 16, v24
	v_mul_f32_e32 v17, v17, v17
	v_add_f32_e32 v11, v11, v25
	v_cvt_pk_bf16_f32 v25, v44, v45
	v_fmac_f32_e32 v17, v16, v16
	v_lshlrev_b32_e32 v18, 16, v25
	v_and_b32_e32 v19, 0xffff0000, v25
	v_fmac_f32_e32 v17, v18, v18
	v_fmac_f32_e32 v17, v19, v19
	v_add_f32_e32 v11, v11, v17
	ds_bpermute_b32 v16, v1, v11
	global_store_dwordx2 v[30:31], v[24:25], off offset:1536
	s_waitcnt lgkmcnt(0)
	v_add_f32_e32 v11, v11, v16
	ds_bpermute_b32 v16, v5, v11
	s_waitcnt lgkmcnt(0)
	v_add_f32_e32 v11, v11, v16
	ds_bpermute_b32 v16, v20, v11
	s_waitcnt lgkmcnt(0)
	v_add_f32_e32 v11, v11, v16
	ds_bpermute_b32 v16, v21, v11
	s_waitcnt lgkmcnt(0)
	v_add_f32_e32 v11, v11, v16
	ds_bpermute_b32 v16, v22, v11
	s_waitcnt lgkmcnt(0)
	v_add_f32_e32 v11, v11, v16
	ds_bpermute_b32 v16, v23, v11
	s_and_saveexec_b64 s[4:5], vcc
	s_cbranch_execz .LBB0_1026
	v_readlane_b32 s10, v243, 4
	v_readlane_b32 s11, v243, 5
	s_waitcnt lgkmcnt(0)
	v_add_f32_e32 v11, v11, v16
	v_lshlrev_b64 v[12:13], 6, v[12:13]
	v_lshl_add_u64 v[14:15], s[10:11], 0, v[14:15]
	v_cndmask_b32_e64 v16, 0, v11, s[8:9]
	v_lshl_add_u64 v[12:13], v[14:15], 0, v[12:13]
	v_mov_b32_e32 v11, v0
	v_lshl_add_u64 v[12:13], v[12:13], 0, v[10:11]
	global_store_dword v[12:13], v16, off
	s_branch .LBB0_1026
